# v19 + NSA: tiled copy of selected-branch keys (ws+440MiB slack) for stage C loads, and window V^T buffer re-laid out in 1-KiB MFMA tiles for stage A2
# speedup vs baseline: 1.0689x; 1.0137x over previous
; DI bf16_t f2bf(float a) { return (bf16_t)(pk2(a, 0.f) & 0xffffu); }
; DI u32x2 pk4(float a, float b, float c, float d) { u32x2 r; r.x = pk2(a, b); r.y = pk2(c, d); return r; }
; template <class AF, class EF>
; DI void gemm_run(unsigned char* lds, int wv, const AF& af, const bf16_t* __restrict__ Bt, int ldb, int M, int N, int K, const EF& ef, int blk_off) {
;     ...
;         for (int k = 0; k < 4; ++k) {
;           auto r = __builtin_amdgcn_permlane16_swap(__float_as_uint(acc[2 * ip][j][k]), __float_as_uint(acc[2 * ip + 1][j][k]), false, false);
;           lo[k] = __uint_as_float(r[0]); hi[k] = __uint_as_float(r[1]);
;         }
;         int n = n0 + wn * 64 + (2 * ip + (q4 & 1)) * 16 + (q4 >> 1) * 8;
;         int m = m0 + wm * 128 + j * 16 + l15;
;         if (n < N) ef.store8(m, n, lo[0], lo[1], lo[2], lo[3], hi[0], hi[1], hi[2], hi[3]);
;   DI void store(int m, int n, float a, float b, float c, float d) const {
;     int bb = m >> 13, s = m & (SEQ - 1);
;     if (n >= C_VS && n < C_KW) { int e = n - C_VS; bf16_t* p = vsT + ((size_t)(bb * 128 + e)) * SEQ + s; p[0] = f2bf(a); p[SEQ] = f2bf(b); p[2 * SEQ] = f2bf(c); p[3 * SEQ] = f2bf(d); }
;     else if (n >= C_VW && n < C_GATE) { int e = n - C_VW; bf16_t* p = vwT + ((size_t)(bb * 128 + e)) * SEQ + s; p[0] = f2bf(a); p[SEQ] = f2bf(b); p[2 * SEQ] = f2bf(c); p[3 * SEQ] = f2bf(d); }
;     else *(u32x2*)(proj + (size_t)m * EIN + n) = pk4(a, b, c, d); }
.LBB0_271:
	v_readlane_b32 s20, v255, 24
	v_readlane_b32 s21, v255, 25
	v_cvt_pk_bf16_f32 v158, v126, v127
	v_cvt_pk_bf16_f32 v159, v128, v129
	v_mov_b64_e32 v[180:181], s[20:21]
	v_mad_i64_i32 v[180:181], s[20:21], v153, s87, v[180:181]
	v_cvt_pk_bf16_f32 v160, v122, v123
	v_cvt_pk_bf16_f32 v161, v124, v125
	v_lshl_add_u64 v[180:181], v[130:131], 1, v[180:181]
	flat_store_dwordx4 v[180:181], v[158:161]
	v_subrev_u32_e32 v230, 0x300, v130
	v_lshrrev_b32_e32 v232, 7, v230
	v_cmp_eq_u32_e64 s[30:31], 0, v232
	s_and_saveexec_b64 s[36:37], s[30:31]
	v_readlane_b32 s80, v255, 24
	v_readlane_b32 s81, v255, 25
	v_lshrrev_b32_e32 v231, 13, v153
	v_lshlrev_b32_e32 v231, 20, v231
	v_lshrrev_b32_e32 v232, 6, v230
	v_lshl_or_b32 v231, v232, 19, v231
	v_bfe_u32 v232, v153, 6, 7
	v_lshl_or_b32 v231, v232, 12, v231
	v_bfe_u32 v232, v153, 5, 1
	v_lshl_or_b32 v231, v232, 11, v231
	v_bfe_u32 v232, v153, 2, 1
	v_lshl_or_b32 v231, v232, 10, v231
	v_bfe_u32 v232, v230, 5, 1
	v_lshl_or_b32 v231, v232, 9, v231
	v_bfe_u32 v232, v153, 3, 2
	v_lshl_or_b32 v231, v232, 7, v231
	v_bfe_u32 v232, v153, 0, 2
	v_lshl_or_b32 v231, v232, 5, v231
	v_and_b32_e32 v232, 31, v230
	v_or_b32_e32 v231, v231, v232
	v_add_u32_e32 v234, 0x9c00000, v231
	v_mov_b32_e32 v235, 0
	v_lshl_add_u64 v[236:237], v[234:235], 1, s[80:81]
	flat_store_dwordx4 v[236:237], v[158:161]
	s_or_b64 exec, exec, s[36:37]
	v_subrev_u32_e32 v230, 0x998, v130
	v_cmp_gt_u32_e64 s[30:31], 64, v230
	s_and_saveexec_b64 s[36:37], s[30:31]
	v_readlane_b32 s80, v255, 24
	v_readlane_b32 s81, v255, 25
	v_lshrrev_b32_e32 v231, 5, v153
	v_lshlrev_b32_e32 v231, 11, v231
	v_and_b32_e32 v232, 31, v153
	v_lshl_or_b32 v231, v232, 4, v231
	v_lshrrev_b32_e32 v232, 4, v230
	v_lshl_or_b32 v231, v232, 9, v231
	v_and_b32_e32 v232, 15, v230
	v_or_b32_e32 v231, v231, v232
	v_add_u32_e32 v234, 0x9000000, v231
	v_mov_b32_e32 v235, 0
	v_lshl_add_u64 v[236:237], v[234:235], 1, s[80:81]
	flat_store_dwordx4 v[236:237], v[158:161]
	s_or_b64 exec, exec, s[36:37]
	s_andn2_b64 s[18:19], s[18:19], exec
	s_or_b64 exec, exec, s[6:7]
	s_and_b64 exec, exec, s[18:19]
	s_cbranch_execz .LBB0_287
.LBB0_272:
	v_and_b32_e32 v158, 0x1f8f, v153
	v_cmp_lt_i32_e32 vcc, s69, v152
	s_and_saveexec_b64 s[6:7], vcc
	s_xor_b64 s[6:7], exec, s[6:7]
	s_cbranch_execz .LBB0_274
	v_lshrrev_b32_e32 v160, 14, v150
	v_and_b32_e32 v180, 0x1c0, v160
	v_lshlrev_b32_e32 v180, 14, v180
	v_bfe_u32 v161, v160, 5, 1
	v_lshl_or_b32 v180, v161, 10, v180
	v_and_b32_e32 v161, 31, v160
	v_lshl_or_b32 v180, v161, 5, v180
	v_lshrrev_b32_e32 v161, 4, v158
	v_lshl_or_b32 v180, v161, 11, v180
	v_and_b32_e32 v161, 15, v158
	v_lshl_or_b32 v180, v161, 1, v180
	v_mov_b32_e32 v181, v1
	v_lshl_add_u64 v[160:161], s[12:13], 0, v[180:181]
	v_cvt_pk_bf16_f32 v126, v126, s0
	flat_store_short v[160:161], v126
	v_add_co_u32_e32 v126, vcc, 0x20, v160
	v_cvt_pk_bf16_f32 v159, v127, s0
	s_nop 0
	v_addc_co_u32_e32 v127, vcc, 0, v161, vcc
	flat_store_short v[126:127], v159
	v_add_co_u32_e32 v126, vcc, 0x40, v160
	v_cvt_pk_bf16_f32 v128, v128, s0
	s_nop 0
	v_addc_co_u32_e32 v127, vcc, 0, v161, vcc
	flat_store_short v[126:127], v128
	v_add_co_u32_e32 v126, vcc, 0x60, v160
	v_cvt_pk_bf16_f32 v128, v129, s0
	s_nop 0
	v_addc_co_u32_e32 v127, vcc, 0, v161, vcc
	flat_store_short v[126:127], v128

; DI bf16_t f2bf(float a) { return (bf16_t)(pk2(a, 0.f) & 0xffffu); }
; DI u32x2 pk4(float a, float b, float c, float d) { u32x2 r; r.x = pk2(a, b); r.y = pk2(c, d); return r; }
;   DI void store(int m, int n, float a, float b, float c, float d) const {
;     ...
;     if (n >= C_VS && n < C_KW) { int e = n - C_VS; bf16_t* p = vsT + ((size_t)(bb * 128 + e)) * SEQ + s; p[0] = f2bf(a); p[SEQ] = f2bf(b); p[2 * SEQ] = f2bf(c); p[3 * SEQ] = f2bf(d); }
;     else if (n >= C_VW && n < C_GATE) { int e = n - C_VW; bf16_t* p = vwT + ((size_t)(bb * 128 + e)) * SEQ + s; p[0] = f2bf(a); p[SEQ] = f2bf(b); p[2 * SEQ] = f2bf(c); p[3 * SEQ] = f2bf(d); }
;     else *(u32x2*)(proj + (size_t)m * EIN + n) = pk4(a, b, c, d); }
.LBB0_280:
	s_or_b64 exec, exec, s[6:7]
	v_cmp_lt_i32_e32 vcc, s69, v152
	s_and_saveexec_b64 s[6:7], vcc
	s_xor_b64 s[6:7], exec, s[6:7]
	s_cbranch_execz .LBB0_282
	v_lshrrev_b32_e32 v126, 14, v146
	v_and_b32_e32 v128, 0x1c0, v126
	v_lshlrev_b32_e32 v128, 14, v128
	v_bfe_u32 v127, v126, 5, 1
	v_lshl_or_b32 v128, v127, 10, v128
	v_and_b32_e32 v127, 31, v126
	v_lshl_or_b32 v128, v127, 5, v128
	v_lshrrev_b32_e32 v127, 4, v158
	v_lshl_or_b32 v128, v127, 11, v128
	v_and_b32_e32 v127, 15, v158
	v_lshl_or_b32 v128, v127, 1, v128
	v_mov_b32_e32 v129, v1
	v_lshl_add_u64 v[126:127], s[12:13], 0, v[128:129]
	v_cvt_pk_bf16_f32 v122, v122, s0
	flat_store_short v[126:127], v122
	v_add_co_u32_e32 v122, vcc, 0x20, v126
	v_cvt_pk_bf16_f32 v128, v123, s0
	s_nop 0
	v_addc_co_u32_e32 v123, vcc, 0, v127, vcc
	flat_store_short v[122:123], v128
	v_add_co_u32_e32 v122, vcc, 0x40, v126
	v_cvt_pk_bf16_f32 v124, v124, s0
	s_nop 0
	v_addc_co_u32_e32 v123, vcc, 0, v127, vcc
	flat_store_short v[122:123], v124
	v_add_co_u32_e32 v122, vcc, 0x60, v126
	v_cvt_pk_bf16_f32 v124, v125, s0
	s_nop 0
	v_addc_co_u32_e32 v123, vcc, 0, v127, vcc
	flat_store_short v[122:123], v124

; DI bf16_t f2bf(float a) { return (bf16_t)(pk2(a, 0.f) & 0xffffu); }
; DI u32x2 pk4(float a, float b, float c, float d) { u32x2 r; r.x = pk2(a, b); r.y = pk2(c, d); return r; }
; template <class AF, class EF>
; DI void gemm_run(unsigned char* lds, int wv, const AF& af, const bf16_t* __restrict__ Bt, int ldb, int M, int N, int K, const EF& ef, int blk_off) {
;     ...
;         for (int k = 0; k < 4; ++k) {
;           auto r = __builtin_amdgcn_permlane16_swap(__float_as_uint(acc[2 * ip][j][k]), __float_as_uint(acc[2 * ip + 1][j][k]), false, false);
;           lo[k] = __uint_as_float(r[0]); hi[k] = __uint_as_float(r[1]);
;         }
;         int n = n0 + wn * 64 + (2 * ip + (q4 & 1)) * 16 + (q4 >> 1) * 8;
;         int m = m0 + wm * 128 + j * 16 + l15;
;         if (n < N) ef.store8(m, n, lo[0], lo[1], lo[2], lo[3], hi[0], hi[1], hi[2], hi[3]);
;   DI void store(int m, int n, float a, float b, float c, float d) const {
;     int bb = m >> 13, s = m & (SEQ - 1);
;     if (n >= C_VS && n < C_KW) { int e = n - C_VS; bf16_t* p = vsT + ((size_t)(bb * 128 + e)) * SEQ + s; p[0] = f2bf(a); p[SEQ] = f2bf(b); p[2 * SEQ] = f2bf(c); p[3 * SEQ] = f2bf(d); }
;     else if (n >= C_VW && n < C_GATE) { int e = n - C_VW; bf16_t* p = vwT + ((size_t)(bb * 128 + e)) * SEQ + s; p[0] = f2bf(a); p[SEQ] = f2bf(b); p[2 * SEQ] = f2bf(c); p[3 * SEQ] = f2bf(d); }
;     else *(u32x2*)(proj + (size_t)m * EIN + n) = pk4(a, b, c, d); }
.LBB0_287:
	s_or_b64 exec, exec, s[16:17]
	v_permlane16_swap_b32_e32 v118, v114
	v_permlane16_swap_b32_e32 v119, v115
	v_permlane16_swap_b32_e32 v120, v116
	v_permlane16_swap_b32_e32 v121, v117
	s_and_saveexec_b64 s[16:17], s[4:5]
	s_cbranch_execz .LBB0_310
	v_cmp_lt_i32_e32 vcc, s69, v152
	s_mov_b64 s[20:21], 0
	s_mov_b64 s[18:19], 0
	s_and_saveexec_b64 s[6:7], vcc
	s_xor_b64 s[6:7], exec, s[6:7]
	v_cmp_ne_u32_e32 vcc, s70, v152
	s_and_b64 s[20:21], vcc, exec
	s_mov_b64 s[18:19], exec
	s_andn2_saveexec_b64 s[22:23], s[6:7]
	v_cmp_eq_u32_e32 vcc, s71, v152
	v_cmp_ne_u32_e64 s[6:7], s71, v152
	s_andn2_b64 s[18:19], s[18:19], exec
	s_and_b64 s[26:27], vcc, exec
	s_andn2_b64 s[20:21], s[20:21], exec
	s_and_b64 s[6:7], s[6:7], exec
	s_or_b64 s[18:19], s[18:19], s[26:27]
	s_or_b64 s[20:21], s[20:21], s[6:7]
	s_or_b64 exec, exec, s[22:23]
	v_or_b32_e32 v122, 16, v153
	s_and_saveexec_b64 s[6:7], s[20:21]
	s_xor_b64 s[6:7], exec, s[6:7]
	s_cbranch_execz .LBB0_294
	v_readlane_b32 s20, v255, 24
	v_readlane_b32 s21, v255, 25
	v_cvt_pk_bf16_f32 v124, v118, v119
	v_cvt_pk_bf16_f32 v125, v120, v121
	v_mov_b64_e32 v[128:129], s[20:21]
	v_mad_i64_i32 v[128:129], s[20:21], v122, s87, v[128:129]
	v_cvt_pk_bf16_f32 v126, v114, v115
	v_cvt_pk_bf16_f32 v127, v116, v117
	v_lshl_add_u64 v[128:129], v[130:131], 1, v[128:129]
	s_andn2_b64 s[18:19], s[18:19], exec
	flat_store_dwordx4 v[128:129], v[124:127]
	v_subrev_u32_e32 v230, 0x300, v130
	v_lshrrev_b32_e32 v232, 7, v230
	v_cmp_eq_u32_e64 s[30:31], 0, v232
	s_and_saveexec_b64 s[36:37], s[30:31]
	v_readlane_b32 s80, v255, 24
	v_readlane_b32 s81, v255, 25
	v_lshrrev_b32_e32 v231, 13, v122
	v_lshlrev_b32_e32 v231, 20, v231
	v_lshrrev_b32_e32 v232, 6, v230
	v_lshl_or_b32 v231, v232, 19, v231
	v_bfe_u32 v232, v122, 6, 7
	v_lshl_or_b32 v231, v232, 12, v231
	v_bfe_u32 v232, v122, 5, 1
	v_lshl_or_b32 v231, v232, 11, v231
	v_bfe_u32 v232, v122, 2, 1
	v_lshl_or_b32 v231, v232, 10, v231
	v_bfe_u32 v232, v230, 5, 1
	v_lshl_or_b32 v231, v232, 9, v231
	v_bfe_u32 v232, v122, 3, 2
	v_lshl_or_b32 v231, v232, 7, v231
	v_bfe_u32 v232, v122, 0, 2
	v_lshl_or_b32 v231, v232, 5, v231
	v_and_b32_e32 v232, 31, v230
	v_or_b32_e32 v231, v231, v232
	v_add_u32_e32 v234, 0x9c00000, v231
	v_mov_b32_e32 v235, 0
	v_lshl_add_u64 v[236:237], v[234:235], 1, s[80:81]
	flat_store_dwordx4 v[236:237], v[124:127]
	s_or_b64 exec, exec, s[36:37]
	v_subrev_u32_e32 v230, 0x998, v130
	v_cmp_gt_u32_e64 s[30:31], 64, v230
	s_and_saveexec_b64 s[36:37], s[30:31]
	v_readlane_b32 s80, v255, 24
	v_readlane_b32 s81, v255, 25
	v_lshrrev_b32_e32 v231, 5, v122
	v_lshlrev_b32_e32 v231, 11, v231
	v_and_b32_e32 v232, 31, v122
	v_lshl_or_b32 v231, v232, 4, v231
	v_lshrrev_b32_e32 v232, 4, v230
	v_lshl_or_b32 v231, v232, 9, v231
	v_and_b32_e32 v232, 15, v230
	v_or_b32_e32 v231, v231, v232
	v_add_u32_e32 v234, 0x9000000, v231
	v_mov_b32_e32 v235, 0
	v_lshl_add_u64 v[236:237], v[234:235], 1, s[80:81]
	flat_store_dwordx4 v[236:237], v[124:127]
	s_or_b64 exec, exec, s[36:37]
.LBB0_294:
	s_or_b64 exec, exec, s[6:7]
	s_and_b64 exec, exec, s[18:19]
	s_cbranch_execz .LBB0_310
	v_and_b32_e32 v123, 0x1f9f, v122
	v_cmp_lt_i32_e32 vcc, s69, v152
	s_and_saveexec_b64 s[6:7], vcc
	s_xor_b64 s[6:7], exec, s[6:7]
	s_cbranch_execz .LBB0_297
	v_lshrrev_b32_e32 v124, 14, v150
	v_and_b32_e32 v126, 0x1c0, v124
	v_lshlrev_b32_e32 v126, 14, v126
	v_bfe_u32 v125, v124, 5, 1
	v_lshl_or_b32 v126, v125, 10, v126
	v_and_b32_e32 v125, 31, v124
	v_lshl_or_b32 v126, v125, 5, v126
	v_lshrrev_b32_e32 v125, 4, v123
	v_lshl_or_b32 v126, v125, 11, v126
	v_and_b32_e32 v125, 15, v123
	v_lshl_or_b32 v126, v125, 1, v126
	v_mov_b32_e32 v127, v1
	v_lshl_add_u64 v[124:125], s[12:13], 0, v[126:127]
	v_cvt_pk_bf16_f32 v118, v118, s0
	flat_store_short v[124:125], v118
	v_add_co_u32_e32 v118, vcc, 0x20, v124
	v_cvt_pk_bf16_f32 v126, v119, s0
	s_nop 0
	v_addc_co_u32_e32 v119, vcc, 0, v125, vcc
	flat_store_short v[118:119], v126
	v_add_co_u32_e32 v118, vcc, 0x40, v124
	v_cvt_pk_bf16_f32 v120, v120, s0
	s_nop 0
	v_addc_co_u32_e32 v119, vcc, 0, v125, vcc
	flat_store_short v[118:119], v120
	v_add_co_u32_e32 v118, vcc, 0x60, v124
	v_cvt_pk_bf16_f32 v120, v121, s0
	s_nop 0
	v_addc_co_u32_e32 v119, vcc, 0, v125, vcc
	flat_store_short v[118:119], v120

; DI bf16_t f2bf(float a) { return (bf16_t)(pk2(a, 0.f) & 0xffffu); }
; DI u32x2 pk4(float a, float b, float c, float d) { u32x2 r; r.x = pk2(a, b); r.y = pk2(c, d); return r; }
;   DI void store(int m, int n, float a, float b, float c, float d) const {
;     ...
;     if (n >= C_VS && n < C_KW) { int e = n - C_VS; bf16_t* p = vsT + ((size_t)(bb * 128 + e)) * SEQ + s; p[0] = f2bf(a); p[SEQ] = f2bf(b); p[2 * SEQ] = f2bf(c); p[3 * SEQ] = f2bf(d); }
;     else if (n >= C_VW && n < C_GATE) { int e = n - C_VW; bf16_t* p = vwT + ((size_t)(bb * 128 + e)) * SEQ + s; p[0] = f2bf(a); p[SEQ] = f2bf(b); p[2 * SEQ] = f2bf(c); p[3 * SEQ] = f2bf(d); }
;     else *(u32x2*)(proj + (size_t)m * EIN + n) = pk4(a, b, c, d); }
.LBB0_303:
	s_or_b64 exec, exec, s[6:7]
	v_cmp_lt_i32_e32 vcc, s69, v152
	s_and_saveexec_b64 s[6:7], vcc
	s_xor_b64 s[6:7], exec, s[6:7]
	s_cbranch_execz .LBB0_305
	v_lshrrev_b32_e32 v118, 14, v146
	v_and_b32_e32 v120, 0x1c0, v118
	v_lshlrev_b32_e32 v120, 14, v120
	v_bfe_u32 v119, v118, 5, 1
	v_lshl_or_b32 v120, v119, 10, v120
	v_and_b32_e32 v119, 31, v118
	v_lshl_or_b32 v120, v119, 5, v120
	v_lshrrev_b32_e32 v119, 4, v123
	v_lshl_or_b32 v120, v119, 11, v120
	v_and_b32_e32 v119, 15, v123
	v_lshl_or_b32 v120, v119, 1, v120
	v_mov_b32_e32 v121, v1
	v_lshl_add_u64 v[118:119], s[12:13], 0, v[120:121]
	v_cvt_pk_bf16_f32 v114, v114, s0
	flat_store_short v[118:119], v114
	v_add_co_u32_e32 v114, vcc, 0x20, v118
	v_cvt_pk_bf16_f32 v120, v115, s0
	s_nop 0
	v_addc_co_u32_e32 v115, vcc, 0, v119, vcc
	flat_store_short v[114:115], v120
	v_add_co_u32_e32 v114, vcc, 0x40, v118
	v_cvt_pk_bf16_f32 v116, v116, s0
	s_nop 0
	v_addc_co_u32_e32 v115, vcc, 0, v119, vcc
	flat_store_short v[114:115], v116
	v_add_co_u32_e32 v114, vcc, 0x60, v118
	v_cvt_pk_bf16_f32 v116, v117, s0
	s_nop 0
	v_addc_co_u32_e32 v115, vcc, 0, v119, vcc
	flat_store_short v[114:115], v116

; DI bf16_t f2bf(float a) { return (bf16_t)(pk2(a, 0.f) & 0xffffu); }
; DI u32x2 pk4(float a, float b, float c, float d) { u32x2 r; r.x = pk2(a, b); r.y = pk2(c, d); return r; }
; template <class AF, class EF>
; DI void gemm_run(unsigned char* lds, int wv, const AF& af, const bf16_t* __restrict__ Bt, int ldb, int M, int N, int K, const EF& ef, int blk_off) {
;     ...
;         for (int k = 0; k < 4; ++k) {
;           auto r = __builtin_amdgcn_permlane16_swap(__float_as_uint(acc[2 * ip][j][k]), __float_as_uint(acc[2 * ip + 1][j][k]), false, false);
;           lo[k] = __uint_as_float(r[0]); hi[k] = __uint_as_float(r[1]);
;         }
;         int n = n0 + wn * 64 + (2 * ip + (q4 & 1)) * 16 + (q4 >> 1) * 8;
;         int m = m0 + wm * 128 + j * 16 + l15;
;         if (n < N) ef.store8(m, n, lo[0], lo[1], lo[2], lo[3], hi[0], hi[1], hi[2], hi[3]);
;   DI void store(int m, int n, float a, float b, float c, float d) const {
;     int bb = m >> 13, s = m & (SEQ - 1);
;     if (n >= C_VS && n < C_KW) { int e = n - C_VS; bf16_t* p = vsT + ((size_t)(bb * 128 + e)) * SEQ + s; p[0] = f2bf(a); p[SEQ] = f2bf(b); p[2 * SEQ] = f2bf(c); p[3 * SEQ] = f2bf(d); }
;     else if (n >= C_VW && n < C_GATE) { int e = n - C_VW; bf16_t* p = vwT + ((size_t)(bb * 128 + e)) * SEQ + s; p[0] = f2bf(a); p[SEQ] = f2bf(b); p[2 * SEQ] = f2bf(c); p[3 * SEQ] = f2bf(d); }
;     else *(u32x2*)(proj + (size_t)m * EIN + n) = pk4(a, b, c, d); }
.LBB0_310:
	s_or_b64 exec, exec, s[16:17]
	v_permlane16_swap_b32_e32 v110, v106
	v_permlane16_swap_b32_e32 v111, v107
	v_permlane16_swap_b32_e32 v112, v108
	v_permlane16_swap_b32_e32 v113, v109
	s_and_saveexec_b64 s[16:17], s[4:5]
	s_cbranch_execz .LBB0_333
	v_cmp_lt_i32_e32 vcc, s69, v152
	s_mov_b64 s[20:21], 0
	s_mov_b64 s[18:19], 0
	s_and_saveexec_b64 s[6:7], vcc
	s_xor_b64 s[6:7], exec, s[6:7]
	v_cmp_ne_u32_e32 vcc, s70, v152
	s_and_b64 s[20:21], vcc, exec
	s_mov_b64 s[18:19], exec
	s_andn2_saveexec_b64 s[22:23], s[6:7]
	v_cmp_eq_u32_e32 vcc, s71, v152
	v_cmp_ne_u32_e64 s[6:7], s71, v152
	s_andn2_b64 s[18:19], s[18:19], exec
	s_and_b64 s[26:27], vcc, exec
	s_andn2_b64 s[20:21], s[20:21], exec
	s_and_b64 s[6:7], s[6:7], exec
	s_or_b64 s[18:19], s[18:19], s[26:27]
	s_or_b64 s[20:21], s[20:21], s[6:7]
	s_or_b64 exec, exec, s[22:23]
	v_or_b32_e32 v114, 32, v153
	s_and_saveexec_b64 s[6:7], s[20:21]
	s_xor_b64 s[6:7], exec, s[6:7]
	s_cbranch_execz .LBB0_317
	v_readlane_b32 s20, v255, 24
	v_readlane_b32 s21, v255, 25
	v_cvt_pk_bf16_f32 v116, v110, v111
	v_cvt_pk_bf16_f32 v117, v112, v113
	v_mov_b64_e32 v[120:121], s[20:21]
	v_mad_i64_i32 v[120:121], s[20:21], v114, s87, v[120:121]
	v_cvt_pk_bf16_f32 v118, v106, v107
	v_cvt_pk_bf16_f32 v119, v108, v109
	v_lshl_add_u64 v[120:121], v[130:131], 1, v[120:121]
	s_andn2_b64 s[18:19], s[18:19], exec
	flat_store_dwordx4 v[120:121], v[116:119]
	v_subrev_u32_e32 v230, 0x300, v130
	v_lshrrev_b32_e32 v232, 7, v230
	v_cmp_eq_u32_e64 s[30:31], 0, v232
	s_and_saveexec_b64 s[36:37], s[30:31]
	v_readlane_b32 s80, v255, 24
	v_readlane_b32 s81, v255, 25
	v_lshrrev_b32_e32 v231, 13, v114
	v_lshlrev_b32_e32 v231, 20, v231
	v_lshrrev_b32_e32 v232, 6, v230
	v_lshl_or_b32 v231, v232, 19, v231
	v_bfe_u32 v232, v114, 6, 7
	v_lshl_or_b32 v231, v232, 12, v231
	v_bfe_u32 v232, v114, 5, 1
	v_lshl_or_b32 v231, v232, 11, v231
	v_bfe_u32 v232, v114, 2, 1
	v_lshl_or_b32 v231, v232, 10, v231
	v_bfe_u32 v232, v230, 5, 1
	v_lshl_or_b32 v231, v232, 9, v231
	v_bfe_u32 v232, v114, 3, 2
	v_lshl_or_b32 v231, v232, 7, v231
	v_bfe_u32 v232, v114, 0, 2
	v_lshl_or_b32 v231, v232, 5, v231
	v_and_b32_e32 v232, 31, v230
	v_or_b32_e32 v231, v231, v232
	v_add_u32_e32 v234, 0x9c00000, v231
	v_mov_b32_e32 v235, 0
	v_lshl_add_u64 v[236:237], v[234:235], 1, s[80:81]
	flat_store_dwordx4 v[236:237], v[116:119]
	s_or_b64 exec, exec, s[36:37]
	v_subrev_u32_e32 v230, 0x998, v130
	v_cmp_gt_u32_e64 s[30:31], 64, v230
	s_and_saveexec_b64 s[36:37], s[30:31]
	v_readlane_b32 s80, v255, 24
	v_readlane_b32 s81, v255, 25
	v_lshrrev_b32_e32 v231, 5, v114
	v_lshlrev_b32_e32 v231, 11, v231
	v_and_b32_e32 v232, 31, v114
	v_lshl_or_b32 v231, v232, 4, v231
	v_lshrrev_b32_e32 v232, 4, v230
	v_lshl_or_b32 v231, v232, 9, v231
	v_and_b32_e32 v232, 15, v230
	v_or_b32_e32 v231, v231, v232
	v_add_u32_e32 v234, 0x9000000, v231
	v_mov_b32_e32 v235, 0
	v_lshl_add_u64 v[236:237], v[234:235], 1, s[80:81]
	flat_store_dwordx4 v[236:237], v[116:119]
	s_or_b64 exec, exec, s[36:37]
.LBB0_317:
	s_or_b64 exec, exec, s[6:7]
	s_and_b64 exec, exec, s[18:19]
	s_cbranch_execz .LBB0_333
	v_and_b32_e32 v115, 0x1faf, v114
	v_cmp_lt_i32_e32 vcc, s69, v152
	s_and_saveexec_b64 s[6:7], vcc
	s_xor_b64 s[6:7], exec, s[6:7]
	s_cbranch_execz .LBB0_320
	v_lshrrev_b32_e32 v116, 14, v150
	v_and_b32_e32 v118, 0x1c0, v116
	v_lshlrev_b32_e32 v118, 14, v118
	v_bfe_u32 v117, v116, 5, 1
	v_lshl_or_b32 v118, v117, 10, v118
	v_and_b32_e32 v117, 31, v116
	v_lshl_or_b32 v118, v117, 5, v118
	v_lshrrev_b32_e32 v117, 4, v115
	v_lshl_or_b32 v118, v117, 11, v118
	v_and_b32_e32 v117, 15, v115
	v_lshl_or_b32 v118, v117, 1, v118
	v_mov_b32_e32 v119, v1
	v_lshl_add_u64 v[116:117], s[12:13], 0, v[118:119]
	v_cvt_pk_bf16_f32 v110, v110, s0
	flat_store_short v[116:117], v110
	v_add_co_u32_e32 v110, vcc, 0x20, v116
	v_cvt_pk_bf16_f32 v118, v111, s0
	s_nop 0
	v_addc_co_u32_e32 v111, vcc, 0, v117, vcc
	flat_store_short v[110:111], v118
	v_add_co_u32_e32 v110, vcc, 0x40, v116
	v_cvt_pk_bf16_f32 v112, v112, s0
	s_nop 0
	v_addc_co_u32_e32 v111, vcc, 0, v117, vcc
	flat_store_short v[110:111], v112
	v_add_co_u32_e32 v110, vcc, 0x60, v116
	v_cvt_pk_bf16_f32 v112, v113, s0
	s_nop 0
	v_addc_co_u32_e32 v111, vcc, 0, v117, vcc
	flat_store_short v[110:111], v112

; DI bf16_t f2bf(float a) { return (bf16_t)(pk2(a, 0.f) & 0xffffu); }
; DI u32x2 pk4(float a, float b, float c, float d) { u32x2 r; r.x = pk2(a, b); r.y = pk2(c, d); return r; }
;   DI void store(int m, int n, float a, float b, float c, float d) const {
;     ...
;     if (n >= C_VS && n < C_KW) { int e = n - C_VS; bf16_t* p = vsT + ((size_t)(bb * 128 + e)) * SEQ + s; p[0] = f2bf(a); p[SEQ] = f2bf(b); p[2 * SEQ] = f2bf(c); p[3 * SEQ] = f2bf(d); }
;     else if (n >= C_VW && n < C_GATE) { int e = n - C_VW; bf16_t* p = vwT + ((size_t)(bb * 128 + e)) * SEQ + s; p[0] = f2bf(a); p[SEQ] = f2bf(b); p[2 * SEQ] = f2bf(c); p[3 * SEQ] = f2bf(d); }
;     else *(u32x2*)(proj + (size_t)m * EIN + n) = pk4(a, b, c, d); }
.LBB0_326:
	s_or_b64 exec, exec, s[6:7]
	v_cmp_lt_i32_e32 vcc, s69, v152
	s_and_saveexec_b64 s[6:7], vcc
	s_xor_b64 s[6:7], exec, s[6:7]
	s_cbranch_execz .LBB0_328
	v_lshrrev_b32_e32 v110, 14, v146
	v_and_b32_e32 v112, 0x1c0, v110
	v_lshlrev_b32_e32 v112, 14, v112
	v_bfe_u32 v111, v110, 5, 1
	v_lshl_or_b32 v112, v111, 10, v112
	v_and_b32_e32 v111, 31, v110
	v_lshl_or_b32 v112, v111, 5, v112
	v_lshrrev_b32_e32 v111, 4, v115
	v_lshl_or_b32 v112, v111, 11, v112
	v_and_b32_e32 v111, 15, v115
	v_lshl_or_b32 v112, v111, 1, v112
	v_mov_b32_e32 v113, v1
	v_lshl_add_u64 v[110:111], s[12:13], 0, v[112:113]
	v_cvt_pk_bf16_f32 v106, v106, s0
	flat_store_short v[110:111], v106
	v_add_co_u32_e32 v106, vcc, 0x20, v110
	v_cvt_pk_bf16_f32 v112, v107, s0
	s_nop 0
	v_addc_co_u32_e32 v107, vcc, 0, v111, vcc
	flat_store_short v[106:107], v112
	v_add_co_u32_e32 v106, vcc, 0x40, v110
	v_cvt_pk_bf16_f32 v108, v108, s0
	s_nop 0
	v_addc_co_u32_e32 v107, vcc, 0, v111, vcc
	flat_store_short v[106:107], v108
	v_add_co_u32_e32 v106, vcc, 0x60, v110
	v_cvt_pk_bf16_f32 v108, v109, s0
	s_nop 0
	v_addc_co_u32_e32 v107, vcc, 0, v111, vcc
	flat_store_short v[106:107], v108

; DI bf16_t f2bf(float a) { return (bf16_t)(pk2(a, 0.f) & 0xffffu); }
; DI u32x2 pk4(float a, float b, float c, float d) { u32x2 r; r.x = pk2(a, b); r.y = pk2(c, d); return r; }
; template <class AF, class EF>
; DI void gemm_run(unsigned char* lds, int wv, const AF& af, const bf16_t* __restrict__ Bt, int ldb, int M, int N, int K, const EF& ef, int blk_off) {
;     ...
;         for (int k = 0; k < 4; ++k) {
;           auto r = __builtin_amdgcn_permlane16_swap(__float_as_uint(acc[2 * ip][j][k]), __float_as_uint(acc[2 * ip + 1][j][k]), false, false);
;           lo[k] = __uint_as_float(r[0]); hi[k] = __uint_as_float(r[1]);
;         }
;         int n = n0 + wn * 64 + (2 * ip + (q4 & 1)) * 16 + (q4 >> 1) * 8;
;         int m = m0 + wm * 128 + j * 16 + l15;
;         if (n < N) ef.store8(m, n, lo[0], lo[1], lo[2], lo[3], hi[0], hi[1], hi[2], hi[3]);
;   DI void store(int m, int n, float a, float b, float c, float d) const {
;     int bb = m >> 13, s = m & (SEQ - 1);
;     if (n >= C_VS && n < C_KW) { int e = n - C_VS; bf16_t* p = vsT + ((size_t)(bb * 128 + e)) * SEQ + s; p[0] = f2bf(a); p[SEQ] = f2bf(b); p[2 * SEQ] = f2bf(c); p[3 * SEQ] = f2bf(d); }
;     else if (n >= C_VW && n < C_GATE) { int e = n - C_VW; bf16_t* p = vwT + ((size_t)(bb * 128 + e)) * SEQ + s; p[0] = f2bf(a); p[SEQ] = f2bf(b); p[2 * SEQ] = f2bf(c); p[3 * SEQ] = f2bf(d); }
;     else *(u32x2*)(proj + (size_t)m * EIN + n) = pk4(a, b, c, d); }
.LBB0_333:
	s_or_b64 exec, exec, s[16:17]
	v_permlane16_swap_b32_e32 v102, v98
	v_permlane16_swap_b32_e32 v103, v99
	v_permlane16_swap_b32_e32 v104, v100
	v_permlane16_swap_b32_e32 v105, v101
	s_and_saveexec_b64 s[16:17], s[4:5]
	s_cbranch_execz .LBB0_356
	v_cmp_lt_i32_e32 vcc, s69, v152
	s_mov_b64 s[20:21], 0
	s_mov_b64 s[18:19], 0
	s_and_saveexec_b64 s[6:7], vcc
	s_xor_b64 s[6:7], exec, s[6:7]
	v_cmp_ne_u32_e32 vcc, s70, v152
	s_and_b64 s[20:21], vcc, exec
	s_mov_b64 s[18:19], exec
	s_andn2_saveexec_b64 s[22:23], s[6:7]
	v_cmp_eq_u32_e32 vcc, s71, v152
	v_cmp_ne_u32_e64 s[6:7], s71, v152
	s_andn2_b64 s[18:19], s[18:19], exec
	s_and_b64 s[26:27], vcc, exec
	s_andn2_b64 s[20:21], s[20:21], exec
	s_and_b64 s[6:7], s[6:7], exec
	s_or_b64 s[18:19], s[18:19], s[26:27]
	s_or_b64 s[20:21], s[20:21], s[6:7]
	s_or_b64 exec, exec, s[22:23]
	v_or_b32_e32 v106, 48, v153
	s_and_saveexec_b64 s[6:7], s[20:21]
	s_xor_b64 s[6:7], exec, s[6:7]
	s_cbranch_execz .LBB0_340
	v_readlane_b32 s20, v255, 24
	v_readlane_b32 s21, v255, 25
	v_cvt_pk_bf16_f32 v108, v102, v103
	v_cvt_pk_bf16_f32 v109, v104, v105
	v_mov_b64_e32 v[112:113], s[20:21]
	v_mad_i64_i32 v[112:113], s[20:21], v106, s87, v[112:113]
	v_cvt_pk_bf16_f32 v110, v98, v99
	v_cvt_pk_bf16_f32 v111, v100, v101
	v_lshl_add_u64 v[112:113], v[130:131], 1, v[112:113]
	s_andn2_b64 s[18:19], s[18:19], exec
	flat_store_dwordx4 v[112:113], v[108:111]
	v_subrev_u32_e32 v230, 0x300, v130
	v_lshrrev_b32_e32 v232, 7, v230
	v_cmp_eq_u32_e64 s[30:31], 0, v232
	s_and_saveexec_b64 s[36:37], s[30:31]
	v_readlane_b32 s80, v255, 24
	v_readlane_b32 s81, v255, 25
	v_lshrrev_b32_e32 v231, 13, v106
	v_lshlrev_b32_e32 v231, 20, v231
	v_lshrrev_b32_e32 v232, 6, v230
	v_lshl_or_b32 v231, v232, 19, v231
	v_bfe_u32 v232, v106, 6, 7
	v_lshl_or_b32 v231, v232, 12, v231
	v_bfe_u32 v232, v106, 5, 1
	v_lshl_or_b32 v231, v232, 11, v231
	v_bfe_u32 v232, v106, 2, 1
	v_lshl_or_b32 v231, v232, 10, v231
	v_bfe_u32 v232, v230, 5, 1
	v_lshl_or_b32 v231, v232, 9, v231
	v_bfe_u32 v232, v106, 3, 2
	v_lshl_or_b32 v231, v232, 7, v231
	v_bfe_u32 v232, v106, 0, 2
	v_lshl_or_b32 v231, v232, 5, v231
	v_and_b32_e32 v232, 31, v230
	v_or_b32_e32 v231, v231, v232
	v_add_u32_e32 v234, 0x9c00000, v231
	v_mov_b32_e32 v235, 0
	v_lshl_add_u64 v[236:237], v[234:235], 1, s[80:81]
	flat_store_dwordx4 v[236:237], v[108:111]
	s_or_b64 exec, exec, s[36:37]
	v_subrev_u32_e32 v230, 0x998, v130
	v_cmp_gt_u32_e64 s[30:31], 64, v230
	s_and_saveexec_b64 s[36:37], s[30:31]
	v_readlane_b32 s80, v255, 24
	v_readlane_b32 s81, v255, 25
	v_lshrrev_b32_e32 v231, 5, v106
	v_lshlrev_b32_e32 v231, 11, v231
	v_and_b32_e32 v232, 31, v106
	v_lshl_or_b32 v231, v232, 4, v231
	v_lshrrev_b32_e32 v232, 4, v230
	v_lshl_or_b32 v231, v232, 9, v231
	v_and_b32_e32 v232, 15, v230
	v_or_b32_e32 v231, v231, v232
	v_add_u32_e32 v234, 0x9000000, v231
	v_mov_b32_e32 v235, 0
	v_lshl_add_u64 v[236:237], v[234:235], 1, s[80:81]
	flat_store_dwordx4 v[236:237], v[108:111]
	s_or_b64 exec, exec, s[36:37]
.LBB0_340:
	s_or_b64 exec, exec, s[6:7]
	s_and_b64 exec, exec, s[18:19]
	s_cbranch_execz .LBB0_356
	v_and_b32_e32 v107, 0x1fbf, v106
	v_cmp_lt_i32_e32 vcc, s69, v152
	s_and_saveexec_b64 s[6:7], vcc
	s_xor_b64 s[6:7], exec, s[6:7]
	s_cbranch_execz .LBB0_343
	v_lshrrev_b32_e32 v108, 14, v150
	v_and_b32_e32 v110, 0x1c0, v108
	v_lshlrev_b32_e32 v110, 14, v110
	v_bfe_u32 v109, v108, 5, 1
	v_lshl_or_b32 v110, v109, 10, v110
	v_and_b32_e32 v109, 31, v108
	v_lshl_or_b32 v110, v109, 5, v110
	v_lshrrev_b32_e32 v109, 4, v107
	v_lshl_or_b32 v110, v109, 11, v110
	v_and_b32_e32 v109, 15, v107
	v_lshl_or_b32 v110, v109, 1, v110
	v_mov_b32_e32 v111, v1
	v_lshl_add_u64 v[108:109], s[12:13], 0, v[110:111]
	v_cvt_pk_bf16_f32 v102, v102, s0
	flat_store_short v[108:109], v102
	v_add_co_u32_e32 v102, vcc, 0x20, v108
	v_cvt_pk_bf16_f32 v110, v103, s0
	s_nop 0
	v_addc_co_u32_e32 v103, vcc, 0, v109, vcc
	flat_store_short v[102:103], v110
	v_add_co_u32_e32 v102, vcc, 0x40, v108
	v_cvt_pk_bf16_f32 v104, v104, s0
	s_nop 0
	v_addc_co_u32_e32 v103, vcc, 0, v109, vcc
	flat_store_short v[102:103], v104
	v_add_co_u32_e32 v102, vcc, 0x60, v108
	v_cvt_pk_bf16_f32 v104, v105, s0
	s_nop 0
	v_addc_co_u32_e32 v103, vcc, 0, v109, vcc
	flat_store_short v[102:103], v104

; DI bf16_t f2bf(float a) { return (bf16_t)(pk2(a, 0.f) & 0xffffu); }
; DI u32x2 pk4(float a, float b, float c, float d) { u32x2 r; r.x = pk2(a, b); r.y = pk2(c, d); return r; }
;   DI void store(int m, int n, float a, float b, float c, float d) const {
;     ...
;     if (n >= C_VS && n < C_KW) { int e = n - C_VS; bf16_t* p = vsT + ((size_t)(bb * 128 + e)) * SEQ + s; p[0] = f2bf(a); p[SEQ] = f2bf(b); p[2 * SEQ] = f2bf(c); p[3 * SEQ] = f2bf(d); }
;     else if (n >= C_VW && n < C_GATE) { int e = n - C_VW; bf16_t* p = vwT + ((size_t)(bb * 128 + e)) * SEQ + s; p[0] = f2bf(a); p[SEQ] = f2bf(b); p[2 * SEQ] = f2bf(c); p[3 * SEQ] = f2bf(d); }
;     else *(u32x2*)(proj + (size_t)m * EIN + n) = pk4(a, b, c, d); }
.LBB0_349:
	s_or_b64 exec, exec, s[6:7]
	v_cmp_lt_i32_e32 vcc, s69, v152
	s_and_saveexec_b64 s[6:7], vcc
	s_xor_b64 s[6:7], exec, s[6:7]
	s_cbranch_execz .LBB0_351
	v_lshrrev_b32_e32 v102, 14, v146
	v_and_b32_e32 v104, 0x1c0, v102
	v_lshlrev_b32_e32 v104, 14, v104
	v_bfe_u32 v103, v102, 5, 1
	v_lshl_or_b32 v104, v103, 10, v104
	v_and_b32_e32 v103, 31, v102
	v_lshl_or_b32 v104, v103, 5, v104
	v_lshrrev_b32_e32 v103, 4, v107
	v_lshl_or_b32 v104, v103, 11, v104
	v_and_b32_e32 v103, 15, v107
	v_lshl_or_b32 v104, v103, 1, v104
	v_mov_b32_e32 v105, v1
	v_lshl_add_u64 v[102:103], s[12:13], 0, v[104:105]
	v_cvt_pk_bf16_f32 v98, v98, s0
	flat_store_short v[102:103], v98
	v_add_co_u32_e32 v98, vcc, 0x20, v102
	v_cvt_pk_bf16_f32 v104, v99, s0
	s_nop 0
	v_addc_co_u32_e32 v99, vcc, 0, v103, vcc
	flat_store_short v[98:99], v104
	v_add_co_u32_e32 v98, vcc, 0x40, v102
	v_cvt_pk_bf16_f32 v100, v100, s0
	s_nop 0
	v_addc_co_u32_e32 v99, vcc, 0, v103, vcc
	flat_store_short v[98:99], v100
	v_add_co_u32_e32 v98, vcc, 0x60, v102
	v_cvt_pk_bf16_f32 v100, v101, s0
	s_nop 0
	v_addc_co_u32_e32 v99, vcc, 0, v103, vcc
	flat_store_short v[98:99], v100

; DI bf16_t f2bf(float a) { return (bf16_t)(pk2(a, 0.f) & 0xffffu); }
; DI u32x2 pk4(float a, float b, float c, float d) { u32x2 r; r.x = pk2(a, b); r.y = pk2(c, d); return r; }
; template <class AF, class EF>
; DI void gemm_run(unsigned char* lds, int wv, const AF& af, const bf16_t* __restrict__ Bt, int ldb, int M, int N, int K, const EF& ef, int blk_off) {
;     ...
;         for (int k = 0; k < 4; ++k) {
;           auto r = __builtin_amdgcn_permlane16_swap(__float_as_uint(acc[2 * ip][j][k]), __float_as_uint(acc[2 * ip + 1][j][k]), false, false);
;           lo[k] = __uint_as_float(r[0]); hi[k] = __uint_as_float(r[1]);
;         }
;         int n = n0 + wn * 64 + (2 * ip + (q4 & 1)) * 16 + (q4 >> 1) * 8;
;         int m = m0 + wm * 128 + j * 16 + l15;
;         if (n < N) ef.store8(m, n, lo[0], lo[1], lo[2], lo[3], hi[0], hi[1], hi[2], hi[3]);
;   DI void store(int m, int n, float a, float b, float c, float d) const {
;     int bb = m >> 13, s = m & (SEQ - 1);
;     if (n >= C_VS && n < C_KW) { int e = n - C_VS; bf16_t* p = vsT + ((size_t)(bb * 128 + e)) * SEQ + s; p[0] = f2bf(a); p[SEQ] = f2bf(b); p[2 * SEQ] = f2bf(c); p[3 * SEQ] = f2bf(d); }
;     else if (n >= C_VW && n < C_GATE) { int e = n - C_VW; bf16_t* p = vwT + ((size_t)(bb * 128 + e)) * SEQ + s; p[0] = f2bf(a); p[SEQ] = f2bf(b); p[2 * SEQ] = f2bf(c); p[3 * SEQ] = f2bf(d); }
;     else *(u32x2*)(proj + (size_t)m * EIN + n) = pk4(a, b, c, d); }
.LBB0_356:
	s_or_b64 exec, exec, s[16:17]
	v_permlane16_swap_b32_e32 v94, v90
	v_permlane16_swap_b32_e32 v95, v91
	v_permlane16_swap_b32_e32 v96, v92
	v_permlane16_swap_b32_e32 v97, v93
	s_and_saveexec_b64 s[16:17], s[4:5]
	s_cbranch_execz .LBB0_379
	v_cmp_lt_i32_e32 vcc, s69, v152
	s_mov_b64 s[20:21], 0
	s_mov_b64 s[18:19], 0
	s_and_saveexec_b64 s[6:7], vcc
	s_xor_b64 s[6:7], exec, s[6:7]
	v_cmp_ne_u32_e32 vcc, s70, v152
	s_and_b64 s[20:21], vcc, exec
	s_mov_b64 s[18:19], exec
	s_andn2_saveexec_b64 s[22:23], s[6:7]
	v_cmp_eq_u32_e32 vcc, s71, v152
	v_cmp_ne_u32_e64 s[6:7], s71, v152
	s_andn2_b64 s[18:19], s[18:19], exec
	s_and_b64 s[26:27], vcc, exec
	s_andn2_b64 s[20:21], s[20:21], exec
	s_and_b64 s[6:7], s[6:7], exec
	s_or_b64 s[18:19], s[18:19], s[26:27]
	s_or_b64 s[20:21], s[20:21], s[6:7]
	s_or_b64 exec, exec, s[22:23]
	v_or_b32_e32 v98, 64, v153
	s_and_saveexec_b64 s[6:7], s[20:21]
	s_xor_b64 s[6:7], exec, s[6:7]
	s_cbranch_execz .LBB0_363
	v_readlane_b32 s20, v255, 24
	v_readlane_b32 s21, v255, 25
	v_cvt_pk_bf16_f32 v100, v94, v95
	v_cvt_pk_bf16_f32 v101, v96, v97
	v_mov_b64_e32 v[104:105], s[20:21]
	v_mad_i64_i32 v[104:105], s[20:21], v98, s87, v[104:105]
	v_cvt_pk_bf16_f32 v102, v90, v91
	v_cvt_pk_bf16_f32 v103, v92, v93
	v_lshl_add_u64 v[104:105], v[130:131], 1, v[104:105]
	s_andn2_b64 s[18:19], s[18:19], exec
	flat_store_dwordx4 v[104:105], v[100:103]
	v_subrev_u32_e32 v230, 0x300, v130
	v_lshrrev_b32_e32 v232, 7, v230
	v_cmp_eq_u32_e64 s[30:31], 0, v232
	s_and_saveexec_b64 s[36:37], s[30:31]
	v_readlane_b32 s80, v255, 24
	v_readlane_b32 s81, v255, 25
	v_lshrrev_b32_e32 v231, 13, v98
	v_lshlrev_b32_e32 v231, 20, v231
	v_lshrrev_b32_e32 v232, 6, v230
	v_lshl_or_b32 v231, v232, 19, v231
	v_bfe_u32 v232, v98, 6, 7
	v_lshl_or_b32 v231, v232, 12, v231
	v_bfe_u32 v232, v98, 5, 1
	v_lshl_or_b32 v231, v232, 11, v231
	v_bfe_u32 v232, v98, 2, 1
	v_lshl_or_b32 v231, v232, 10, v231
	v_bfe_u32 v232, v230, 5, 1
	v_lshl_or_b32 v231, v232, 9, v231
	v_bfe_u32 v232, v98, 3, 2
	v_lshl_or_b32 v231, v232, 7, v231
	v_bfe_u32 v232, v98, 0, 2
	v_lshl_or_b32 v231, v232, 5, v231
	v_and_b32_e32 v232, 31, v230
	v_or_b32_e32 v231, v231, v232
	v_add_u32_e32 v234, 0x9c00000, v231
	v_mov_b32_e32 v235, 0
	v_lshl_add_u64 v[236:237], v[234:235], 1, s[80:81]
	flat_store_dwordx4 v[236:237], v[100:103]
	s_or_b64 exec, exec, s[36:37]
	v_subrev_u32_e32 v230, 0x998, v130
	v_cmp_gt_u32_e64 s[30:31], 64, v230
	s_and_saveexec_b64 s[36:37], s[30:31]
	v_readlane_b32 s80, v255, 24
	v_readlane_b32 s81, v255, 25
	v_lshrrev_b32_e32 v231, 5, v98
	v_lshlrev_b32_e32 v231, 11, v231
	v_and_b32_e32 v232, 31, v98
	v_lshl_or_b32 v231, v232, 4, v231
	v_lshrrev_b32_e32 v232, 4, v230
	v_lshl_or_b32 v231, v232, 9, v231
	v_and_b32_e32 v232, 15, v230
	v_or_b32_e32 v231, v231, v232
	v_add_u32_e32 v234, 0x9000000, v231
	v_mov_b32_e32 v235, 0
	v_lshl_add_u64 v[236:237], v[234:235], 1, s[80:81]
	flat_store_dwordx4 v[236:237], v[100:103]
	s_or_b64 exec, exec, s[36:37]
.LBB0_363:
	s_or_b64 exec, exec, s[6:7]
	s_and_b64 exec, exec, s[18:19]
	s_cbranch_execz .LBB0_379
	v_and_b32_e32 v99, 0x1fcf, v98
	v_cmp_lt_i32_e32 vcc, s69, v152
	s_and_saveexec_b64 s[6:7], vcc
	s_xor_b64 s[6:7], exec, s[6:7]
	s_cbranch_execz .LBB0_366
	v_lshrrev_b32_e32 v100, 14, v150
	v_and_b32_e32 v102, 0x1c0, v100
	v_lshlrev_b32_e32 v102, 14, v102
	v_bfe_u32 v101, v100, 5, 1
	v_lshl_or_b32 v102, v101, 10, v102
	v_and_b32_e32 v101, 31, v100
	v_lshl_or_b32 v102, v101, 5, v102
	v_lshrrev_b32_e32 v101, 4, v99
	v_lshl_or_b32 v102, v101, 11, v102
	v_and_b32_e32 v101, 15, v99
	v_lshl_or_b32 v102, v101, 1, v102
	v_mov_b32_e32 v103, v1
	v_lshl_add_u64 v[100:101], s[12:13], 0, v[102:103]
	v_cvt_pk_bf16_f32 v94, v94, s0
	flat_store_short v[100:101], v94
	v_add_co_u32_e32 v94, vcc, 0x20, v100
	v_cvt_pk_bf16_f32 v102, v95, s0
	s_nop 0
	v_addc_co_u32_e32 v95, vcc, 0, v101, vcc
	flat_store_short v[94:95], v102
	v_add_co_u32_e32 v94, vcc, 0x40, v100
	v_cvt_pk_bf16_f32 v96, v96, s0
	s_nop 0
	v_addc_co_u32_e32 v95, vcc, 0, v101, vcc
	flat_store_short v[94:95], v96
	v_add_co_u32_e32 v94, vcc, 0x60, v100
	v_cvt_pk_bf16_f32 v96, v97, s0
	s_nop 0
	v_addc_co_u32_e32 v95, vcc, 0, v101, vcc
	flat_store_short v[94:95], v96

; DI bf16_t f2bf(float a) { return (bf16_t)(pk2(a, 0.f) & 0xffffu); }
; DI u32x2 pk4(float a, float b, float c, float d) { u32x2 r; r.x = pk2(a, b); r.y = pk2(c, d); return r; }
;   DI void store(int m, int n, float a, float b, float c, float d) const {
;     ...
;     if (n >= C_VS && n < C_KW) { int e = n - C_VS; bf16_t* p = vsT + ((size_t)(bb * 128 + e)) * SEQ + s; p[0] = f2bf(a); p[SEQ] = f2bf(b); p[2 * SEQ] = f2bf(c); p[3 * SEQ] = f2bf(d); }
;     else if (n >= C_VW && n < C_GATE) { int e = n - C_VW; bf16_t* p = vwT + ((size_t)(bb * 128 + e)) * SEQ + s; p[0] = f2bf(a); p[SEQ] = f2bf(b); p[2 * SEQ] = f2bf(c); p[3 * SEQ] = f2bf(d); }
;     else *(u32x2*)(proj + (size_t)m * EIN + n) = pk4(a, b, c, d); }
.LBB0_372:
	s_or_b64 exec, exec, s[6:7]
	v_cmp_lt_i32_e32 vcc, s69, v152
	s_and_saveexec_b64 s[6:7], vcc
	s_xor_b64 s[6:7], exec, s[6:7]
	s_cbranch_execz .LBB0_374
	v_lshrrev_b32_e32 v94, 14, v146
	v_and_b32_e32 v96, 0x1c0, v94
	v_lshlrev_b32_e32 v96, 14, v96
	v_bfe_u32 v95, v94, 5, 1
	v_lshl_or_b32 v96, v95, 10, v96
	v_and_b32_e32 v95, 31, v94
	v_lshl_or_b32 v96, v95, 5, v96
	v_lshrrev_b32_e32 v95, 4, v99
	v_lshl_or_b32 v96, v95, 11, v96
	v_and_b32_e32 v95, 15, v99
	v_lshl_or_b32 v96, v95, 1, v96
	v_mov_b32_e32 v97, v1
	v_lshl_add_u64 v[94:95], s[12:13], 0, v[96:97]
	v_cvt_pk_bf16_f32 v90, v90, s0
	flat_store_short v[94:95], v90
	v_add_co_u32_e32 v90, vcc, 0x20, v94
	v_cvt_pk_bf16_f32 v96, v91, s0
	s_nop 0
	v_addc_co_u32_e32 v91, vcc, 0, v95, vcc
	flat_store_short v[90:91], v96
	v_add_co_u32_e32 v90, vcc, 0x40, v94
	v_cvt_pk_bf16_f32 v92, v92, s0
	s_nop 0
	v_addc_co_u32_e32 v91, vcc, 0, v95, vcc
	flat_store_short v[90:91], v92
	v_add_co_u32_e32 v90, vcc, 0x60, v94
	v_cvt_pk_bf16_f32 v92, v93, s0
	s_nop 0
	v_addc_co_u32_e32 v91, vcc, 0, v95, vcc
	flat_store_short v[90:91], v92

; DI bf16_t f2bf(float a) { return (bf16_t)(pk2(a, 0.f) & 0xffffu); }
; DI u32x2 pk4(float a, float b, float c, float d) { u32x2 r; r.x = pk2(a, b); r.y = pk2(c, d); return r; }
; template <class AF, class EF>
; DI void gemm_run(unsigned char* lds, int wv, const AF& af, const bf16_t* __restrict__ Bt, int ldb, int M, int N, int K, const EF& ef, int blk_off) {
;     ...
;         for (int k = 0; k < 4; ++k) {
;           auto r = __builtin_amdgcn_permlane16_swap(__float_as_uint(acc[2 * ip][j][k]), __float_as_uint(acc[2 * ip + 1][j][k]), false, false);
;           lo[k] = __uint_as_float(r[0]); hi[k] = __uint_as_float(r[1]);
;         }
;         int n = n0 + wn * 64 + (2 * ip + (q4 & 1)) * 16 + (q4 >> 1) * 8;
;         int m = m0 + wm * 128 + j * 16 + l15;
;         if (n < N) ef.store8(m, n, lo[0], lo[1], lo[2], lo[3], hi[0], hi[1], hi[2], hi[3]);
;   DI void store(int m, int n, float a, float b, float c, float d) const {
;     int bb = m >> 13, s = m & (SEQ - 1);
;     if (n >= C_VS && n < C_KW) { int e = n - C_VS; bf16_t* p = vsT + ((size_t)(bb * 128 + e)) * SEQ + s; p[0] = f2bf(a); p[SEQ] = f2bf(b); p[2 * SEQ] = f2bf(c); p[3 * SEQ] = f2bf(d); }
;     else if (n >= C_VW && n < C_GATE) { int e = n - C_VW; bf16_t* p = vwT + ((size_t)(bb * 128 + e)) * SEQ + s; p[0] = f2bf(a); p[SEQ] = f2bf(b); p[2 * SEQ] = f2bf(c); p[3 * SEQ] = f2bf(d); }
;     else *(u32x2*)(proj + (size_t)m * EIN + n) = pk4(a, b, c, d); }
.LBB0_379:
	s_or_b64 exec, exec, s[16:17]
	v_permlane16_swap_b32_e32 v86, v82
	v_permlane16_swap_b32_e32 v87, v83
	v_permlane16_swap_b32_e32 v88, v84
	v_permlane16_swap_b32_e32 v89, v85
	s_and_saveexec_b64 s[16:17], s[4:5]
	s_cbranch_execz .LBB0_402
	v_cmp_lt_i32_e32 vcc, s69, v152
	s_mov_b64 s[20:21], 0
	s_mov_b64 s[18:19], 0
	s_and_saveexec_b64 s[6:7], vcc
	s_xor_b64 s[6:7], exec, s[6:7]
	v_cmp_ne_u32_e32 vcc, s70, v152
	s_and_b64 s[20:21], vcc, exec
	s_mov_b64 s[18:19], exec
	s_andn2_saveexec_b64 s[22:23], s[6:7]
	v_cmp_eq_u32_e32 vcc, s71, v152
	v_cmp_ne_u32_e64 s[6:7], s71, v152
	s_andn2_b64 s[18:19], s[18:19], exec
	s_and_b64 s[26:27], vcc, exec
	s_andn2_b64 s[20:21], s[20:21], exec
	s_and_b64 s[6:7], s[6:7], exec
	s_or_b64 s[18:19], s[18:19], s[26:27]
	s_or_b64 s[20:21], s[20:21], s[6:7]
	s_or_b64 exec, exec, s[22:23]
	v_or_b32_e32 v90, 0x50, v153
	s_and_saveexec_b64 s[6:7], s[20:21]
	s_xor_b64 s[6:7], exec, s[6:7]
	s_cbranch_execz .LBB0_386
	v_readlane_b32 s20, v255, 24
	v_readlane_b32 s21, v255, 25
	v_cvt_pk_bf16_f32 v92, v86, v87
	v_cvt_pk_bf16_f32 v93, v88, v89
	v_mov_b64_e32 v[96:97], s[20:21]
	v_mad_i64_i32 v[96:97], s[20:21], v90, s87, v[96:97]
	v_cvt_pk_bf16_f32 v94, v82, v83
	v_cvt_pk_bf16_f32 v95, v84, v85
	v_lshl_add_u64 v[96:97], v[130:131], 1, v[96:97]
	s_andn2_b64 s[18:19], s[18:19], exec
	flat_store_dwordx4 v[96:97], v[92:95]
	v_subrev_u32_e32 v230, 0x300, v130
	v_lshrrev_b32_e32 v232, 7, v230
	v_cmp_eq_u32_e64 s[30:31], 0, v232
	s_and_saveexec_b64 s[36:37], s[30:31]
	v_readlane_b32 s80, v255, 24
	v_readlane_b32 s81, v255, 25
	v_lshrrev_b32_e32 v231, 13, v90
	v_lshlrev_b32_e32 v231, 20, v231
	v_lshrrev_b32_e32 v232, 6, v230
	v_lshl_or_b32 v231, v232, 19, v231
	v_bfe_u32 v232, v90, 6, 7
	v_lshl_or_b32 v231, v232, 12, v231
	v_bfe_u32 v232, v90, 5, 1
	v_lshl_or_b32 v231, v232, 11, v231
	v_bfe_u32 v232, v90, 2, 1
	v_lshl_or_b32 v231, v232, 10, v231
	v_bfe_u32 v232, v230, 5, 1
	v_lshl_or_b32 v231, v232, 9, v231
	v_bfe_u32 v232, v90, 3, 2
	v_lshl_or_b32 v231, v232, 7, v231
	v_bfe_u32 v232, v90, 0, 2
	v_lshl_or_b32 v231, v232, 5, v231
	v_and_b32_e32 v232, 31, v230
	v_or_b32_e32 v231, v231, v232
	v_add_u32_e32 v234, 0x9c00000, v231
	v_mov_b32_e32 v235, 0
	v_lshl_add_u64 v[236:237], v[234:235], 1, s[80:81]
	flat_store_dwordx4 v[236:237], v[92:95]
	s_or_b64 exec, exec, s[36:37]
	v_subrev_u32_e32 v230, 0x998, v130
	v_cmp_gt_u32_e64 s[30:31], 64, v230
	s_and_saveexec_b64 s[36:37], s[30:31]
	v_readlane_b32 s80, v255, 24
	v_readlane_b32 s81, v255, 25
	v_lshrrev_b32_e32 v231, 5, v90
	v_lshlrev_b32_e32 v231, 11, v231
	v_and_b32_e32 v232, 31, v90
	v_lshl_or_b32 v231, v232, 4, v231
	v_lshrrev_b32_e32 v232, 4, v230
	v_lshl_or_b32 v231, v232, 9, v231
	v_and_b32_e32 v232, 15, v230
	v_or_b32_e32 v231, v231, v232
	v_add_u32_e32 v234, 0x9000000, v231
	v_mov_b32_e32 v235, 0
	v_lshl_add_u64 v[236:237], v[234:235], 1, s[80:81]
	flat_store_dwordx4 v[236:237], v[92:95]
	s_or_b64 exec, exec, s[36:37]
.LBB0_386:
	s_or_b64 exec, exec, s[6:7]
	s_and_b64 exec, exec, s[18:19]
	s_cbranch_execz .LBB0_402
	v_and_b32_e32 v91, 0x1fdf, v90
	v_cmp_lt_i32_e32 vcc, s69, v152
	s_and_saveexec_b64 s[6:7], vcc
	s_xor_b64 s[6:7], exec, s[6:7]
	s_cbranch_execz .LBB0_389
	v_lshrrev_b32_e32 v92, 14, v150
	v_and_b32_e32 v94, 0x1c0, v92
	v_lshlrev_b32_e32 v94, 14, v94
	v_bfe_u32 v93, v92, 5, 1
	v_lshl_or_b32 v94, v93, 10, v94
	v_and_b32_e32 v93, 31, v92
	v_lshl_or_b32 v94, v93, 5, v94
	v_lshrrev_b32_e32 v93, 4, v91
	v_lshl_or_b32 v94, v93, 11, v94
	v_and_b32_e32 v93, 15, v91
	v_lshl_or_b32 v94, v93, 1, v94
	v_mov_b32_e32 v95, v1
	v_lshl_add_u64 v[92:93], s[12:13], 0, v[94:95]
	v_cvt_pk_bf16_f32 v86, v86, s0
	flat_store_short v[92:93], v86
	v_add_co_u32_e32 v86, vcc, 0x20, v92
	v_cvt_pk_bf16_f32 v94, v87, s0
	s_nop 0
	v_addc_co_u32_e32 v87, vcc, 0, v93, vcc
	flat_store_short v[86:87], v94
	v_add_co_u32_e32 v86, vcc, 0x40, v92
	v_cvt_pk_bf16_f32 v88, v88, s0
	s_nop 0
	v_addc_co_u32_e32 v87, vcc, 0, v93, vcc
	flat_store_short v[86:87], v88
	v_add_co_u32_e32 v86, vcc, 0x60, v92
	v_cvt_pk_bf16_f32 v88, v89, s0
	s_nop 0
	v_addc_co_u32_e32 v87, vcc, 0, v93, vcc
	flat_store_short v[86:87], v88

; DI bf16_t f2bf(float a) { return (bf16_t)(pk2(a, 0.f) & 0xffffu); }
; DI u32x2 pk4(float a, float b, float c, float d) { u32x2 r; r.x = pk2(a, b); r.y = pk2(c, d); return r; }
;   DI void store(int m, int n, float a, float b, float c, float d) const {
;     ...
;     if (n >= C_VS && n < C_KW) { int e = n - C_VS; bf16_t* p = vsT + ((size_t)(bb * 128 + e)) * SEQ + s; p[0] = f2bf(a); p[SEQ] = f2bf(b); p[2 * SEQ] = f2bf(c); p[3 * SEQ] = f2bf(d); }
;     else if (n >= C_VW && n < C_GATE) { int e = n - C_VW; bf16_t* p = vwT + ((size_t)(bb * 128 + e)) * SEQ + s; p[0] = f2bf(a); p[SEQ] = f2bf(b); p[2 * SEQ] = f2bf(c); p[3 * SEQ] = f2bf(d); }
;     else *(u32x2*)(proj + (size_t)m * EIN + n) = pk4(a, b, c, d); }
.LBB0_395:
	s_or_b64 exec, exec, s[6:7]
	v_cmp_lt_i32_e32 vcc, s69, v152
	s_and_saveexec_b64 s[6:7], vcc
	s_xor_b64 s[6:7], exec, s[6:7]
	s_cbranch_execz .LBB0_397
	v_lshrrev_b32_e32 v86, 14, v146
	v_and_b32_e32 v88, 0x1c0, v86
	v_lshlrev_b32_e32 v88, 14, v88
	v_bfe_u32 v87, v86, 5, 1
	v_lshl_or_b32 v88, v87, 10, v88
	v_and_b32_e32 v87, 31, v86
	v_lshl_or_b32 v88, v87, 5, v88
	v_lshrrev_b32_e32 v87, 4, v91
	v_lshl_or_b32 v88, v87, 11, v88
	v_and_b32_e32 v87, 15, v91
	v_lshl_or_b32 v88, v87, 1, v88
	v_mov_b32_e32 v89, v1
	v_lshl_add_u64 v[86:87], s[12:13], 0, v[88:89]
	v_cvt_pk_bf16_f32 v82, v82, s0
	flat_store_short v[86:87], v82
	v_add_co_u32_e32 v82, vcc, 0x20, v86
	v_cvt_pk_bf16_f32 v88, v83, s0
	s_nop 0
	v_addc_co_u32_e32 v83, vcc, 0, v87, vcc
	flat_store_short v[82:83], v88
	v_add_co_u32_e32 v82, vcc, 0x40, v86
	v_cvt_pk_bf16_f32 v84, v84, s0
	s_nop 0
	v_addc_co_u32_e32 v83, vcc, 0, v87, vcc
	flat_store_short v[82:83], v84
	v_add_co_u32_e32 v82, vcc, 0x60, v86
	v_cvt_pk_bf16_f32 v84, v85, s0
	s_nop 0
	v_addc_co_u32_e32 v83, vcc, 0, v87, vcc
	flat_store_short v[82:83], v84

; DI bf16_t f2bf(float a) { return (bf16_t)(pk2(a, 0.f) & 0xffffu); }
; DI u32x2 pk4(float a, float b, float c, float d) { u32x2 r; r.x = pk2(a, b); r.y = pk2(c, d); return r; }
; template <class AF, class EF>
; DI void gemm_run(unsigned char* lds, int wv, const AF& af, const bf16_t* __restrict__ Bt, int ldb, int M, int N, int K, const EF& ef, int blk_off) {
;     ...
;         for (int k = 0; k < 4; ++k) {
;           auto r = __builtin_amdgcn_permlane16_swap(__float_as_uint(acc[2 * ip][j][k]), __float_as_uint(acc[2 * ip + 1][j][k]), false, false);
;           lo[k] = __uint_as_float(r[0]); hi[k] = __uint_as_float(r[1]);
;         }
;         int n = n0 + wn * 64 + (2 * ip + (q4 & 1)) * 16 + (q4 >> 1) * 8;
;         int m = m0 + wm * 128 + j * 16 + l15;
;         if (n < N) ef.store8(m, n, lo[0], lo[1], lo[2], lo[3], hi[0], hi[1], hi[2], hi[3]);
;   DI void store(int m, int n, float a, float b, float c, float d) const {
;     int bb = m >> 13, s = m & (SEQ - 1);
;     if (n >= C_VS && n < C_KW) { int e = n - C_VS; bf16_t* p = vsT + ((size_t)(bb * 128 + e)) * SEQ + s; p[0] = f2bf(a); p[SEQ] = f2bf(b); p[2 * SEQ] = f2bf(c); p[3 * SEQ] = f2bf(d); }
;     else if (n >= C_VW && n < C_GATE) { int e = n - C_VW; bf16_t* p = vwT + ((size_t)(bb * 128 + e)) * SEQ + s; p[0] = f2bf(a); p[SEQ] = f2bf(b); p[2 * SEQ] = f2bf(c); p[3 * SEQ] = f2bf(d); }
;     else *(u32x2*)(proj + (size_t)m * EIN + n) = pk4(a, b, c, d); }
.LBB0_402:
	s_or_b64 exec, exec, s[16:17]
	v_permlane16_swap_b32_e32 v78, v74
	v_permlane16_swap_b32_e32 v79, v75
	v_permlane16_swap_b32_e32 v80, v76
	v_permlane16_swap_b32_e32 v81, v77
	s_and_saveexec_b64 s[16:17], s[4:5]
	s_cbranch_execz .LBB0_425
	v_cmp_lt_i32_e32 vcc, s69, v152
	s_mov_b64 s[20:21], 0
	s_mov_b64 s[18:19], 0
	s_and_saveexec_b64 s[6:7], vcc
	s_xor_b64 s[6:7], exec, s[6:7]
	v_cmp_ne_u32_e32 vcc, s70, v152
	s_and_b64 s[20:21], vcc, exec
	s_mov_b64 s[18:19], exec
	s_andn2_saveexec_b64 s[22:23], s[6:7]
	v_cmp_eq_u32_e32 vcc, s71, v152
	v_cmp_ne_u32_e64 s[6:7], s71, v152
	s_andn2_b64 s[18:19], s[18:19], exec
	s_and_b64 s[26:27], vcc, exec
	s_andn2_b64 s[20:21], s[20:21], exec
	s_and_b64 s[6:7], s[6:7], exec
	s_or_b64 s[18:19], s[18:19], s[26:27]
	s_or_b64 s[20:21], s[20:21], s[6:7]
	s_or_b64 exec, exec, s[22:23]
	v_or_b32_e32 v82, 0x60, v153
	s_and_saveexec_b64 s[6:7], s[20:21]
	s_xor_b64 s[6:7], exec, s[6:7]
	s_cbranch_execz .LBB0_409
	v_readlane_b32 s20, v255, 24
	v_readlane_b32 s21, v255, 25
	v_cvt_pk_bf16_f32 v84, v78, v79
	v_cvt_pk_bf16_f32 v85, v80, v81
	v_mov_b64_e32 v[88:89], s[20:21]
	v_mad_i64_i32 v[88:89], s[20:21], v82, s87, v[88:89]
	v_cvt_pk_bf16_f32 v86, v74, v75
	v_cvt_pk_bf16_f32 v87, v76, v77
	v_lshl_add_u64 v[88:89], v[130:131], 1, v[88:89]
	s_andn2_b64 s[18:19], s[18:19], exec
	flat_store_dwordx4 v[88:89], v[84:87]
	v_subrev_u32_e32 v230, 0x300, v130
	v_lshrrev_b32_e32 v232, 7, v230
	v_cmp_eq_u32_e64 s[30:31], 0, v232
	s_and_saveexec_b64 s[36:37], s[30:31]
	v_readlane_b32 s80, v255, 24
	v_readlane_b32 s81, v255, 25
	v_lshrrev_b32_e32 v231, 13, v82
	v_lshlrev_b32_e32 v231, 20, v231
	v_lshrrev_b32_e32 v232, 6, v230
	v_lshl_or_b32 v231, v232, 19, v231
	v_bfe_u32 v232, v82, 6, 7
	v_lshl_or_b32 v231, v232, 12, v231
	v_bfe_u32 v232, v82, 5, 1
	v_lshl_or_b32 v231, v232, 11, v231
	v_bfe_u32 v232, v82, 2, 1
	v_lshl_or_b32 v231, v232, 10, v231
	v_bfe_u32 v232, v230, 5, 1
	v_lshl_or_b32 v231, v232, 9, v231
	v_bfe_u32 v232, v82, 3, 2
	v_lshl_or_b32 v231, v232, 7, v231
	v_bfe_u32 v232, v82, 0, 2
	v_lshl_or_b32 v231, v232, 5, v231
	v_and_b32_e32 v232, 31, v230
	v_or_b32_e32 v231, v231, v232
	v_add_u32_e32 v234, 0x9c00000, v231
	v_mov_b32_e32 v235, 0
	v_lshl_add_u64 v[236:237], v[234:235], 1, s[80:81]
	flat_store_dwordx4 v[236:237], v[84:87]
	s_or_b64 exec, exec, s[36:37]
	v_subrev_u32_e32 v230, 0x998, v130
	v_cmp_gt_u32_e64 s[30:31], 64, v230
	s_and_saveexec_b64 s[36:37], s[30:31]
	v_readlane_b32 s80, v255, 24
	v_readlane_b32 s81, v255, 25
	v_lshrrev_b32_e32 v231, 5, v82
	v_lshlrev_b32_e32 v231, 11, v231
	v_and_b32_e32 v232, 31, v82
	v_lshl_or_b32 v231, v232, 4, v231
	v_lshrrev_b32_e32 v232, 4, v230
	v_lshl_or_b32 v231, v232, 9, v231
	v_and_b32_e32 v232, 15, v230
	v_or_b32_e32 v231, v231, v232
	v_add_u32_e32 v234, 0x9000000, v231
	v_mov_b32_e32 v235, 0
	v_lshl_add_u64 v[236:237], v[234:235], 1, s[80:81]
	flat_store_dwordx4 v[236:237], v[84:87]
	s_or_b64 exec, exec, s[36:37]
.LBB0_409:
	s_or_b64 exec, exec, s[6:7]
	s_and_b64 exec, exec, s[18:19]
	s_cbranch_execz .LBB0_425
	v_and_b32_e32 v83, 0x1fef, v82
	v_cmp_lt_i32_e32 vcc, s69, v152
	s_and_saveexec_b64 s[6:7], vcc
	s_xor_b64 s[6:7], exec, s[6:7]
	s_cbranch_execz .LBB0_412
	v_lshrrev_b32_e32 v84, 14, v150
	v_and_b32_e32 v86, 0x1c0, v84
	v_lshlrev_b32_e32 v86, 14, v86
	v_bfe_u32 v85, v84, 5, 1
	v_lshl_or_b32 v86, v85, 10, v86
	v_and_b32_e32 v85, 31, v84
	v_lshl_or_b32 v86, v85, 5, v86
	v_lshrrev_b32_e32 v85, 4, v83
	v_lshl_or_b32 v86, v85, 11, v86
	v_and_b32_e32 v85, 15, v83
	v_lshl_or_b32 v86, v85, 1, v86
	v_mov_b32_e32 v87, v1
	v_lshl_add_u64 v[84:85], s[12:13], 0, v[86:87]
	v_cvt_pk_bf16_f32 v78, v78, s0
	flat_store_short v[84:85], v78
	v_add_co_u32_e32 v78, vcc, 0x20, v84
	v_cvt_pk_bf16_f32 v86, v79, s0
	s_nop 0
	v_addc_co_u32_e32 v79, vcc, 0, v85, vcc
	flat_store_short v[78:79], v86
	v_add_co_u32_e32 v78, vcc, 0x40, v84
	v_cvt_pk_bf16_f32 v80, v80, s0
	s_nop 0
	v_addc_co_u32_e32 v79, vcc, 0, v85, vcc
	flat_store_short v[78:79], v80
	v_add_co_u32_e32 v78, vcc, 0x60, v84
	v_cvt_pk_bf16_f32 v80, v81, s0
	s_nop 0
	v_addc_co_u32_e32 v79, vcc, 0, v85, vcc
	flat_store_short v[78:79], v80

; DI bf16_t f2bf(float a) { return (bf16_t)(pk2(a, 0.f) & 0xffffu); }
; DI u32x2 pk4(float a, float b, float c, float d) { u32x2 r; r.x = pk2(a, b); r.y = pk2(c, d); return r; }
;   DI void store(int m, int n, float a, float b, float c, float d) const {
;     ...
;     if (n >= C_VS && n < C_KW) { int e = n - C_VS; bf16_t* p = vsT + ((size_t)(bb * 128 + e)) * SEQ + s; p[0] = f2bf(a); p[SEQ] = f2bf(b); p[2 * SEQ] = f2bf(c); p[3 * SEQ] = f2bf(d); }
;     else if (n >= C_VW && n < C_GATE) { int e = n - C_VW; bf16_t* p = vwT + ((size_t)(bb * 128 + e)) * SEQ + s; p[0] = f2bf(a); p[SEQ] = f2bf(b); p[2 * SEQ] = f2bf(c); p[3 * SEQ] = f2bf(d); }
;     else *(u32x2*)(proj + (size_t)m * EIN + n) = pk4(a, b, c, d); }
.LBB0_418:
	s_or_b64 exec, exec, s[6:7]
	v_cmp_lt_i32_e32 vcc, s69, v152
	s_and_saveexec_b64 s[6:7], vcc
	s_xor_b64 s[6:7], exec, s[6:7]
	s_cbranch_execz .LBB0_420
	v_lshrrev_b32_e32 v78, 14, v146
	v_and_b32_e32 v80, 0x1c0, v78
	v_lshlrev_b32_e32 v80, 14, v80
	v_bfe_u32 v79, v78, 5, 1
	v_lshl_or_b32 v80, v79, 10, v80
	v_and_b32_e32 v79, 31, v78
	v_lshl_or_b32 v80, v79, 5, v80
	v_lshrrev_b32_e32 v79, 4, v83
	v_lshl_or_b32 v80, v79, 11, v80
	v_and_b32_e32 v79, 15, v83
	v_lshl_or_b32 v80, v79, 1, v80
	v_mov_b32_e32 v81, v1
	v_lshl_add_u64 v[78:79], s[12:13], 0, v[80:81]
	v_cvt_pk_bf16_f32 v74, v74, s0
	flat_store_short v[78:79], v74
	v_add_co_u32_e32 v74, vcc, 0x20, v78
	v_cvt_pk_bf16_f32 v80, v75, s0
	s_nop 0
	v_addc_co_u32_e32 v75, vcc, 0, v79, vcc
	flat_store_short v[74:75], v80
	v_add_co_u32_e32 v74, vcc, 0x40, v78
	v_cvt_pk_bf16_f32 v76, v76, s0
	s_nop 0
	v_addc_co_u32_e32 v75, vcc, 0, v79, vcc
	flat_store_short v[74:75], v76
	v_add_co_u32_e32 v74, vcc, 0x60, v78
	v_cvt_pk_bf16_f32 v76, v77, s0
	s_nop 0
	v_addc_co_u32_e32 v75, vcc, 0, v79, vcc
	flat_store_short v[74:75], v76

; DI bf16_t f2bf(float a) { return (bf16_t)(pk2(a, 0.f) & 0xffffu); }
; DI u32x2 pk4(float a, float b, float c, float d) { u32x2 r; r.x = pk2(a, b); r.y = pk2(c, d); return r; }
; template <class AF, class EF>
; DI void gemm_run(unsigned char* lds, int wv, const AF& af, const bf16_t* __restrict__ Bt, int ldb, int M, int N, int K, const EF& ef, int blk_off) {
;     ...
;         for (int k = 0; k < 4; ++k) {
;           auto r = __builtin_amdgcn_permlane16_swap(__float_as_uint(acc[2 * ip][j][k]), __float_as_uint(acc[2 * ip + 1][j][k]), false, false);
;           lo[k] = __uint_as_float(r[0]); hi[k] = __uint_as_float(r[1]);
;         }
;         int n = n0 + wn * 64 + (2 * ip + (q4 & 1)) * 16 + (q4 >> 1) * 8;
;         int m = m0 + wm * 128 + j * 16 + l15;
;         if (n < N) ef.store8(m, n, lo[0], lo[1], lo[2], lo[3], hi[0], hi[1], hi[2], hi[3]);
;   DI void store(int m, int n, float a, float b, float c, float d) const {
;     int bb = m >> 13, s = m & (SEQ - 1);
;     if (n >= C_VS && n < C_KW) { int e = n - C_VS; bf16_t* p = vsT + ((size_t)(bb * 128 + e)) * SEQ + s; p[0] = f2bf(a); p[SEQ] = f2bf(b); p[2 * SEQ] = f2bf(c); p[3 * SEQ] = f2bf(d); }
;     else if (n >= C_VW && n < C_GATE) { int e = n - C_VW; bf16_t* p = vwT + ((size_t)(bb * 128 + e)) * SEQ + s; p[0] = f2bf(a); p[SEQ] = f2bf(b); p[2 * SEQ] = f2bf(c); p[3 * SEQ] = f2bf(d); }
;     else *(u32x2*)(proj + (size_t)m * EIN + n) = pk4(a, b, c, d); }
.LBB0_425:
	s_or_b64 exec, exec, s[16:17]
	v_permlane16_swap_b32_e32 v70, v66
	v_permlane16_swap_b32_e32 v71, v67
	v_permlane16_swap_b32_e32 v72, v68
	v_permlane16_swap_b32_e32 v73, v69
	s_and_saveexec_b64 s[6:7], s[4:5]
	s_cbranch_execz .LBB0_448
	v_cmp_lt_i32_e32 vcc, s69, v152
	s_mov_b64 s[18:19], 0
	s_mov_b64 s[16:17], 0
	s_and_saveexec_b64 s[4:5], vcc
	s_xor_b64 s[4:5], exec, s[4:5]
	v_cmp_ne_u32_e32 vcc, s70, v152
	s_and_b64 s[18:19], vcc, exec
	s_mov_b64 s[16:17], exec
	s_andn2_saveexec_b64 s[20:21], s[4:5]
	v_cmp_eq_u32_e32 vcc, s71, v152
	v_cmp_ne_u32_e64 s[4:5], s71, v152
	s_andn2_b64 s[16:17], s[16:17], exec
	s_and_b64 s[22:23], vcc, exec
	s_andn2_b64 s[18:19], s[18:19], exec
	s_and_b64 s[4:5], s[4:5], exec
	s_or_b64 s[16:17], s[16:17], s[22:23]
	s_or_b64 s[18:19], s[18:19], s[4:5]
	s_or_b64 exec, exec, s[20:21]
	v_or_b32_e32 v74, 0x70, v153
	s_and_saveexec_b64 s[4:5], s[18:19]
	s_xor_b64 s[4:5], exec, s[4:5]
	s_cbranch_execz .LBB0_432
	v_readlane_b32 s18, v255, 24
	v_readlane_b32 s19, v255, 25
	v_cvt_pk_bf16_f32 v76, v70, v71
	v_cvt_pk_bf16_f32 v77, v72, v73
	v_mov_b64_e32 v[80:81], s[18:19]
	v_mad_i64_i32 v[80:81], s[18:19], v74, s87, v[80:81]
	v_cvt_pk_bf16_f32 v78, v66, v67
	v_cvt_pk_bf16_f32 v79, v68, v69
	v_lshl_add_u64 v[80:81], v[130:131], 1, v[80:81]
	s_andn2_b64 s[16:17], s[16:17], exec
	flat_store_dwordx4 v[80:81], v[76:79]
	v_subrev_u32_e32 v230, 0x300, v130
	v_lshrrev_b32_e32 v232, 7, v230
	v_cmp_eq_u32_e64 s[30:31], 0, v232
	s_and_saveexec_b64 s[36:37], s[30:31]
	v_readlane_b32 s80, v255, 24
	v_readlane_b32 s81, v255, 25
	v_lshrrev_b32_e32 v231, 13, v74
	v_lshlrev_b32_e32 v231, 20, v231
	v_lshrrev_b32_e32 v232, 6, v230
	v_lshl_or_b32 v231, v232, 19, v231
	v_bfe_u32 v232, v74, 6, 7
	v_lshl_or_b32 v231, v232, 12, v231
	v_bfe_u32 v232, v74, 5, 1
	v_lshl_or_b32 v231, v232, 11, v231
	v_bfe_u32 v232, v74, 2, 1
	v_lshl_or_b32 v231, v232, 10, v231
	v_bfe_u32 v232, v230, 5, 1
	v_lshl_or_b32 v231, v232, 9, v231
	v_bfe_u32 v232, v74, 3, 2
	v_lshl_or_b32 v231, v232, 7, v231
	v_bfe_u32 v232, v74, 0, 2
	v_lshl_or_b32 v231, v232, 5, v231
	v_and_b32_e32 v232, 31, v230
	v_or_b32_e32 v231, v231, v232
	v_add_u32_e32 v234, 0x9c00000, v231
	v_mov_b32_e32 v235, 0
	v_lshl_add_u64 v[236:237], v[234:235], 1, s[80:81]
	flat_store_dwordx4 v[236:237], v[76:79]
	s_or_b64 exec, exec, s[36:37]
	v_subrev_u32_e32 v230, 0x998, v130
	v_cmp_gt_u32_e64 s[30:31], 64, v230
	s_and_saveexec_b64 s[36:37], s[30:31]
	v_readlane_b32 s80, v255, 24
	v_readlane_b32 s81, v255, 25
	v_lshrrev_b32_e32 v231, 5, v74
	v_lshlrev_b32_e32 v231, 11, v231
	v_and_b32_e32 v232, 31, v74
	v_lshl_or_b32 v231, v232, 4, v231
	v_lshrrev_b32_e32 v232, 4, v230
	v_lshl_or_b32 v231, v232, 9, v231
	v_and_b32_e32 v232, 15, v230
	v_or_b32_e32 v231, v231, v232
	v_add_u32_e32 v234, 0x9000000, v231
	v_mov_b32_e32 v235, 0
	v_lshl_add_u64 v[236:237], v[234:235], 1, s[80:81]
	flat_store_dwordx4 v[236:237], v[76:79]
	s_or_b64 exec, exec, s[36:37]
.LBB0_432:
	s_or_b64 exec, exec, s[4:5]
	s_and_b64 exec, exec, s[16:17]
	s_cbranch_execz .LBB0_448
	v_and_b32_e32 v75, 0x1fff, v74
	v_cmp_lt_i32_e32 vcc, s69, v152
	s_and_saveexec_b64 s[4:5], vcc
	s_xor_b64 s[4:5], exec, s[4:5]
	s_cbranch_execz .LBB0_435
	v_lshrrev_b32_e32 v76, 14, v150
	v_and_b32_e32 v78, 0x1c0, v76
	v_lshlrev_b32_e32 v78, 14, v78
	v_bfe_u32 v77, v76, 5, 1
	v_lshl_or_b32 v78, v77, 10, v78
	v_and_b32_e32 v77, 31, v76
	v_lshl_or_b32 v78, v77, 5, v78
	v_lshrrev_b32_e32 v77, 4, v75
	v_lshl_or_b32 v78, v77, 11, v78
	v_and_b32_e32 v77, 15, v75
	v_lshl_or_b32 v78, v77, 1, v78
	v_mov_b32_e32 v79, v1
	v_lshl_add_u64 v[76:77], s[12:13], 0, v[78:79]
	v_cvt_pk_bf16_f32 v70, v70, s0
	flat_store_short v[76:77], v70
	v_add_co_u32_e32 v70, vcc, 0x20, v76
	v_cvt_pk_bf16_f32 v78, v71, s0
	s_nop 0
	v_addc_co_u32_e32 v71, vcc, 0, v77, vcc
	flat_store_short v[70:71], v78
	v_add_co_u32_e32 v70, vcc, 0x40, v76
	v_cvt_pk_bf16_f32 v72, v72, s0
	s_nop 0
	v_addc_co_u32_e32 v71, vcc, 0, v77, vcc
	flat_store_short v[70:71], v72
	v_add_co_u32_e32 v70, vcc, 0x60, v76
	v_cvt_pk_bf16_f32 v72, v73, s0
	s_nop 0
	v_addc_co_u32_e32 v71, vcc, 0, v77, vcc
	flat_store_short v[70:71], v72

; DI bf16_t f2bf(float a) { return (bf16_t)(pk2(a, 0.f) & 0xffffu); }
; DI u32x2 pk4(float a, float b, float c, float d) { u32x2 r; r.x = pk2(a, b); r.y = pk2(c, d); return r; }
;   DI void store(int m, int n, float a, float b, float c, float d) const {
;     ...
;     if (n >= C_VS && n < C_KW) { int e = n - C_VS; bf16_t* p = vsT + ((size_t)(bb * 128 + e)) * SEQ + s; p[0] = f2bf(a); p[SEQ] = f2bf(b); p[2 * SEQ] = f2bf(c); p[3 * SEQ] = f2bf(d); }
;     else if (n >= C_VW && n < C_GATE) { int e = n - C_VW; bf16_t* p = vwT + ((size_t)(bb * 128 + e)) * SEQ + s; p[0] = f2bf(a); p[SEQ] = f2bf(b); p[2 * SEQ] = f2bf(c); p[3 * SEQ] = f2bf(d); }
;     else *(u32x2*)(proj + (size_t)m * EIN + n) = pk4(a, b, c, d); }
.LBB0_441:
	s_or_b64 exec, exec, s[4:5]
	v_cmp_lt_i32_e32 vcc, s69, v152
	s_and_saveexec_b64 s[4:5], vcc
	s_xor_b64 s[4:5], exec, s[4:5]
	s_cbranch_execz .LBB0_443
	v_lshrrev_b32_e32 v70, 14, v146
	v_and_b32_e32 v72, 0x1c0, v70
	v_lshlrev_b32_e32 v72, 14, v72
	v_bfe_u32 v71, v70, 5, 1
	v_lshl_or_b32 v72, v71, 10, v72
	v_and_b32_e32 v71, 31, v70
	v_lshl_or_b32 v72, v71, 5, v72
	v_lshrrev_b32_e32 v71, 4, v75
	v_lshl_or_b32 v72, v71, 11, v72
	v_and_b32_e32 v71, 15, v75
	v_lshl_or_b32 v72, v71, 1, v72
	v_mov_b32_e32 v73, v1
	v_lshl_add_u64 v[70:71], s[12:13], 0, v[72:73]
	v_cvt_pk_bf16_f32 v66, v66, s0
	flat_store_short v[70:71], v66
	v_add_co_u32_e32 v66, vcc, 0x20, v70
	v_cvt_pk_bf16_f32 v72, v67, s0
	s_nop 0
	v_addc_co_u32_e32 v67, vcc, 0, v71, vcc
	flat_store_short v[66:67], v72
	v_add_co_u32_e32 v66, vcc, 0x40, v70
	v_cvt_pk_bf16_f32 v68, v68, s0
	s_nop 0
	v_addc_co_u32_e32 v67, vcc, 0, v71, vcc
	flat_store_short v[66:67], v68
	v_add_co_u32_e32 v66, vcc, 0x60, v70
	v_cvt_pk_bf16_f32 v68, v69, s0
	s_nop 0
	v_addc_co_u32_e32 v67, vcc, 0, v71, vcc
	flat_store_short v[66:67], v68

; DI bf16_t f2bf(float a) { return (bf16_t)(pk2(a, 0.f) & 0xffffu); }
; DI u32x2 pk4(float a, float b, float c, float d) { u32x2 r; r.x = pk2(a, b); r.y = pk2(c, d); return r; }
; template <class AF, class EF>
; DI void gemm_run(unsigned char* lds, int wv, const AF& af, const bf16_t* __restrict__ Bt, int ldb, int M, int N, int K, const EF& ef, int blk_off) {
;     ...
;         for (int k = 0; k < 4; ++k) {
;           auto r = __builtin_amdgcn_permlane16_swap(__float_as_uint(acc[2 * ip][j][k]), __float_as_uint(acc[2 * ip + 1][j][k]), false, false);
;           lo[k] = __uint_as_float(r[0]); hi[k] = __uint_as_float(r[1]);
;         }
;         int n = n0 + wn * 64 + (2 * ip + (q4 & 1)) * 16 + (q4 >> 1) * 8;
;         int m = m0 + wm * 128 + j * 16 + l15;
;         if (n < N) ef.store8(m, n, lo[0], lo[1], lo[2], lo[3], hi[0], hi[1], hi[2], hi[3]);
;   DI void store(int m, int n, float a, float b, float c, float d) const {
;     int bb = m >> 13, s = m & (SEQ - 1);
;     if (n >= C_VS && n < C_KW) { int e = n - C_VS; bf16_t* p = vsT + ((size_t)(bb * 128 + e)) * SEQ + s; p[0] = f2bf(a); p[SEQ] = f2bf(b); p[2 * SEQ] = f2bf(c); p[3 * SEQ] = f2bf(d); }
;     else if (n >= C_VW && n < C_GATE) { int e = n - C_VW; bf16_t* p = vwT + ((size_t)(bb * 128 + e)) * SEQ + s; p[0] = f2bf(a); p[SEQ] = f2bf(b); p[2 * SEQ] = f2bf(c); p[3 * SEQ] = f2bf(d); }
;     else *(u32x2*)(proj + (size_t)m * EIN + n) = pk4(a, b, c, d); }
.LBB0_455:
	v_readlane_b32 s20, v255, 24
	v_readlane_b32 s21, v255, 25
	v_cvt_pk_bf16_f32 v74, v62, v63
	v_cvt_pk_bf16_f32 v75, v64, v65
	v_mov_b64_e32 v[78:79], s[20:21]
	v_mad_i64_i32 v[78:79], s[20:21], v153, s87, v[78:79]
	v_cvt_pk_bf16_f32 v76, v58, v59
	v_cvt_pk_bf16_f32 v77, v60, v61
	v_lshl_add_u64 v[78:79], v[130:131], 1, v[78:79]
	s_andn2_b64 s[18:19], s[18:19], exec
	flat_store_dwordx4 v[78:79], v[74:77] offset:64
	v_subrev_u32_e32 v230, 0x2e0, v130
	v_lshrrev_b32_e32 v232, 7, v230
	v_cmp_eq_u32_e64 s[30:31], 0, v232
	s_and_saveexec_b64 s[36:37], s[30:31]
	v_readlane_b32 s80, v255, 24
	v_readlane_b32 s81, v255, 25
	v_lshrrev_b32_e32 v231, 13, v153
	v_lshlrev_b32_e32 v231, 20, v231
	v_lshrrev_b32_e32 v232, 6, v230
	v_lshl_or_b32 v231, v232, 19, v231
	v_bfe_u32 v232, v153, 6, 7
	v_lshl_or_b32 v231, v232, 12, v231
	v_bfe_u32 v232, v153, 5, 1
	v_lshl_or_b32 v231, v232, 11, v231
	v_bfe_u32 v232, v153, 2, 1
	v_lshl_or_b32 v231, v232, 10, v231
	v_bfe_u32 v232, v230, 5, 1
	v_lshl_or_b32 v231, v232, 9, v231
	v_bfe_u32 v232, v153, 3, 2
	v_lshl_or_b32 v231, v232, 7, v231
	v_bfe_u32 v232, v153, 0, 2
	v_lshl_or_b32 v231, v232, 5, v231
	v_and_b32_e32 v232, 31, v230
	v_or_b32_e32 v231, v231, v232
	v_add_u32_e32 v234, 0x9c00000, v231
	v_mov_b32_e32 v235, 0
	v_lshl_add_u64 v[236:237], v[234:235], 1, s[80:81]
	flat_store_dwordx4 v[236:237], v[74:77]
	s_or_b64 exec, exec, s[36:37]
	v_subrev_u32_e32 v230, 0x978, v130
	v_cmp_gt_u32_e64 s[30:31], 64, v230
	s_and_saveexec_b64 s[36:37], s[30:31]
	v_readlane_b32 s80, v255, 24
	v_readlane_b32 s81, v255, 25
	v_lshrrev_b32_e32 v231, 5, v153
	v_lshlrev_b32_e32 v231, 11, v231
	v_and_b32_e32 v232, 31, v153
	v_lshl_or_b32 v231, v232, 4, v231
	v_lshrrev_b32_e32 v232, 4, v230
	v_lshl_or_b32 v231, v232, 9, v231
	v_and_b32_e32 v232, 15, v230
	v_or_b32_e32 v231, v231, v232
	v_add_u32_e32 v234, 0x9000000, v231
	v_mov_b32_e32 v235, 0
	v_lshl_add_u64 v[236:237], v[234:235], 1, s[80:81]
	flat_store_dwordx4 v[236:237], v[74:77]
	s_or_b64 exec, exec, s[36:37]
	s_or_b64 exec, exec, s[6:7]
	s_and_b64 exec, exec, s[18:19]
	s_cbranch_execz .LBB0_471
.LBB0_456:
	v_and_b32_e32 v74, 0x1f8f, v153
	v_cmp_lt_i32_e32 vcc, s69, v152
	s_and_saveexec_b64 s[6:7], vcc
	s_xor_b64 s[6:7], exec, s[6:7]
	s_cbranch_execz .LBB0_458
	v_lshrrev_b32_e32 v76, 14, v72
	v_and_b32_e32 v78, 0x1c0, v76
	v_lshlrev_b32_e32 v78, 14, v78
	v_bfe_u32 v77, v76, 5, 1
	v_lshl_or_b32 v78, v77, 10, v78
	v_and_b32_e32 v77, 31, v76
	v_lshl_or_b32 v78, v77, 5, v78
	v_lshrrev_b32_e32 v77, 4, v74
	v_lshl_or_b32 v78, v77, 11, v78
	v_and_b32_e32 v77, 15, v74
	v_lshl_or_b32 v78, v77, 1, v78
	v_mov_b32_e32 v79, v1
	v_lshl_add_u64 v[76:77], s[12:13], 0, v[78:79]
	v_cvt_pk_bf16_f32 v62, v62, s0
	flat_store_short v[76:77], v62
	v_add_co_u32_e32 v62, vcc, 0x20, v76
	v_cvt_pk_bf16_f32 v75, v63, s0
	s_nop 0
	v_addc_co_u32_e32 v63, vcc, 0, v77, vcc
	flat_store_short v[62:63], v75
	v_add_co_u32_e32 v62, vcc, 0x40, v76
	v_cvt_pk_bf16_f32 v64, v64, s0
	s_nop 0
	v_addc_co_u32_e32 v63, vcc, 0, v77, vcc
	flat_store_short v[62:63], v64
	v_add_co_u32_e32 v62, vcc, 0x60, v76
	v_cvt_pk_bf16_f32 v64, v65, s0
	s_nop 0
	v_addc_co_u32_e32 v63, vcc, 0, v77, vcc
	flat_store_short v[62:63], v64

; DI bf16_t f2bf(float a) { return (bf16_t)(pk2(a, 0.f) & 0xffffu); }
; DI u32x2 pk4(float a, float b, float c, float d) { u32x2 r; r.x = pk2(a, b); r.y = pk2(c, d); return r; }
;   DI void store(int m, int n, float a, float b, float c, float d) const {
;     ...
;     if (n >= C_VS && n < C_KW) { int e = n - C_VS; bf16_t* p = vsT + ((size_t)(bb * 128 + e)) * SEQ + s; p[0] = f2bf(a); p[SEQ] = f2bf(b); p[2 * SEQ] = f2bf(c); p[3 * SEQ] = f2bf(d); }
;     else if (n >= C_VW && n < C_GATE) { int e = n - C_VW; bf16_t* p = vwT + ((size_t)(bb * 128 + e)) * SEQ + s; p[0] = f2bf(a); p[SEQ] = f2bf(b); p[2 * SEQ] = f2bf(c); p[3 * SEQ] = f2bf(d); }
;     else *(u32x2*)(proj + (size_t)m * EIN + n) = pk4(a, b, c, d); }
.LBB0_464:
	s_or_b64 exec, exec, s[6:7]
	v_cmp_lt_i32_e32 vcc, s69, v152
	s_and_saveexec_b64 s[6:7], vcc
	s_xor_b64 s[6:7], exec, s[6:7]
	s_cbranch_execz .LBB0_466
	v_lshrrev_b32_e32 v62, 14, v68
	v_and_b32_e32 v64, 0x1c0, v62
	v_lshlrev_b32_e32 v64, 14, v64
	v_bfe_u32 v63, v62, 5, 1
	v_lshl_or_b32 v64, v63, 10, v64
	v_and_b32_e32 v63, 31, v62
	v_lshl_or_b32 v64, v63, 5, v64
	v_lshrrev_b32_e32 v63, 4, v74
	v_lshl_or_b32 v64, v63, 11, v64
	v_and_b32_e32 v63, 15, v74
	v_lshl_or_b32 v64, v63, 1, v64
	v_mov_b32_e32 v65, v1
	v_lshl_add_u64 v[62:63], s[12:13], 0, v[64:65]
	v_cvt_pk_bf16_f32 v58, v58, s0
	flat_store_short v[62:63], v58
	v_add_co_u32_e32 v58, vcc, 0x20, v62
	v_cvt_pk_bf16_f32 v64, v59, s0
	s_nop 0
	v_addc_co_u32_e32 v59, vcc, 0, v63, vcc
	flat_store_short v[58:59], v64
	v_add_co_u32_e32 v58, vcc, 0x40, v62
	v_cvt_pk_bf16_f32 v60, v60, s0
	s_nop 0
	v_addc_co_u32_e32 v59, vcc, 0, v63, vcc
	flat_store_short v[58:59], v60
	v_add_co_u32_e32 v58, vcc, 0x60, v62
	v_cvt_pk_bf16_f32 v60, v61, s0
	s_nop 0
	v_addc_co_u32_e32 v59, vcc, 0, v63, vcc
	flat_store_short v[58:59], v60

; DI bf16_t f2bf(float a) { return (bf16_t)(pk2(a, 0.f) & 0xffffu); }
; DI u32x2 pk4(float a, float b, float c, float d) { u32x2 r; r.x = pk2(a, b); r.y = pk2(c, d); return r; }
; template <class AF, class EF>
; DI void gemm_run(unsigned char* lds, int wv, const AF& af, const bf16_t* __restrict__ Bt, int ldb, int M, int N, int K, const EF& ef, int blk_off) {
;     ...
;         for (int k = 0; k < 4; ++k) {
;           auto r = __builtin_amdgcn_permlane16_swap(__float_as_uint(acc[2 * ip][j][k]), __float_as_uint(acc[2 * ip + 1][j][k]), false, false);
;           lo[k] = __uint_as_float(r[0]); hi[k] = __uint_as_float(r[1]);
;         }
;         int n = n0 + wn * 64 + (2 * ip + (q4 & 1)) * 16 + (q4 >> 1) * 8;
;         int m = m0 + wm * 128 + j * 16 + l15;
;         if (n < N) ef.store8(m, n, lo[0], lo[1], lo[2], lo[3], hi[0], hi[1], hi[2], hi[3]);
;   DI void store(int m, int n, float a, float b, float c, float d) const {
;     int bb = m >> 13, s = m & (SEQ - 1);
;     if (n >= C_VS && n < C_KW) { int e = n - C_VS; bf16_t* p = vsT + ((size_t)(bb * 128 + e)) * SEQ + s; p[0] = f2bf(a); p[SEQ] = f2bf(b); p[2 * SEQ] = f2bf(c); p[3 * SEQ] = f2bf(d); }
;     else if (n >= C_VW && n < C_GATE) { int e = n - C_VW; bf16_t* p = vwT + ((size_t)(bb * 128 + e)) * SEQ + s; p[0] = f2bf(a); p[SEQ] = f2bf(b); p[2 * SEQ] = f2bf(c); p[3 * SEQ] = f2bf(d); }
;     else *(u32x2*)(proj + (size_t)m * EIN + n) = pk4(a, b, c, d); }
.LBB0_471:
	s_or_b64 exec, exec, s[16:17]
	v_permlane16_swap_b32_e32 v54, v50
	v_permlane16_swap_b32_e32 v55, v51
	v_permlane16_swap_b32_e32 v56, v52
	v_permlane16_swap_b32_e32 v57, v53
	s_and_saveexec_b64 s[16:17], s[4:5]
	s_cbranch_execz .LBB0_494
	v_cmp_lt_i32_e32 vcc, s69, v152
	s_mov_b64 s[20:21], 0
	s_mov_b64 s[18:19], 0
	s_and_saveexec_b64 s[6:7], vcc
	s_xor_b64 s[6:7], exec, s[6:7]
	v_cmp_ne_u32_e32 vcc, s70, v152
	s_and_b64 s[20:21], vcc, exec
	s_mov_b64 s[18:19], exec
	s_andn2_saveexec_b64 s[22:23], s[6:7]
	v_cmp_eq_u32_e32 vcc, s71, v152
	v_cmp_ne_u32_e64 s[6:7], s71, v152
	s_andn2_b64 s[18:19], s[18:19], exec
	s_and_b64 s[26:27], vcc, exec
	s_andn2_b64 s[20:21], s[20:21], exec
	s_and_b64 s[6:7], s[6:7], exec
	s_or_b64 s[18:19], s[18:19], s[26:27]
	s_or_b64 s[20:21], s[20:21], s[6:7]
	s_or_b64 exec, exec, s[22:23]
	v_or_b32_e32 v58, 16, v153
	s_and_saveexec_b64 s[6:7], s[20:21]
	s_xor_b64 s[6:7], exec, s[6:7]
	s_cbranch_execz .LBB0_478
	v_readlane_b32 s20, v255, 24
	v_readlane_b32 s21, v255, 25
	v_cvt_pk_bf16_f32 v60, v54, v55
	v_cvt_pk_bf16_f32 v61, v56, v57
	v_mov_b64_e32 v[64:65], s[20:21]
	v_mad_i64_i32 v[64:65], s[20:21], v58, s87, v[64:65]
	v_cvt_pk_bf16_f32 v62, v50, v51
	v_cvt_pk_bf16_f32 v63, v52, v53
	v_lshl_add_u64 v[64:65], v[130:131], 1, v[64:65]
	s_andn2_b64 s[18:19], s[18:19], exec
	flat_store_dwordx4 v[64:65], v[60:63] offset:64
	v_subrev_u32_e32 v230, 0x2e0, v130
	v_lshrrev_b32_e32 v232, 7, v230
	v_cmp_eq_u32_e64 s[30:31], 0, v232
	s_and_saveexec_b64 s[36:37], s[30:31]
	v_readlane_b32 s80, v255, 24
	v_readlane_b32 s81, v255, 25
	v_lshrrev_b32_e32 v231, 13, v58
	v_lshlrev_b32_e32 v231, 20, v231
	v_lshrrev_b32_e32 v232, 6, v230
	v_lshl_or_b32 v231, v232, 19, v231
	v_bfe_u32 v232, v58, 6, 7
	v_lshl_or_b32 v231, v232, 12, v231
	v_bfe_u32 v232, v58, 5, 1
	v_lshl_or_b32 v231, v232, 11, v231
	v_bfe_u32 v232, v58, 2, 1
	v_lshl_or_b32 v231, v232, 10, v231
	v_bfe_u32 v232, v230, 5, 1
	v_lshl_or_b32 v231, v232, 9, v231
	v_bfe_u32 v232, v58, 3, 2
	v_lshl_or_b32 v231, v232, 7, v231
	v_bfe_u32 v232, v58, 0, 2
	v_lshl_or_b32 v231, v232, 5, v231
	v_and_b32_e32 v232, 31, v230
	v_or_b32_e32 v231, v231, v232
	v_add_u32_e32 v234, 0x9c00000, v231
	v_mov_b32_e32 v235, 0
	v_lshl_add_u64 v[236:237], v[234:235], 1, s[80:81]
	flat_store_dwordx4 v[236:237], v[60:63]
	s_or_b64 exec, exec, s[36:37]
	v_subrev_u32_e32 v230, 0x978, v130
	v_cmp_gt_u32_e64 s[30:31], 64, v230
	s_and_saveexec_b64 s[36:37], s[30:31]
	v_readlane_b32 s80, v255, 24
	v_readlane_b32 s81, v255, 25
	v_lshrrev_b32_e32 v231, 5, v58
	v_lshlrev_b32_e32 v231, 11, v231
	v_and_b32_e32 v232, 31, v58
	v_lshl_or_b32 v231, v232, 4, v231
	v_lshrrev_b32_e32 v232, 4, v230
	v_lshl_or_b32 v231, v232, 9, v231
	v_and_b32_e32 v232, 15, v230
	v_or_b32_e32 v231, v231, v232
	v_add_u32_e32 v234, 0x9000000, v231
	v_mov_b32_e32 v235, 0
	v_lshl_add_u64 v[236:237], v[234:235], 1, s[80:81]
	flat_store_dwordx4 v[236:237], v[60:63]
	s_or_b64 exec, exec, s[36:37]
.LBB0_478:
	s_or_b64 exec, exec, s[6:7]
	s_and_b64 exec, exec, s[18:19]
	s_cbranch_execz .LBB0_494
	v_and_b32_e32 v59, 0x1f9f, v58
	v_cmp_lt_i32_e32 vcc, s69, v152
	s_and_saveexec_b64 s[6:7], vcc
	s_xor_b64 s[6:7], exec, s[6:7]
	s_cbranch_execz .LBB0_481
	v_lshrrev_b32_e32 v60, 14, v72
	v_and_b32_e32 v62, 0x1c0, v60
	v_lshlrev_b32_e32 v62, 14, v62
	v_bfe_u32 v61, v60, 5, 1
	v_lshl_or_b32 v62, v61, 10, v62
	v_and_b32_e32 v61, 31, v60
	v_lshl_or_b32 v62, v61, 5, v62
	v_lshrrev_b32_e32 v61, 4, v59
	v_lshl_or_b32 v62, v61, 11, v62
	v_and_b32_e32 v61, 15, v59
	v_lshl_or_b32 v62, v61, 1, v62
	v_mov_b32_e32 v63, v1
	v_lshl_add_u64 v[60:61], s[12:13], 0, v[62:63]
	v_cvt_pk_bf16_f32 v54, v54, s0
	flat_store_short v[60:61], v54
	v_add_co_u32_e32 v54, vcc, 0x20, v60
	v_cvt_pk_bf16_f32 v62, v55, s0
	s_nop 0
	v_addc_co_u32_e32 v55, vcc, 0, v61, vcc
	flat_store_short v[54:55], v62
	v_add_co_u32_e32 v54, vcc, 0x40, v60
	v_cvt_pk_bf16_f32 v56, v56, s0
	s_nop 0
	v_addc_co_u32_e32 v55, vcc, 0, v61, vcc
	flat_store_short v[54:55], v56
	v_add_co_u32_e32 v54, vcc, 0x60, v60
	v_cvt_pk_bf16_f32 v56, v57, s0
	s_nop 0
	v_addc_co_u32_e32 v55, vcc, 0, v61, vcc
	flat_store_short v[54:55], v56

; DI bf16_t f2bf(float a) { return (bf16_t)(pk2(a, 0.f) & 0xffffu); }
; DI u32x2 pk4(float a, float b, float c, float d) { u32x2 r; r.x = pk2(a, b); r.y = pk2(c, d); return r; }
;   DI void store(int m, int n, float a, float b, float c, float d) const {
;     ...
;     if (n >= C_VS && n < C_KW) { int e = n - C_VS; bf16_t* p = vsT + ((size_t)(bb * 128 + e)) * SEQ + s; p[0] = f2bf(a); p[SEQ] = f2bf(b); p[2 * SEQ] = f2bf(c); p[3 * SEQ] = f2bf(d); }
;     else if (n >= C_VW && n < C_GATE) { int e = n - C_VW; bf16_t* p = vwT + ((size_t)(bb * 128 + e)) * SEQ + s; p[0] = f2bf(a); p[SEQ] = f2bf(b); p[2 * SEQ] = f2bf(c); p[3 * SEQ] = f2bf(d); }
;     else *(u32x2*)(proj + (size_t)m * EIN + n) = pk4(a, b, c, d); }
.LBB0_487:
	s_or_b64 exec, exec, s[6:7]
	v_cmp_lt_i32_e32 vcc, s69, v152
	s_and_saveexec_b64 s[6:7], vcc
	s_xor_b64 s[6:7], exec, s[6:7]
	s_cbranch_execz .LBB0_489
	v_lshrrev_b32_e32 v54, 14, v68
	v_and_b32_e32 v56, 0x1c0, v54
	v_lshlrev_b32_e32 v56, 14, v56
	v_bfe_u32 v55, v54, 5, 1
	v_lshl_or_b32 v56, v55, 10, v56
	v_and_b32_e32 v55, 31, v54
	v_lshl_or_b32 v56, v55, 5, v56
	v_lshrrev_b32_e32 v55, 4, v59
	v_lshl_or_b32 v56, v55, 11, v56
	v_and_b32_e32 v55, 15, v59
	v_lshl_or_b32 v56, v55, 1, v56
	v_mov_b32_e32 v57, v1
	v_lshl_add_u64 v[54:55], s[12:13], 0, v[56:57]
	v_cvt_pk_bf16_f32 v50, v50, s0
	flat_store_short v[54:55], v50
	v_add_co_u32_e32 v50, vcc, 0x20, v54
	v_cvt_pk_bf16_f32 v56, v51, s0
	s_nop 0
	v_addc_co_u32_e32 v51, vcc, 0, v55, vcc
	flat_store_short v[50:51], v56
	v_add_co_u32_e32 v50, vcc, 0x40, v54
	v_cvt_pk_bf16_f32 v52, v52, s0
	s_nop 0
	v_addc_co_u32_e32 v51, vcc, 0, v55, vcc
	flat_store_short v[50:51], v52
	v_add_co_u32_e32 v50, vcc, 0x60, v54
	v_cvt_pk_bf16_f32 v52, v53, s0
	s_nop 0
	v_addc_co_u32_e32 v51, vcc, 0, v55, vcc
	flat_store_short v[50:51], v52

; DI bf16_t f2bf(float a) { return (bf16_t)(pk2(a, 0.f) & 0xffffu); }
; DI u32x2 pk4(float a, float b, float c, float d) { u32x2 r; r.x = pk2(a, b); r.y = pk2(c, d); return r; }
; template <class AF, class EF>
; DI void gemm_run(unsigned char* lds, int wv, const AF& af, const bf16_t* __restrict__ Bt, int ldb, int M, int N, int K, const EF& ef, int blk_off) {
;     ...
;         for (int k = 0; k < 4; ++k) {
;           auto r = __builtin_amdgcn_permlane16_swap(__float_as_uint(acc[2 * ip][j][k]), __float_as_uint(acc[2 * ip + 1][j][k]), false, false);
;           lo[k] = __uint_as_float(r[0]); hi[k] = __uint_as_float(r[1]);
;         }
;         int n = n0 + wn * 64 + (2 * ip + (q4 & 1)) * 16 + (q4 >> 1) * 8;
;         int m = m0 + wm * 128 + j * 16 + l15;
;         if (n < N) ef.store8(m, n, lo[0], lo[1], lo[2], lo[3], hi[0], hi[1], hi[2], hi[3]);
;   DI void store(int m, int n, float a, float b, float c, float d) const {
;     int bb = m >> 13, s = m & (SEQ - 1);
;     if (n >= C_VS && n < C_KW) { int e = n - C_VS; bf16_t* p = vsT + ((size_t)(bb * 128 + e)) * SEQ + s; p[0] = f2bf(a); p[SEQ] = f2bf(b); p[2 * SEQ] = f2bf(c); p[3 * SEQ] = f2bf(d); }
;     else if (n >= C_VW && n < C_GATE) { int e = n - C_VW; bf16_t* p = vwT + ((size_t)(bb * 128 + e)) * SEQ + s; p[0] = f2bf(a); p[SEQ] = f2bf(b); p[2 * SEQ] = f2bf(c); p[3 * SEQ] = f2bf(d); }
;     else *(u32x2*)(proj + (size_t)m * EIN + n) = pk4(a, b, c, d); }
.LBB0_494:
	s_or_b64 exec, exec, s[16:17]
	v_permlane16_swap_b32_e32 v46, v42
	v_permlane16_swap_b32_e32 v47, v43
	v_permlane16_swap_b32_e32 v48, v44
	v_permlane16_swap_b32_e32 v49, v45
	s_and_saveexec_b64 s[16:17], s[4:5]
	s_cbranch_execz .LBB0_517
	v_cmp_lt_i32_e32 vcc, s69, v152
	s_mov_b64 s[20:21], 0
	s_mov_b64 s[18:19], 0
	s_and_saveexec_b64 s[6:7], vcc
	s_xor_b64 s[6:7], exec, s[6:7]
	v_cmp_ne_u32_e32 vcc, s70, v152
	s_and_b64 s[20:21], vcc, exec
	s_mov_b64 s[18:19], exec
	s_andn2_saveexec_b64 s[22:23], s[6:7]
	v_cmp_eq_u32_e32 vcc, s71, v152
	v_cmp_ne_u32_e64 s[6:7], s71, v152
	s_andn2_b64 s[18:19], s[18:19], exec
	s_and_b64 s[26:27], vcc, exec
	s_andn2_b64 s[20:21], s[20:21], exec
	s_and_b64 s[6:7], s[6:7], exec
	s_or_b64 s[18:19], s[18:19], s[26:27]
	s_or_b64 s[20:21], s[20:21], s[6:7]
	s_or_b64 exec, exec, s[22:23]
	v_or_b32_e32 v50, 32, v153
	s_and_saveexec_b64 s[6:7], s[20:21]
	s_xor_b64 s[6:7], exec, s[6:7]
	s_cbranch_execz .LBB0_501
	v_readlane_b32 s20, v255, 24
	v_readlane_b32 s21, v255, 25
	v_cvt_pk_bf16_f32 v52, v46, v47
	v_cvt_pk_bf16_f32 v53, v48, v49
	v_mov_b64_e32 v[56:57], s[20:21]
	v_mad_i64_i32 v[56:57], s[20:21], v50, s87, v[56:57]
	v_cvt_pk_bf16_f32 v54, v42, v43
	v_cvt_pk_bf16_f32 v55, v44, v45
	v_lshl_add_u64 v[56:57], v[130:131], 1, v[56:57]
	s_andn2_b64 s[18:19], s[18:19], exec
	flat_store_dwordx4 v[56:57], v[52:55] offset:64
	v_subrev_u32_e32 v230, 0x2e0, v130
	v_lshrrev_b32_e32 v232, 7, v230
	v_cmp_eq_u32_e64 s[30:31], 0, v232
	s_and_saveexec_b64 s[36:37], s[30:31]
	v_readlane_b32 s80, v255, 24
	v_readlane_b32 s81, v255, 25
	v_lshrrev_b32_e32 v231, 13, v50
	v_lshlrev_b32_e32 v231, 20, v231
	v_lshrrev_b32_e32 v232, 6, v230
	v_lshl_or_b32 v231, v232, 19, v231
	v_bfe_u32 v232, v50, 6, 7
	v_lshl_or_b32 v231, v232, 12, v231
	v_bfe_u32 v232, v50, 5, 1
	v_lshl_or_b32 v231, v232, 11, v231
	v_bfe_u32 v232, v50, 2, 1
	v_lshl_or_b32 v231, v232, 10, v231
	v_bfe_u32 v232, v230, 5, 1
	v_lshl_or_b32 v231, v232, 9, v231
	v_bfe_u32 v232, v50, 3, 2
	v_lshl_or_b32 v231, v232, 7, v231
	v_bfe_u32 v232, v50, 0, 2
	v_lshl_or_b32 v231, v232, 5, v231
	v_and_b32_e32 v232, 31, v230
	v_or_b32_e32 v231, v231, v232
	v_add_u32_e32 v234, 0x9c00000, v231
	v_mov_b32_e32 v235, 0
	v_lshl_add_u64 v[236:237], v[234:235], 1, s[80:81]
	flat_store_dwordx4 v[236:237], v[52:55]
	s_or_b64 exec, exec, s[36:37]
	v_subrev_u32_e32 v230, 0x978, v130
	v_cmp_gt_u32_e64 s[30:31], 64, v230
	s_and_saveexec_b64 s[36:37], s[30:31]
	v_readlane_b32 s80, v255, 24
	v_readlane_b32 s81, v255, 25
	v_lshrrev_b32_e32 v231, 5, v50
	v_lshlrev_b32_e32 v231, 11, v231
	v_and_b32_e32 v232, 31, v50
	v_lshl_or_b32 v231, v232, 4, v231
	v_lshrrev_b32_e32 v232, 4, v230
	v_lshl_or_b32 v231, v232, 9, v231
	v_and_b32_e32 v232, 15, v230
	v_or_b32_e32 v231, v231, v232
	v_add_u32_e32 v234, 0x9000000, v231
	v_mov_b32_e32 v235, 0
	v_lshl_add_u64 v[236:237], v[234:235], 1, s[80:81]
	flat_store_dwordx4 v[236:237], v[52:55]
	s_or_b64 exec, exec, s[36:37]
.LBB0_501:
	s_or_b64 exec, exec, s[6:7]
	s_and_b64 exec, exec, s[18:19]
	s_cbranch_execz .LBB0_517
	v_and_b32_e32 v51, 0x1faf, v50
	v_cmp_lt_i32_e32 vcc, s69, v152
	s_and_saveexec_b64 s[6:7], vcc
	s_xor_b64 s[6:7], exec, s[6:7]
	s_cbranch_execz .LBB0_504
	v_lshrrev_b32_e32 v52, 14, v72
	v_and_b32_e32 v54, 0x1c0, v52
	v_lshlrev_b32_e32 v54, 14, v54
	v_bfe_u32 v53, v52, 5, 1
	v_lshl_or_b32 v54, v53, 10, v54
	v_and_b32_e32 v53, 31, v52
	v_lshl_or_b32 v54, v53, 5, v54
	v_lshrrev_b32_e32 v53, 4, v51
	v_lshl_or_b32 v54, v53, 11, v54
	v_and_b32_e32 v53, 15, v51
	v_lshl_or_b32 v54, v53, 1, v54
	v_mov_b32_e32 v55, v1
	v_lshl_add_u64 v[52:53], s[12:13], 0, v[54:55]
	v_cvt_pk_bf16_f32 v46, v46, s0
	flat_store_short v[52:53], v46
	v_add_co_u32_e32 v46, vcc, 0x20, v52
	v_cvt_pk_bf16_f32 v54, v47, s0
	s_nop 0
	v_addc_co_u32_e32 v47, vcc, 0, v53, vcc
	flat_store_short v[46:47], v54
	v_add_co_u32_e32 v46, vcc, 0x40, v52
	v_cvt_pk_bf16_f32 v48, v48, s0
	s_nop 0
	v_addc_co_u32_e32 v47, vcc, 0, v53, vcc
	flat_store_short v[46:47], v48
	v_add_co_u32_e32 v46, vcc, 0x60, v52
	v_cvt_pk_bf16_f32 v48, v49, s0
	s_nop 0
	v_addc_co_u32_e32 v47, vcc, 0, v53, vcc
	flat_store_short v[46:47], v48

; DI bf16_t f2bf(float a) { return (bf16_t)(pk2(a, 0.f) & 0xffffu); }
; DI u32x2 pk4(float a, float b, float c, float d) { u32x2 r; r.x = pk2(a, b); r.y = pk2(c, d); return r; }
;   DI void store(int m, int n, float a, float b, float c, float d) const {
;     ...
;     if (n >= C_VS && n < C_KW) { int e = n - C_VS; bf16_t* p = vsT + ((size_t)(bb * 128 + e)) * SEQ + s; p[0] = f2bf(a); p[SEQ] = f2bf(b); p[2 * SEQ] = f2bf(c); p[3 * SEQ] = f2bf(d); }
;     else if (n >= C_VW && n < C_GATE) { int e = n - C_VW; bf16_t* p = vwT + ((size_t)(bb * 128 + e)) * SEQ + s; p[0] = f2bf(a); p[SEQ] = f2bf(b); p[2 * SEQ] = f2bf(c); p[3 * SEQ] = f2bf(d); }
;     else *(u32x2*)(proj + (size_t)m * EIN + n) = pk4(a, b, c, d); }
.LBB0_510:
	s_or_b64 exec, exec, s[6:7]
	v_cmp_lt_i32_e32 vcc, s69, v152
	s_and_saveexec_b64 s[6:7], vcc
	s_xor_b64 s[6:7], exec, s[6:7]
	s_cbranch_execz .LBB0_512
	v_lshrrev_b32_e32 v46, 14, v68
	v_and_b32_e32 v48, 0x1c0, v46
	v_lshlrev_b32_e32 v48, 14, v48
	v_bfe_u32 v47, v46, 5, 1
	v_lshl_or_b32 v48, v47, 10, v48
	v_and_b32_e32 v47, 31, v46
	v_lshl_or_b32 v48, v47, 5, v48
	v_lshrrev_b32_e32 v47, 4, v51
	v_lshl_or_b32 v48, v47, 11, v48
	v_and_b32_e32 v47, 15, v51
	v_lshl_or_b32 v48, v47, 1, v48
	v_mov_b32_e32 v49, v1
	v_lshl_add_u64 v[46:47], s[12:13], 0, v[48:49]
	v_cvt_pk_bf16_f32 v42, v42, s0
	flat_store_short v[46:47], v42
	v_add_co_u32_e32 v42, vcc, 0x20, v46
	v_cvt_pk_bf16_f32 v48, v43, s0
	s_nop 0
	v_addc_co_u32_e32 v43, vcc, 0, v47, vcc
	flat_store_short v[42:43], v48
	v_add_co_u32_e32 v42, vcc, 0x40, v46
	v_cvt_pk_bf16_f32 v44, v44, s0
	s_nop 0
	v_addc_co_u32_e32 v43, vcc, 0, v47, vcc
	flat_store_short v[42:43], v44
	v_add_co_u32_e32 v42, vcc, 0x60, v46
	v_cvt_pk_bf16_f32 v44, v45, s0
	s_nop 0
	v_addc_co_u32_e32 v43, vcc, 0, v47, vcc
	flat_store_short v[42:43], v44

; DI bf16_t f2bf(float a) { return (bf16_t)(pk2(a, 0.f) & 0xffffu); }
; DI u32x2 pk4(float a, float b, float c, float d) { u32x2 r; r.x = pk2(a, b); r.y = pk2(c, d); return r; }
; template <class AF, class EF>
; DI void gemm_run(unsigned char* lds, int wv, const AF& af, const bf16_t* __restrict__ Bt, int ldb, int M, int N, int K, const EF& ef, int blk_off) {
;     ...
;         for (int k = 0; k < 4; ++k) {
;           auto r = __builtin_amdgcn_permlane16_swap(__float_as_uint(acc[2 * ip][j][k]), __float_as_uint(acc[2 * ip + 1][j][k]), false, false);
;           lo[k] = __uint_as_float(r[0]); hi[k] = __uint_as_float(r[1]);
;         }
;         int n = n0 + wn * 64 + (2 * ip + (q4 & 1)) * 16 + (q4 >> 1) * 8;
;         int m = m0 + wm * 128 + j * 16 + l15;
;         if (n < N) ef.store8(m, n, lo[0], lo[1], lo[2], lo[3], hi[0], hi[1], hi[2], hi[3]);
;   DI void store(int m, int n, float a, float b, float c, float d) const {
;     int bb = m >> 13, s = m & (SEQ - 1);
;     if (n >= C_VS && n < C_KW) { int e = n - C_VS; bf16_t* p = vsT + ((size_t)(bb * 128 + e)) * SEQ + s; p[0] = f2bf(a); p[SEQ] = f2bf(b); p[2 * SEQ] = f2bf(c); p[3 * SEQ] = f2bf(d); }
;     else if (n >= C_VW && n < C_GATE) { int e = n - C_VW; bf16_t* p = vwT + ((size_t)(bb * 128 + e)) * SEQ + s; p[0] = f2bf(a); p[SEQ] = f2bf(b); p[2 * SEQ] = f2bf(c); p[3 * SEQ] = f2bf(d); }
;     else *(u32x2*)(proj + (size_t)m * EIN + n) = pk4(a, b, c, d); }
.LBB0_517:
	s_or_b64 exec, exec, s[16:17]
	v_permlane16_swap_b32_e32 v38, v34
	v_permlane16_swap_b32_e32 v39, v35
	v_permlane16_swap_b32_e32 v40, v36
	v_permlane16_swap_b32_e32 v41, v37
	s_and_saveexec_b64 s[16:17], s[4:5]
	s_cbranch_execz .LBB0_540
	v_cmp_lt_i32_e32 vcc, s69, v152
	s_mov_b64 s[20:21], 0
	s_mov_b64 s[18:19], 0
	s_and_saveexec_b64 s[6:7], vcc
	s_xor_b64 s[6:7], exec, s[6:7]
	v_cmp_ne_u32_e32 vcc, s70, v152
	s_and_b64 s[20:21], vcc, exec
	s_mov_b64 s[18:19], exec
	s_andn2_saveexec_b64 s[22:23], s[6:7]
	v_cmp_eq_u32_e32 vcc, s71, v152
	v_cmp_ne_u32_e64 s[6:7], s71, v152
	s_andn2_b64 s[18:19], s[18:19], exec
	s_and_b64 s[26:27], vcc, exec
	s_andn2_b64 s[20:21], s[20:21], exec
	s_and_b64 s[6:7], s[6:7], exec
	s_or_b64 s[18:19], s[18:19], s[26:27]
	s_or_b64 s[20:21], s[20:21], s[6:7]
	s_or_b64 exec, exec, s[22:23]
	v_or_b32_e32 v42, 48, v153
	s_and_saveexec_b64 s[6:7], s[20:21]
	s_xor_b64 s[6:7], exec, s[6:7]
	s_cbranch_execz .LBB0_524
	v_readlane_b32 s20, v255, 24
	v_readlane_b32 s21, v255, 25
	v_cvt_pk_bf16_f32 v44, v38, v39
	v_cvt_pk_bf16_f32 v45, v40, v41
	v_mov_b64_e32 v[48:49], s[20:21]
	v_mad_i64_i32 v[48:49], s[20:21], v42, s87, v[48:49]
	v_cvt_pk_bf16_f32 v46, v34, v35
	v_cvt_pk_bf16_f32 v47, v36, v37
	v_lshl_add_u64 v[48:49], v[130:131], 1, v[48:49]
	s_andn2_b64 s[18:19], s[18:19], exec
	flat_store_dwordx4 v[48:49], v[44:47] offset:64
	v_subrev_u32_e32 v230, 0x2e0, v130
	v_lshrrev_b32_e32 v232, 7, v230
	v_cmp_eq_u32_e64 s[30:31], 0, v232
	s_and_saveexec_b64 s[36:37], s[30:31]
	v_readlane_b32 s80, v255, 24
	v_readlane_b32 s81, v255, 25
	v_lshrrev_b32_e32 v231, 13, v42
	v_lshlrev_b32_e32 v231, 20, v231
	v_lshrrev_b32_e32 v232, 6, v230
	v_lshl_or_b32 v231, v232, 19, v231
	v_bfe_u32 v232, v42, 6, 7
	v_lshl_or_b32 v231, v232, 12, v231
	v_bfe_u32 v232, v42, 5, 1
	v_lshl_or_b32 v231, v232, 11, v231
	v_bfe_u32 v232, v42, 2, 1
	v_lshl_or_b32 v231, v232, 10, v231
	v_bfe_u32 v232, v230, 5, 1
	v_lshl_or_b32 v231, v232, 9, v231
	v_bfe_u32 v232, v42, 3, 2
	v_lshl_or_b32 v231, v232, 7, v231
	v_bfe_u32 v232, v42, 0, 2
	v_lshl_or_b32 v231, v232, 5, v231
	v_and_b32_e32 v232, 31, v230
	v_or_b32_e32 v231, v231, v232
	v_add_u32_e32 v234, 0x9c00000, v231
	v_mov_b32_e32 v235, 0
	v_lshl_add_u64 v[236:237], v[234:235], 1, s[80:81]
	flat_store_dwordx4 v[236:237], v[44:47]
	s_or_b64 exec, exec, s[36:37]
	v_subrev_u32_e32 v230, 0x978, v130
	v_cmp_gt_u32_e64 s[30:31], 64, v230
	s_and_saveexec_b64 s[36:37], s[30:31]
	v_readlane_b32 s80, v255, 24
	v_readlane_b32 s81, v255, 25
	v_lshrrev_b32_e32 v231, 5, v42
	v_lshlrev_b32_e32 v231, 11, v231
	v_and_b32_e32 v232, 31, v42
	v_lshl_or_b32 v231, v232, 4, v231
	v_lshrrev_b32_e32 v232, 4, v230
	v_lshl_or_b32 v231, v232, 9, v231
	v_and_b32_e32 v232, 15, v230
	v_or_b32_e32 v231, v231, v232
	v_add_u32_e32 v234, 0x9000000, v231
	v_mov_b32_e32 v235, 0
	v_lshl_add_u64 v[236:237], v[234:235], 1, s[80:81]
	flat_store_dwordx4 v[236:237], v[44:47]
	s_or_b64 exec, exec, s[36:37]
.LBB0_524:
	s_or_b64 exec, exec, s[6:7]
	s_and_b64 exec, exec, s[18:19]
	s_cbranch_execz .LBB0_540
	v_and_b32_e32 v43, 0x1fbf, v42
	v_cmp_lt_i32_e32 vcc, s69, v152
	s_and_saveexec_b64 s[6:7], vcc
	s_xor_b64 s[6:7], exec, s[6:7]
	s_cbranch_execz .LBB0_527
	v_lshrrev_b32_e32 v44, 14, v72
	v_and_b32_e32 v46, 0x1c0, v44
	v_lshlrev_b32_e32 v46, 14, v46
	v_bfe_u32 v45, v44, 5, 1
	v_lshl_or_b32 v46, v45, 10, v46
	v_and_b32_e32 v45, 31, v44
	v_lshl_or_b32 v46, v45, 5, v46
	v_lshrrev_b32_e32 v45, 4, v43
	v_lshl_or_b32 v46, v45, 11, v46
	v_and_b32_e32 v45, 15, v43
	v_lshl_or_b32 v46, v45, 1, v46
	v_mov_b32_e32 v47, v1
	v_lshl_add_u64 v[44:45], s[12:13], 0, v[46:47]
	v_cvt_pk_bf16_f32 v38, v38, s0
	flat_store_short v[44:45], v38
	v_add_co_u32_e32 v38, vcc, 0x20, v44
	v_cvt_pk_bf16_f32 v46, v39, s0
	s_nop 0
	v_addc_co_u32_e32 v39, vcc, 0, v45, vcc
	flat_store_short v[38:39], v46
	v_add_co_u32_e32 v38, vcc, 0x40, v44
	v_cvt_pk_bf16_f32 v40, v40, s0
	s_nop 0
	v_addc_co_u32_e32 v39, vcc, 0, v45, vcc
	flat_store_short v[38:39], v40
	v_add_co_u32_e32 v38, vcc, 0x60, v44
	v_cvt_pk_bf16_f32 v40, v41, s0
	s_nop 0
	v_addc_co_u32_e32 v39, vcc, 0, v45, vcc
	flat_store_short v[38:39], v40

; DI bf16_t f2bf(float a) { return (bf16_t)(pk2(a, 0.f) & 0xffffu); }
; DI u32x2 pk4(float a, float b, float c, float d) { u32x2 r; r.x = pk2(a, b); r.y = pk2(c, d); return r; }
;   DI void store(int m, int n, float a, float b, float c, float d) const {
;     ...
;     if (n >= C_VS && n < C_KW) { int e = n - C_VS; bf16_t* p = vsT + ((size_t)(bb * 128 + e)) * SEQ + s; p[0] = f2bf(a); p[SEQ] = f2bf(b); p[2 * SEQ] = f2bf(c); p[3 * SEQ] = f2bf(d); }
;     else if (n >= C_VW && n < C_GATE) { int e = n - C_VW; bf16_t* p = vwT + ((size_t)(bb * 128 + e)) * SEQ + s; p[0] = f2bf(a); p[SEQ] = f2bf(b); p[2 * SEQ] = f2bf(c); p[3 * SEQ] = f2bf(d); }
;     else *(u32x2*)(proj + (size_t)m * EIN + n) = pk4(a, b, c, d); }
.LBB0_533:
	s_or_b64 exec, exec, s[6:7]
	v_cmp_lt_i32_e32 vcc, s69, v152
	s_and_saveexec_b64 s[6:7], vcc
	s_xor_b64 s[6:7], exec, s[6:7]
	s_cbranch_execz .LBB0_535
	v_lshrrev_b32_e32 v38, 14, v68
	v_and_b32_e32 v40, 0x1c0, v38
	v_lshlrev_b32_e32 v40, 14, v40
	v_bfe_u32 v39, v38, 5, 1
	v_lshl_or_b32 v40, v39, 10, v40
	v_and_b32_e32 v39, 31, v38
	v_lshl_or_b32 v40, v39, 5, v40
	v_lshrrev_b32_e32 v39, 4, v43
	v_lshl_or_b32 v40, v39, 11, v40
	v_and_b32_e32 v39, 15, v43
	v_lshl_or_b32 v40, v39, 1, v40
	v_mov_b32_e32 v41, v1
	v_lshl_add_u64 v[38:39], s[12:13], 0, v[40:41]
	v_cvt_pk_bf16_f32 v34, v34, s0
	flat_store_short v[38:39], v34
	v_add_co_u32_e32 v34, vcc, 0x20, v38
	v_cvt_pk_bf16_f32 v40, v35, s0
	s_nop 0
	v_addc_co_u32_e32 v35, vcc, 0, v39, vcc
	flat_store_short v[34:35], v40
	v_add_co_u32_e32 v34, vcc, 0x40, v38
	v_cvt_pk_bf16_f32 v36, v36, s0
	s_nop 0
	v_addc_co_u32_e32 v35, vcc, 0, v39, vcc
	flat_store_short v[34:35], v36
	v_add_co_u32_e32 v34, vcc, 0x60, v38
	v_cvt_pk_bf16_f32 v36, v37, s0
	s_nop 0
	v_addc_co_u32_e32 v35, vcc, 0, v39, vcc
	flat_store_short v[34:35], v36

; DI bf16_t f2bf(float a) { return (bf16_t)(pk2(a, 0.f) & 0xffffu); }
; DI u32x2 pk4(float a, float b, float c, float d) { u32x2 r; r.x = pk2(a, b); r.y = pk2(c, d); return r; }
; template <class AF, class EF>
; DI void gemm_run(unsigned char* lds, int wv, const AF& af, const bf16_t* __restrict__ Bt, int ldb, int M, int N, int K, const EF& ef, int blk_off) {
;     ...
;         for (int k = 0; k < 4; ++k) {
;           auto r = __builtin_amdgcn_permlane16_swap(__float_as_uint(acc[2 * ip][j][k]), __float_as_uint(acc[2 * ip + 1][j][k]), false, false);
;           lo[k] = __uint_as_float(r[0]); hi[k] = __uint_as_float(r[1]);
;         }
;         int n = n0 + wn * 64 + (2 * ip + (q4 & 1)) * 16 + (q4 >> 1) * 8;
;         int m = m0 + wm * 128 + j * 16 + l15;
;         if (n < N) ef.store8(m, n, lo[0], lo[1], lo[2], lo[3], hi[0], hi[1], hi[2], hi[3]);
;   DI void store(int m, int n, float a, float b, float c, float d) const {
;     int bb = m >> 13, s = m & (SEQ - 1);
;     if (n >= C_VS && n < C_KW) { int e = n - C_VS; bf16_t* p = vsT + ((size_t)(bb * 128 + e)) * SEQ + s; p[0] = f2bf(a); p[SEQ] = f2bf(b); p[2 * SEQ] = f2bf(c); p[3 * SEQ] = f2bf(d); }
;     else if (n >= C_VW && n < C_GATE) { int e = n - C_VW; bf16_t* p = vwT + ((size_t)(bb * 128 + e)) * SEQ + s; p[0] = f2bf(a); p[SEQ] = f2bf(b); p[2 * SEQ] = f2bf(c); p[3 * SEQ] = f2bf(d); }
;     else *(u32x2*)(proj + (size_t)m * EIN + n) = pk4(a, b, c, d); }
.LBB0_540:
	s_or_b64 exec, exec, s[16:17]
	v_permlane16_swap_b32_e32 v30, v26
	v_permlane16_swap_b32_e32 v31, v27
	v_permlane16_swap_b32_e32 v32, v28
	v_permlane16_swap_b32_e32 v33, v29
	s_and_saveexec_b64 s[16:17], s[4:5]
	s_cbranch_execz .LBB0_563
	v_cmp_lt_i32_e32 vcc, s69, v152
	s_mov_b64 s[20:21], 0
	s_mov_b64 s[18:19], 0
	s_and_saveexec_b64 s[6:7], vcc
	s_xor_b64 s[6:7], exec, s[6:7]
	v_cmp_ne_u32_e32 vcc, s70, v152
	s_and_b64 s[20:21], vcc, exec
	s_mov_b64 s[18:19], exec
	s_andn2_saveexec_b64 s[22:23], s[6:7]
	v_cmp_eq_u32_e32 vcc, s71, v152
	v_cmp_ne_u32_e64 s[6:7], s71, v152
	s_andn2_b64 s[18:19], s[18:19], exec
	s_and_b64 s[26:27], vcc, exec
	s_andn2_b64 s[20:21], s[20:21], exec
	s_and_b64 s[6:7], s[6:7], exec
	s_or_b64 s[18:19], s[18:19], s[26:27]
	s_or_b64 s[20:21], s[20:21], s[6:7]
	s_or_b64 exec, exec, s[22:23]
	v_or_b32_e32 v34, 64, v153
	s_and_saveexec_b64 s[6:7], s[20:21]
	s_xor_b64 s[6:7], exec, s[6:7]
	s_cbranch_execz .LBB0_547
	v_readlane_b32 s20, v255, 24
	v_readlane_b32 s21, v255, 25
	v_cvt_pk_bf16_f32 v36, v30, v31
	v_cvt_pk_bf16_f32 v37, v32, v33
	v_mov_b64_e32 v[40:41], s[20:21]
	v_mad_i64_i32 v[40:41], s[20:21], v34, s87, v[40:41]
	v_cvt_pk_bf16_f32 v38, v26, v27
	v_cvt_pk_bf16_f32 v39, v28, v29
	v_lshl_add_u64 v[40:41], v[130:131], 1, v[40:41]
	s_andn2_b64 s[18:19], s[18:19], exec
	flat_store_dwordx4 v[40:41], v[36:39] offset:64
	v_subrev_u32_e32 v230, 0x2e0, v130
	v_lshrrev_b32_e32 v232, 7, v230
	v_cmp_eq_u32_e64 s[30:31], 0, v232
	s_and_saveexec_b64 s[36:37], s[30:31]
	v_readlane_b32 s80, v255, 24
	v_readlane_b32 s81, v255, 25
	v_lshrrev_b32_e32 v231, 13, v34
	v_lshlrev_b32_e32 v231, 20, v231
	v_lshrrev_b32_e32 v232, 6, v230
	v_lshl_or_b32 v231, v232, 19, v231
	v_bfe_u32 v232, v34, 6, 7
	v_lshl_or_b32 v231, v232, 12, v231
	v_bfe_u32 v232, v34, 5, 1
	v_lshl_or_b32 v231, v232, 11, v231
	v_bfe_u32 v232, v34, 2, 1
	v_lshl_or_b32 v231, v232, 10, v231
	v_bfe_u32 v232, v230, 5, 1
	v_lshl_or_b32 v231, v232, 9, v231
	v_bfe_u32 v232, v34, 3, 2
	v_lshl_or_b32 v231, v232, 7, v231
	v_bfe_u32 v232, v34, 0, 2
	v_lshl_or_b32 v231, v232, 5, v231
	v_and_b32_e32 v232, 31, v230
	v_or_b32_e32 v231, v231, v232
	v_add_u32_e32 v234, 0x9c00000, v231
	v_mov_b32_e32 v235, 0
	v_lshl_add_u64 v[236:237], v[234:235], 1, s[80:81]
	flat_store_dwordx4 v[236:237], v[36:39]
	s_or_b64 exec, exec, s[36:37]
	v_subrev_u32_e32 v230, 0x978, v130
	v_cmp_gt_u32_e64 s[30:31], 64, v230
	s_and_saveexec_b64 s[36:37], s[30:31]
	v_readlane_b32 s80, v255, 24
	v_readlane_b32 s81, v255, 25
	v_lshrrev_b32_e32 v231, 5, v34
	v_lshlrev_b32_e32 v231, 11, v231
	v_and_b32_e32 v232, 31, v34
	v_lshl_or_b32 v231, v232, 4, v231
	v_lshrrev_b32_e32 v232, 4, v230
	v_lshl_or_b32 v231, v232, 9, v231
	v_and_b32_e32 v232, 15, v230
	v_or_b32_e32 v231, v231, v232
	v_add_u32_e32 v234, 0x9000000, v231
	v_mov_b32_e32 v235, 0
	v_lshl_add_u64 v[236:237], v[234:235], 1, s[80:81]
	flat_store_dwordx4 v[236:237], v[36:39]
	s_or_b64 exec, exec, s[36:37]
.LBB0_547:
	s_or_b64 exec, exec, s[6:7]
	s_and_b64 exec, exec, s[18:19]
	s_cbranch_execz .LBB0_563
	v_and_b32_e32 v35, 0x1fcf, v34
	v_cmp_lt_i32_e32 vcc, s69, v152
	s_and_saveexec_b64 s[6:7], vcc
	s_xor_b64 s[6:7], exec, s[6:7]
	s_cbranch_execz .LBB0_550
	v_lshrrev_b32_e32 v36, 14, v72
	v_and_b32_e32 v38, 0x1c0, v36
	v_lshlrev_b32_e32 v38, 14, v38
	v_bfe_u32 v37, v36, 5, 1
	v_lshl_or_b32 v38, v37, 10, v38
	v_and_b32_e32 v37, 31, v36
	v_lshl_or_b32 v38, v37, 5, v38
	v_lshrrev_b32_e32 v37, 4, v35
	v_lshl_or_b32 v38, v37, 11, v38
	v_and_b32_e32 v37, 15, v35
	v_lshl_or_b32 v38, v37, 1, v38
	v_mov_b32_e32 v39, v1
	v_lshl_add_u64 v[36:37], s[12:13], 0, v[38:39]
	v_cvt_pk_bf16_f32 v30, v30, s0
	flat_store_short v[36:37], v30
	v_add_co_u32_e32 v30, vcc, 0x20, v36
	v_cvt_pk_bf16_f32 v38, v31, s0
	s_nop 0
	v_addc_co_u32_e32 v31, vcc, 0, v37, vcc
	flat_store_short v[30:31], v38
	v_add_co_u32_e32 v30, vcc, 0x40, v36
	v_cvt_pk_bf16_f32 v32, v32, s0
	s_nop 0
	v_addc_co_u32_e32 v31, vcc, 0, v37, vcc
	flat_store_short v[30:31], v32
	v_add_co_u32_e32 v30, vcc, 0x60, v36
	v_cvt_pk_bf16_f32 v32, v33, s0
	s_nop 0
	v_addc_co_u32_e32 v31, vcc, 0, v37, vcc
	flat_store_short v[30:31], v32

; DI bf16_t f2bf(float a) { return (bf16_t)(pk2(a, 0.f) & 0xffffu); }
; DI u32x2 pk4(float a, float b, float c, float d) { u32x2 r; r.x = pk2(a, b); r.y = pk2(c, d); return r; }
;   DI void store(int m, int n, float a, float b, float c, float d) const {
;     ...
;     if (n >= C_VS && n < C_KW) { int e = n - C_VS; bf16_t* p = vsT + ((size_t)(bb * 128 + e)) * SEQ + s; p[0] = f2bf(a); p[SEQ] = f2bf(b); p[2 * SEQ] = f2bf(c); p[3 * SEQ] = f2bf(d); }
;     else if (n >= C_VW && n < C_GATE) { int e = n - C_VW; bf16_t* p = vwT + ((size_t)(bb * 128 + e)) * SEQ + s; p[0] = f2bf(a); p[SEQ] = f2bf(b); p[2 * SEQ] = f2bf(c); p[3 * SEQ] = f2bf(d); }
;     else *(u32x2*)(proj + (size_t)m * EIN + n) = pk4(a, b, c, d); }
.LBB0_556:
	s_or_b64 exec, exec, s[6:7]
	v_cmp_lt_i32_e32 vcc, s69, v152
	s_and_saveexec_b64 s[6:7], vcc
	s_xor_b64 s[6:7], exec, s[6:7]
	s_cbranch_execz .LBB0_558
	v_lshrrev_b32_e32 v30, 14, v68
	v_and_b32_e32 v32, 0x1c0, v30
	v_lshlrev_b32_e32 v32, 14, v32
	v_bfe_u32 v31, v30, 5, 1
	v_lshl_or_b32 v32, v31, 10, v32
	v_and_b32_e32 v31, 31, v30
	v_lshl_or_b32 v32, v31, 5, v32
	v_lshrrev_b32_e32 v31, 4, v35
	v_lshl_or_b32 v32, v31, 11, v32
	v_and_b32_e32 v31, 15, v35
	v_lshl_or_b32 v32, v31, 1, v32
	v_mov_b32_e32 v33, v1
	v_lshl_add_u64 v[30:31], s[12:13], 0, v[32:33]
	v_cvt_pk_bf16_f32 v26, v26, s0
	flat_store_short v[30:31], v26
	v_add_co_u32_e32 v26, vcc, 0x20, v30
	v_cvt_pk_bf16_f32 v32, v27, s0
	s_nop 0
	v_addc_co_u32_e32 v27, vcc, 0, v31, vcc
	flat_store_short v[26:27], v32
	v_add_co_u32_e32 v26, vcc, 0x40, v30
	v_cvt_pk_bf16_f32 v28, v28, s0
	s_nop 0
	v_addc_co_u32_e32 v27, vcc, 0, v31, vcc
	flat_store_short v[26:27], v28
	v_add_co_u32_e32 v26, vcc, 0x60, v30
	v_cvt_pk_bf16_f32 v28, v29, s0
	s_nop 0
	v_addc_co_u32_e32 v27, vcc, 0, v31, vcc
	flat_store_short v[26:27], v28

; DI bf16_t f2bf(float a) { return (bf16_t)(pk2(a, 0.f) & 0xffffu); }
; DI u32x2 pk4(float a, float b, float c, float d) { u32x2 r; r.x = pk2(a, b); r.y = pk2(c, d); return r; }
; template <class AF, class EF>
; DI void gemm_run(unsigned char* lds, int wv, const AF& af, const bf16_t* __restrict__ Bt, int ldb, int M, int N, int K, const EF& ef, int blk_off) {
;     ...
;         for (int k = 0; k < 4; ++k) {
;           auto r = __builtin_amdgcn_permlane16_swap(__float_as_uint(acc[2 * ip][j][k]), __float_as_uint(acc[2 * ip + 1][j][k]), false, false);
;           lo[k] = __uint_as_float(r[0]); hi[k] = __uint_as_float(r[1]);
;         }
;         int n = n0 + wn * 64 + (2 * ip + (q4 & 1)) * 16 + (q4 >> 1) * 8;
;         int m = m0 + wm * 128 + j * 16 + l15;
;         if (n < N) ef.store8(m, n, lo[0], lo[1], lo[2], lo[3], hi[0], hi[1], hi[2], hi[3]);
;   DI void store(int m, int n, float a, float b, float c, float d) const {
;     int bb = m >> 13, s = m & (SEQ - 1);
;     if (n >= C_VS && n < C_KW) { int e = n - C_VS; bf16_t* p = vsT + ((size_t)(bb * 128 + e)) * SEQ + s; p[0] = f2bf(a); p[SEQ] = f2bf(b); p[2 * SEQ] = f2bf(c); p[3 * SEQ] = f2bf(d); }
;     else if (n >= C_VW && n < C_GATE) { int e = n - C_VW; bf16_t* p = vwT + ((size_t)(bb * 128 + e)) * SEQ + s; p[0] = f2bf(a); p[SEQ] = f2bf(b); p[2 * SEQ] = f2bf(c); p[3 * SEQ] = f2bf(d); }
;     else *(u32x2*)(proj + (size_t)m * EIN + n) = pk4(a, b, c, d); }
.LBB0_563:
	s_or_b64 exec, exec, s[16:17]
	v_permlane16_swap_b32_e32 v22, v18
	v_permlane16_swap_b32_e32 v23, v19
	v_permlane16_swap_b32_e32 v24, v20
	v_permlane16_swap_b32_e32 v25, v21
	s_and_saveexec_b64 s[16:17], s[4:5]
	s_cbranch_execz .LBB0_586
	v_cmp_lt_i32_e32 vcc, s69, v152
	s_mov_b64 s[20:21], 0
	s_mov_b64 s[18:19], 0
	s_and_saveexec_b64 s[6:7], vcc
	s_xor_b64 s[6:7], exec, s[6:7]
	v_cmp_ne_u32_e32 vcc, s70, v152
	s_and_b64 s[20:21], vcc, exec
	s_mov_b64 s[18:19], exec
	s_andn2_saveexec_b64 s[22:23], s[6:7]
	v_cmp_eq_u32_e32 vcc, s71, v152
	v_cmp_ne_u32_e64 s[6:7], s71, v152
	s_andn2_b64 s[18:19], s[18:19], exec
	s_and_b64 s[26:27], vcc, exec
	s_andn2_b64 s[20:21], s[20:21], exec
	s_and_b64 s[6:7], s[6:7], exec
	s_or_b64 s[18:19], s[18:19], s[26:27]
	s_or_b64 s[20:21], s[20:21], s[6:7]
	s_or_b64 exec, exec, s[22:23]
	v_or_b32_e32 v26, 0x50, v153
	s_and_saveexec_b64 s[6:7], s[20:21]
	s_xor_b64 s[6:7], exec, s[6:7]
	s_cbranch_execz .LBB0_570
	v_readlane_b32 s20, v255, 24
	v_readlane_b32 s21, v255, 25
	v_cvt_pk_bf16_f32 v28, v22, v23
	v_cvt_pk_bf16_f32 v29, v24, v25
	v_mov_b64_e32 v[32:33], s[20:21]
	v_mad_i64_i32 v[32:33], s[20:21], v26, s87, v[32:33]
	v_cvt_pk_bf16_f32 v30, v18, v19
	v_cvt_pk_bf16_f32 v31, v20, v21
	v_lshl_add_u64 v[32:33], v[130:131], 1, v[32:33]
	s_andn2_b64 s[18:19], s[18:19], exec
	flat_store_dwordx4 v[32:33], v[28:31] offset:64
	v_subrev_u32_e32 v230, 0x2e0, v130
	v_lshrrev_b32_e32 v232, 7, v230
	v_cmp_eq_u32_e64 s[30:31], 0, v232
	s_and_saveexec_b64 s[36:37], s[30:31]
	v_readlane_b32 s80, v255, 24
	v_readlane_b32 s81, v255, 25
	v_lshrrev_b32_e32 v231, 13, v26
	v_lshlrev_b32_e32 v231, 20, v231
	v_lshrrev_b32_e32 v232, 6, v230
	v_lshl_or_b32 v231, v232, 19, v231
	v_bfe_u32 v232, v26, 6, 7
	v_lshl_or_b32 v231, v232, 12, v231
	v_bfe_u32 v232, v26, 5, 1
	v_lshl_or_b32 v231, v232, 11, v231
	v_bfe_u32 v232, v26, 2, 1
	v_lshl_or_b32 v231, v232, 10, v231
	v_bfe_u32 v232, v230, 5, 1
	v_lshl_or_b32 v231, v232, 9, v231
	v_bfe_u32 v232, v26, 3, 2
	v_lshl_or_b32 v231, v232, 7, v231
	v_bfe_u32 v232, v26, 0, 2
	v_lshl_or_b32 v231, v232, 5, v231
	v_and_b32_e32 v232, 31, v230
	v_or_b32_e32 v231, v231, v232
	v_add_u32_e32 v234, 0x9c00000, v231
	v_mov_b32_e32 v235, 0
	v_lshl_add_u64 v[236:237], v[234:235], 1, s[80:81]
	flat_store_dwordx4 v[236:237], v[28:31]
	s_or_b64 exec, exec, s[36:37]
	v_subrev_u32_e32 v230, 0x978, v130
	v_cmp_gt_u32_e64 s[30:31], 64, v230
	s_and_saveexec_b64 s[36:37], s[30:31]
	v_readlane_b32 s80, v255, 24
	v_readlane_b32 s81, v255, 25
	v_lshrrev_b32_e32 v231, 5, v26
	v_lshlrev_b32_e32 v231, 11, v231
	v_and_b32_e32 v232, 31, v26
	v_lshl_or_b32 v231, v232, 4, v231
	v_lshrrev_b32_e32 v232, 4, v230
	v_lshl_or_b32 v231, v232, 9, v231
	v_and_b32_e32 v232, 15, v230
	v_or_b32_e32 v231, v231, v232
	v_add_u32_e32 v234, 0x9000000, v231
	v_mov_b32_e32 v235, 0
	v_lshl_add_u64 v[236:237], v[234:235], 1, s[80:81]
	flat_store_dwordx4 v[236:237], v[28:31]
	s_or_b64 exec, exec, s[36:37]
.LBB0_570:
	s_or_b64 exec, exec, s[6:7]
	s_and_b64 exec, exec, s[18:19]
	s_cbranch_execz .LBB0_586
	v_and_b32_e32 v27, 0x1fdf, v26
	v_cmp_lt_i32_e32 vcc, s69, v152
	s_and_saveexec_b64 s[6:7], vcc
	s_xor_b64 s[6:7], exec, s[6:7]
	s_cbranch_execz .LBB0_573
	v_lshrrev_b32_e32 v28, 14, v72
	v_and_b32_e32 v30, 0x1c0, v28
	v_lshlrev_b32_e32 v30, 14, v30
	v_bfe_u32 v29, v28, 5, 1
	v_lshl_or_b32 v30, v29, 10, v30
	v_and_b32_e32 v29, 31, v28
	v_lshl_or_b32 v30, v29, 5, v30
	v_lshrrev_b32_e32 v29, 4, v27
	v_lshl_or_b32 v30, v29, 11, v30
	v_and_b32_e32 v29, 15, v27
	v_lshl_or_b32 v30, v29, 1, v30
	v_mov_b32_e32 v31, v1
	v_lshl_add_u64 v[28:29], s[12:13], 0, v[30:31]
	v_cvt_pk_bf16_f32 v22, v22, s0
	flat_store_short v[28:29], v22
	v_add_co_u32_e32 v22, vcc, 0x20, v28
	v_cvt_pk_bf16_f32 v30, v23, s0
	s_nop 0
	v_addc_co_u32_e32 v23, vcc, 0, v29, vcc
	flat_store_short v[22:23], v30
	v_add_co_u32_e32 v22, vcc, 0x40, v28
	v_cvt_pk_bf16_f32 v24, v24, s0
	s_nop 0
	v_addc_co_u32_e32 v23, vcc, 0, v29, vcc
	flat_store_short v[22:23], v24
	v_add_co_u32_e32 v22, vcc, 0x60, v28
	v_cvt_pk_bf16_f32 v24, v25, s0
	s_nop 0
	v_addc_co_u32_e32 v23, vcc, 0, v29, vcc
	flat_store_short v[22:23], v24

; DI bf16_t f2bf(float a) { return (bf16_t)(pk2(a, 0.f) & 0xffffu); }
;   DI void store(int m, int n, float a, float b, float c, float d) const {
;     ...
;     if (n >= C_VS && n < C_KW) { int e = n - C_VS; bf16_t* p = vsT + ((size_t)(bb * 128 + e)) * SEQ + s; p[0] = f2bf(a); p[SEQ] = f2bf(b); p[2 * SEQ] = f2bf(c); p[3 * SEQ] = f2bf(d); }
;     else if (n >= C_VW && n < C_GATE) { int e = n - C_VW; bf16_t* p = vwT + ((size_t)(bb * 128 + e)) * SEQ + s; p[0] = f2bf(a); p[SEQ] = f2bf(b); p[2 * SEQ] = f2bf(c); p[3 * SEQ] = f2bf(d); }
.LBB0_579:
	s_or_b64 exec, exec, s[6:7]
	v_cmp_lt_i32_e32 vcc, s69, v152
	s_and_saveexec_b64 s[6:7], vcc
	s_xor_b64 s[6:7], exec, s[6:7]
	s_cbranch_execz .LBB0_581
	v_lshrrev_b32_e32 v22, 14, v68
	v_and_b32_e32 v24, 0x1c0, v22
	v_lshlrev_b32_e32 v24, 14, v24
	v_bfe_u32 v23, v22, 5, 1
	v_lshl_or_b32 v24, v23, 10, v24
	v_and_b32_e32 v23, 31, v22
	v_lshl_or_b32 v24, v23, 5, v24
	v_lshrrev_b32_e32 v23, 4, v27
	v_lshl_or_b32 v24, v23, 11, v24
	v_and_b32_e32 v23, 15, v27
	v_lshl_or_b32 v24, v23, 1, v24
	v_mov_b32_e32 v25, v1
	v_lshl_add_u64 v[22:23], s[12:13], 0, v[24:25]
	v_cvt_pk_bf16_f32 v18, v18, s0
	flat_store_short v[22:23], v18
	v_add_co_u32_e32 v18, vcc, 0x20, v22
	v_cvt_pk_bf16_f32 v24, v19, s0
	s_nop 0
	v_addc_co_u32_e32 v19, vcc, 0, v23, vcc
	flat_store_short v[18:19], v24
	v_add_co_u32_e32 v18, vcc, 0x40, v22
	v_cvt_pk_bf16_f32 v20, v20, s0
	s_nop 0
	v_addc_co_u32_e32 v19, vcc, 0, v23, vcc
	flat_store_short v[18:19], v20
	v_add_co_u32_e32 v18, vcc, 0x60, v22
	v_cvt_pk_bf16_f32 v20, v21, s0
	s_nop 0
	v_addc_co_u32_e32 v19, vcc, 0, v23, vcc
	flat_store_short v[18:19], v20

; DI bf16_t f2bf(float a) { return (bf16_t)(pk2(a, 0.f) & 0xffffu); }
; DI u32x2 pk4(float a, float b, float c, float d) { u32x2 r; r.x = pk2(a, b); r.y = pk2(c, d); return r; }
; template <class AF, class EF>
; DI void gemm_run(unsigned char* lds, int wv, const AF& af, const bf16_t* __restrict__ Bt, int ldb, int M, int N, int K, const EF& ef, int blk_off) {
;     ...
;         for (int k = 0; k < 4; ++k) {
;           auto r = __builtin_amdgcn_permlane16_swap(__float_as_uint(acc[2 * ip][j][k]), __float_as_uint(acc[2 * ip + 1][j][k]), false, false);
;           lo[k] = __uint_as_float(r[0]); hi[k] = __uint_as_float(r[1]);
;         }
;         int n = n0 + wn * 64 + (2 * ip + (q4 & 1)) * 16 + (q4 >> 1) * 8;
;         int m = m0 + wm * 128 + j * 16 + l15;
;         if (n < N) ef.store8(m, n, lo[0], lo[1], lo[2], lo[3], hi[0], hi[1], hi[2], hi[3]);
;   DI void store(int m, int n, float a, float b, float c, float d) const {
;     int bb = m >> 13, s = m & (SEQ - 1);
;     if (n >= C_VS && n < C_KW) { int e = n - C_VS; bf16_t* p = vsT + ((size_t)(bb * 128 + e)) * SEQ + s; p[0] = f2bf(a); p[SEQ] = f2bf(b); p[2 * SEQ] = f2bf(c); p[3 * SEQ] = f2bf(d); }
;     else if (n >= C_VW && n < C_GATE) { int e = n - C_VW; bf16_t* p = vwT + ((size_t)(bb * 128 + e)) * SEQ + s; p[0] = f2bf(a); p[SEQ] = f2bf(b); p[2 * SEQ] = f2bf(c); p[3 * SEQ] = f2bf(d); }
;     else *(u32x2*)(proj + (size_t)m * EIN + n) = pk4(a, b, c, d); }
.LBB0_586:
	s_or_b64 exec, exec, s[16:17]
	v_permlane16_swap_b32_e32 v14, v10
	v_permlane16_swap_b32_e32 v15, v11
	v_permlane16_swap_b32_e32 v16, v12
	v_permlane16_swap_b32_e32 v17, v13
	s_and_saveexec_b64 s[16:17], s[4:5]
	s_cbranch_execz .LBB0_609
	v_cmp_lt_i32_e32 vcc, s69, v152
	s_mov_b64 s[20:21], 0
	s_mov_b64 s[18:19], 0
	s_and_saveexec_b64 s[6:7], vcc
	s_xor_b64 s[6:7], exec, s[6:7]
	v_cmp_ne_u32_e32 vcc, s70, v152
	s_and_b64 s[20:21], vcc, exec
	s_mov_b64 s[18:19], exec
	s_andn2_saveexec_b64 s[22:23], s[6:7]
	v_cmp_eq_u32_e32 vcc, s71, v152
	v_cmp_ne_u32_e64 s[6:7], s71, v152
	s_andn2_b64 s[18:19], s[18:19], exec
	s_and_b64 s[26:27], vcc, exec
	s_andn2_b64 s[20:21], s[20:21], exec
	s_and_b64 s[6:7], s[6:7], exec
	s_or_b64 s[18:19], s[18:19], s[26:27]
	s_or_b64 s[20:21], s[20:21], s[6:7]
	s_or_b64 exec, exec, s[22:23]
	v_or_b32_e32 v18, 0x60, v153
	s_and_saveexec_b64 s[6:7], s[20:21]
	s_xor_b64 s[6:7], exec, s[6:7]
	s_cbranch_execz .LBB0_593
	v_readlane_b32 s20, v255, 24
	v_readlane_b32 s21, v255, 25
	v_cvt_pk_bf16_f32 v20, v14, v15
	v_cvt_pk_bf16_f32 v21, v16, v17
	v_mov_b64_e32 v[24:25], s[20:21]
	v_mad_i64_i32 v[24:25], s[20:21], v18, s87, v[24:25]
	v_cvt_pk_bf16_f32 v22, v10, v11
	v_cvt_pk_bf16_f32 v23, v12, v13
	v_lshl_add_u64 v[24:25], v[130:131], 1, v[24:25]
	s_andn2_b64 s[18:19], s[18:19], exec
	flat_store_dwordx4 v[24:25], v[20:23] offset:64
	v_subrev_u32_e32 v230, 0x2e0, v130
	v_lshrrev_b32_e32 v232, 7, v230
	v_cmp_eq_u32_e64 s[30:31], 0, v232
	s_and_saveexec_b64 s[36:37], s[30:31]
	v_readlane_b32 s80, v255, 24
	v_readlane_b32 s81, v255, 25
	v_lshrrev_b32_e32 v231, 13, v18
	v_lshlrev_b32_e32 v231, 20, v231
	v_lshrrev_b32_e32 v232, 6, v230
	v_lshl_or_b32 v231, v232, 19, v231
	v_bfe_u32 v232, v18, 6, 7
	v_lshl_or_b32 v231, v232, 12, v231
	v_bfe_u32 v232, v18, 5, 1
	v_lshl_or_b32 v231, v232, 11, v231
	v_bfe_u32 v232, v18, 2, 1
	v_lshl_or_b32 v231, v232, 10, v231
	v_bfe_u32 v232, v230, 5, 1
	v_lshl_or_b32 v231, v232, 9, v231
	v_bfe_u32 v232, v18, 3, 2
	v_lshl_or_b32 v231, v232, 7, v231
	v_bfe_u32 v232, v18, 0, 2
	v_lshl_or_b32 v231, v232, 5, v231
	v_and_b32_e32 v232, 31, v230
	v_or_b32_e32 v231, v231, v232
	v_add_u32_e32 v234, 0x9c00000, v231
	v_mov_b32_e32 v235, 0
	v_lshl_add_u64 v[236:237], v[234:235], 1, s[80:81]
	flat_store_dwordx4 v[236:237], v[20:23]
	s_or_b64 exec, exec, s[36:37]
	v_subrev_u32_e32 v230, 0x978, v130
	v_cmp_gt_u32_e64 s[30:31], 64, v230
	s_and_saveexec_b64 s[36:37], s[30:31]
	v_readlane_b32 s80, v255, 24
	v_readlane_b32 s81, v255, 25
	v_lshrrev_b32_e32 v231, 5, v18
	v_lshlrev_b32_e32 v231, 11, v231
	v_and_b32_e32 v232, 31, v18
	v_lshl_or_b32 v231, v232, 4, v231
	v_lshrrev_b32_e32 v232, 4, v230
	v_lshl_or_b32 v231, v232, 9, v231
	v_and_b32_e32 v232, 15, v230
	v_or_b32_e32 v231, v231, v232
	v_add_u32_e32 v234, 0x9000000, v231
	v_mov_b32_e32 v235, 0
	v_lshl_add_u64 v[236:237], v[234:235], 1, s[80:81]
	flat_store_dwordx4 v[236:237], v[20:23]
	s_or_b64 exec, exec, s[36:37]
.LBB0_593:
	s_or_b64 exec, exec, s[6:7]
	s_and_b64 exec, exec, s[18:19]
	s_cbranch_execz .LBB0_609
	v_and_b32_e32 v19, 0x1fef, v18
	v_cmp_lt_i32_e32 vcc, s69, v152
	s_and_saveexec_b64 s[6:7], vcc
	s_xor_b64 s[6:7], exec, s[6:7]
	s_cbranch_execz .LBB0_596
	v_lshrrev_b32_e32 v20, 14, v72
	v_and_b32_e32 v22, 0x1c0, v20
	v_lshlrev_b32_e32 v22, 14, v22
	v_bfe_u32 v21, v20, 5, 1
	v_lshl_or_b32 v22, v21, 10, v22
	v_and_b32_e32 v21, 31, v20
	v_lshl_or_b32 v22, v21, 5, v22
	v_lshrrev_b32_e32 v21, 4, v19
	v_lshl_or_b32 v22, v21, 11, v22
	v_and_b32_e32 v21, 15, v19
	v_lshl_or_b32 v22, v21, 1, v22
	v_mov_b32_e32 v23, v1
	v_lshl_add_u64 v[20:21], s[12:13], 0, v[22:23]
	v_cvt_pk_bf16_f32 v14, v14, s0
	flat_store_short v[20:21], v14
	v_add_co_u32_e32 v14, vcc, 0x20, v20
	v_cvt_pk_bf16_f32 v22, v15, s0
	s_nop 0
	v_addc_co_u32_e32 v15, vcc, 0, v21, vcc
	flat_store_short v[14:15], v22
	v_add_co_u32_e32 v14, vcc, 0x40, v20
	v_cvt_pk_bf16_f32 v16, v16, s0
	s_nop 0
	v_addc_co_u32_e32 v15, vcc, 0, v21, vcc
	flat_store_short v[14:15], v16
	v_add_co_u32_e32 v14, vcc, 0x60, v20
	v_cvt_pk_bf16_f32 v16, v17, s0
	s_nop 0
	v_addc_co_u32_e32 v15, vcc, 0, v21, vcc
	flat_store_short v[14:15], v16

; DI bf16_t f2bf(float a) { return (bf16_t)(pk2(a, 0.f) & 0xffffu); }
;   DI void store(int m, int n, float a, float b, float c, float d) const {
;     ...
;     if (n >= C_VS && n < C_KW) { int e = n - C_VS; bf16_t* p = vsT + ((size_t)(bb * 128 + e)) * SEQ + s; p[0] = f2bf(a); p[SEQ] = f2bf(b); p[2 * SEQ] = f2bf(c); p[3 * SEQ] = f2bf(d); }
;     else if (n >= C_VW && n < C_GATE) { int e = n - C_VW; bf16_t* p = vwT + ((size_t)(bb * 128 + e)) * SEQ + s; p[0] = f2bf(a); p[SEQ] = f2bf(b); p[2 * SEQ] = f2bf(c); p[3 * SEQ] = f2bf(d); }
.LBB0_602:
	s_or_b64 exec, exec, s[6:7]
	v_cmp_lt_i32_e32 vcc, s69, v152
	s_and_saveexec_b64 s[6:7], vcc
	s_xor_b64 s[6:7], exec, s[6:7]
	s_cbranch_execz .LBB0_604
	v_lshrrev_b32_e32 v14, 14, v68
	v_and_b32_e32 v16, 0x1c0, v14
	v_lshlrev_b32_e32 v16, 14, v16
	v_bfe_u32 v15, v14, 5, 1
	v_lshl_or_b32 v16, v15, 10, v16
	v_and_b32_e32 v15, 31, v14
	v_lshl_or_b32 v16, v15, 5, v16
	v_lshrrev_b32_e32 v15, 4, v19
	v_lshl_or_b32 v16, v15, 11, v16
	v_and_b32_e32 v15, 15, v19
	v_lshl_or_b32 v16, v15, 1, v16
	v_mov_b32_e32 v17, v1
	v_lshl_add_u64 v[14:15], s[12:13], 0, v[16:17]
	v_cvt_pk_bf16_f32 v10, v10, s0
	flat_store_short v[14:15], v10
	v_add_co_u32_e32 v10, vcc, 0x20, v14
	v_cvt_pk_bf16_f32 v16, v11, s0
	s_nop 0
	v_addc_co_u32_e32 v11, vcc, 0, v15, vcc
	flat_store_short v[10:11], v16
	v_add_co_u32_e32 v10, vcc, 0x40, v14
	v_cvt_pk_bf16_f32 v12, v12, s0
	s_nop 0
	v_addc_co_u32_e32 v11, vcc, 0, v15, vcc
	flat_store_short v[10:11], v12
	v_add_co_u32_e32 v10, vcc, 0x60, v14
	v_cvt_pk_bf16_f32 v12, v13, s0
	s_nop 0
	v_addc_co_u32_e32 v11, vcc, 0, v15, vcc
	flat_store_short v[10:11], v12

; DI bf16_t f2bf(float a) { return (bf16_t)(pk2(a, 0.f) & 0xffffu); }
; DI u32x2 pk4(float a, float b, float c, float d) { u32x2 r; r.x = pk2(a, b); r.y = pk2(c, d); return r; }
; template <class AF, class EF>
; DI void gemm_run(unsigned char* lds, int wv, const AF& af, const bf16_t* __restrict__ Bt, int ldb, int M, int N, int K, const EF& ef, int blk_off) {
;     ...
;         for (int k = 0; k < 4; ++k) {
;           auto r = __builtin_amdgcn_permlane16_swap(__float_as_uint(acc[2 * ip][j][k]), __float_as_uint(acc[2 * ip + 1][j][k]), false, false);
;           lo[k] = __uint_as_float(r[0]); hi[k] = __uint_as_float(r[1]);
;         }
;         int n = n0 + wn * 64 + (2 * ip + (q4 & 1)) * 16 + (q4 >> 1) * 8;
;         int m = m0 + wm * 128 + j * 16 + l15;
;         if (n < N) ef.store8(m, n, lo[0], lo[1], lo[2], lo[3], hi[0], hi[1], hi[2], hi[3]);
;   DI void store(int m, int n, float a, float b, float c, float d) const {
;     int bb = m >> 13, s = m & (SEQ - 1);
;     if (n >= C_VS && n < C_KW) { int e = n - C_VS; bf16_t* p = vsT + ((size_t)(bb * 128 + e)) * SEQ + s; p[0] = f2bf(a); p[SEQ] = f2bf(b); p[2 * SEQ] = f2bf(c); p[3 * SEQ] = f2bf(d); }
;     else if (n >= C_VW && n < C_GATE) { int e = n - C_VW; bf16_t* p = vwT + ((size_t)(bb * 128 + e)) * SEQ + s; p[0] = f2bf(a); p[SEQ] = f2bf(b); p[2 * SEQ] = f2bf(c); p[3 * SEQ] = f2bf(d); }
;     else *(u32x2*)(proj + (size_t)m * EIN + n) = pk4(a, b, c, d); }
.LBB0_609:
	s_or_b64 exec, exec, s[16:17]
	v_permlane16_swap_b32_e32 v2, v6
	v_permlane16_swap_b32_e32 v3, v7
	v_permlane16_swap_b32_e32 v4, v8
	v_permlane16_swap_b32_e32 v5, v9
	s_and_saveexec_b64 s[6:7], s[4:5]
	s_cbranch_execz .LBB0_259
	v_cmp_lt_i32_e32 vcc, s69, v152
	s_mov_b64 s[18:19], 0
	s_mov_b64 s[16:17], 0
	s_and_saveexec_b64 s[4:5], vcc
	s_xor_b64 s[4:5], exec, s[4:5]
	v_cmp_ne_u32_e32 vcc, s70, v152
	s_and_b64 s[18:19], vcc, exec
	s_mov_b64 s[16:17], exec
	s_or_saveexec_b64 s[20:21], s[4:5]
	v_cmp_ne_u32_e32 vcc, s71, v152
	s_xor_b64 exec, exec, s[20:21]
	v_cmp_eq_u32_e64 s[4:5], s71, v152
	s_andn2_b64 s[16:17], s[16:17], exec
	s_and_b64 s[4:5], s[4:5], exec
	s_or_b64 s[16:17], s[16:17], s[4:5]
	s_andn2_b64 s[4:5], s[18:19], exec
	s_and_b64 s[18:19], vcc, exec
	s_or_b64 s[18:19], s[4:5], s[18:19]
	s_or_b64 exec, exec, s[20:21]
	v_or_b32_e32 v10, 0x70, v153
	s_and_saveexec_b64 s[4:5], s[18:19]
	s_xor_b64 s[4:5], exec, s[4:5]
	s_cbranch_execz .LBB0_616
	v_readlane_b32 s18, v255, 24
	v_readlane_b32 s19, v255, 25
	v_cvt_pk_bf16_f32 v12, v2, v3
	v_cvt_pk_bf16_f32 v13, v4, v5
	v_mov_b64_e32 v[16:17], s[18:19]
	v_mad_i64_i32 v[16:17], s[18:19], v10, s87, v[16:17]
	v_cvt_pk_bf16_f32 v14, v6, v7
	v_cvt_pk_bf16_f32 v15, v8, v9
	v_lshl_add_u64 v[16:17], v[130:131], 1, v[16:17]
	s_andn2_b64 s[16:17], s[16:17], exec
	flat_store_dwordx4 v[16:17], v[12:15] offset:64
	v_subrev_u32_e32 v230, 0x2e0, v130
	v_lshrrev_b32_e32 v232, 7, v230
	v_cmp_eq_u32_e64 s[30:31], 0, v232
	s_and_saveexec_b64 s[36:37], s[30:31]
	v_readlane_b32 s80, v255, 24
	v_readlane_b32 s81, v255, 25
	v_lshrrev_b32_e32 v231, 13, v10
	v_lshlrev_b32_e32 v231, 20, v231
	v_lshrrev_b32_e32 v232, 6, v230
	v_lshl_or_b32 v231, v232, 19, v231
	v_bfe_u32 v232, v10, 6, 7
	v_lshl_or_b32 v231, v232, 12, v231
	v_bfe_u32 v232, v10, 5, 1
	v_lshl_or_b32 v231, v232, 11, v231
	v_bfe_u32 v232, v10, 2, 1
	v_lshl_or_b32 v231, v232, 10, v231
	v_bfe_u32 v232, v230, 5, 1
	v_lshl_or_b32 v231, v232, 9, v231
	v_bfe_u32 v232, v10, 3, 2
	v_lshl_or_b32 v231, v232, 7, v231
	v_bfe_u32 v232, v10, 0, 2
	v_lshl_or_b32 v231, v232, 5, v231
	v_and_b32_e32 v232, 31, v230
	v_or_b32_e32 v231, v231, v232
	v_add_u32_e32 v234, 0x9c00000, v231
	v_mov_b32_e32 v235, 0
	v_lshl_add_u64 v[236:237], v[234:235], 1, s[80:81]
	flat_store_dwordx4 v[236:237], v[12:15]
	s_or_b64 exec, exec, s[36:37]
	v_subrev_u32_e32 v230, 0x978, v130
	v_cmp_gt_u32_e64 s[30:31], 64, v230
	s_and_saveexec_b64 s[36:37], s[30:31]
	v_readlane_b32 s80, v255, 24
	v_readlane_b32 s81, v255, 25
	v_lshrrev_b32_e32 v231, 5, v10
	v_lshlrev_b32_e32 v231, 11, v231
	v_and_b32_e32 v232, 31, v10
	v_lshl_or_b32 v231, v232, 4, v231
	v_lshrrev_b32_e32 v232, 4, v230
	v_lshl_or_b32 v231, v232, 9, v231
	v_and_b32_e32 v232, 15, v230
	v_or_b32_e32 v231, v231, v232
	v_add_u32_e32 v234, 0x9000000, v231
	v_mov_b32_e32 v235, 0
	v_lshl_add_u64 v[236:237], v[234:235], 1, s[80:81]
	flat_store_dwordx4 v[236:237], v[12:15]
	s_or_b64 exec, exec, s[36:37]
.LBB0_616:
	s_or_b64 exec, exec, s[4:5]
	s_and_b64 exec, exec, s[16:17]
	s_cbranch_execz .LBB0_259
	v_and_b32_e32 v11, 0x1fff, v10
	v_cmp_lt_i32_e32 vcc, s69, v152
	s_and_saveexec_b64 s[4:5], vcc
	s_xor_b64 s[4:5], exec, s[4:5]
	s_cbranch_execz .LBB0_619
	v_lshrrev_b32_e32 v12, 14, v72
	v_and_b32_e32 v0, 0x1c0, v12
	v_lshlrev_b32_e32 v0, 14, v0
	v_bfe_u32 v13, v12, 5, 1
	v_lshl_or_b32 v0, v13, 10, v0
	v_and_b32_e32 v13, 31, v12
	v_lshl_or_b32 v0, v13, 5, v0
	v_lshrrev_b32_e32 v13, 4, v11
	v_lshl_or_b32 v0, v13, 11, v0
	v_and_b32_e32 v13, 15, v11
	v_lshl_or_b32 v0, v13, 1, v0
	v_lshl_add_u64 v[12:13], s[12:13], 0, v[0:1]
	v_cvt_pk_bf16_f32 v0, v2, s0
	v_add_co_u32_e32 v2, vcc, 0x20, v12
	flat_store_short v[12:13], v0
	v_cvt_pk_bf16_f32 v0, v3, s0
	v_addc_co_u32_e32 v3, vcc, 0, v13, vcc
	flat_store_short v[2:3], v0
	v_add_co_u32_e32 v2, vcc, 0x40, v12
	v_cvt_pk_bf16_f32 v0, v4, s0
	s_nop 0
	v_addc_co_u32_e32 v3, vcc, 0, v13, vcc
	flat_store_short v[2:3], v0
	v_add_co_u32_e32 v2, vcc, 0x60, v12
	v_cvt_pk_bf16_f32 v0, v5, s0
	s_nop 0
	v_addc_co_u32_e32 v3, vcc, 0, v13, vcc
	flat_store_short v[2:3], v0

; DI bf16_t f2bf(float a) { return (bf16_t)(pk2(a, 0.f) & 0xffffu); }
;   DI void store(int m, int n, float a, float b, float c, float d) const {
;     ...
;     if (n >= C_VS && n < C_KW) { int e = n - C_VS; bf16_t* p = vsT + ((size_t)(bb * 128 + e)) * SEQ + s; p[0] = f2bf(a); p[SEQ] = f2bf(b); p[2 * SEQ] = f2bf(c); p[3 * SEQ] = f2bf(d); }
;     else if (n >= C_VW && n < C_GATE) { int e = n - C_VW; bf16_t* p = vwT + ((size_t)(bb * 128 + e)) * SEQ + s; p[0] = f2bf(a); p[SEQ] = f2bf(b); p[2 * SEQ] = f2bf(c); p[3 * SEQ] = f2bf(d); }
.LBB0_625:
	s_or_b64 exec, exec, s[4:5]
	v_cmp_lt_i32_e32 vcc, s69, v152
	s_and_saveexec_b64 s[4:5], vcc
	s_xor_b64 s[4:5], exec, s[4:5]
	s_cbranch_execz .LBB0_627
	v_lshrrev_b32_e32 v2, 14, v68
	v_and_b32_e32 v0, 0x1c0, v2
	v_lshlrev_b32_e32 v0, 14, v0
	v_bfe_u32 v3, v2, 5, 1
	v_lshl_or_b32 v0, v3, 10, v0
	v_and_b32_e32 v3, 31, v2
	v_lshl_or_b32 v0, v3, 5, v0
	v_lshrrev_b32_e32 v3, 4, v11
	v_lshl_or_b32 v0, v3, 11, v0
	v_and_b32_e32 v3, 15, v11
	v_lshl_or_b32 v0, v3, 1, v0
	v_lshl_add_u64 v[2:3], s[12:13], 0, v[0:1]
	v_cvt_pk_bf16_f32 v0, v6, s0
	v_add_co_u32_e32 v4, vcc, 0x20, v2
	flat_store_short v[2:3], v0
	v_cvt_pk_bf16_f32 v0, v7, s0
	v_addc_co_u32_e32 v5, vcc, 0, v3, vcc
	flat_store_short v[4:5], v0
	v_add_co_u32_e32 v4, vcc, 0x40, v2
	v_cvt_pk_bf16_f32 v0, v8, s0
	s_nop 0
	v_addc_co_u32_e32 v5, vcc, 0, v3, vcc
	v_add_co_u32_e32 v2, vcc, 0x60, v2
	flat_store_short v[4:5], v0
	v_cvt_pk_bf16_f32 v0, v9, s0
	v_addc_co_u32_e32 v3, vcc, 0, v3, vcc
	flat_store_short v[2:3], v0

; template <class T> DI T* opqp(T* p) { unsigned long long v = (unsigned long long)p; asm volatile("" : "+s"(v)); return (T*)v; }
; DI int tid_of(int wave_s) { unsigned z = 0; asm volatile("" : "+s"(z)); int l = __builtin_amdgcn_mbcnt_hi(~0u, __builtin_amdgcn_mbcnt_lo(~0u, z)); return wave_s * 64 + l; }
; DI int pi_row(int r) { return (r & 0x13) | ((r & 4) << 1) | ((r & 8) >> 1); }
; #define P kparams()
; DI void nsa_phase(unsigned char* lds, KParamPtr P, int wv) {
;   unsigned char* wsq = opqp(P->ws);
;   const float* tab = (const float*)(lds + LDS_TAB);
;   const int tid = tid_of(wv), lane = tid & 63, wave = tid >> 6, l31 = lane & 31, hh = lane >> 5;
;   unsigned char* selL = lds + LDS_WORK + wave * 512;
;   float* scw = (float*)(lds + LDS_WORK + 4096 + wave * 16384);
;   const bf16_t* proj = (const bf16_t*)(wsq + OFF_U + U_PROJ);
;   const bf16_t* vsT = (const bf16_t*)(wsq + OFF_U + U_VST);
;   const bf16_t* vwT = (const bf16_t*)(wsq + OFF_U + U_VWT);
;   const bf16_t* kc = (const bf16_t*)(wsq + OFF_MISC + MS_KC);
;   const bf16_t* vcT = (const bf16_t*)(wsq + OFF_MISC + MS_VCT);
;   float* part = (float*)(wsq + OFF_HB);
;   bf16_t* ao = (bf16_t*)(wsq + OFF_AO);
;   const int nw = gridDim.x * 8, gw = blockIdx.x * 8 + wave;
;   const int pr = pi_row(l31);
;   for (int it = gw; it < 2048; it += nw) {
;     const int blk_ = it >> 3, combo_ = blk_ & 7;
;     const int b = combo_ >> 1, g = combo_ & 1, tile = ((blk_ >> 3) << 3) + (it & 7), t0 = tile * 32, t = t0 + l31;
;     const size_t tok = (size_t)b * SEQ + t;
;     const bf16_t* kcb = kc + (size_t)((b * 2 + g) * 512) * 64;
;     const bf16_t* vcb = vcT + (size_t)((b * 2 + g) * 64) * 512;
;     ...
;         const unsigned kwo = (unsigned)((b * SEQ + s_lo + pr) * EIN + C_KW + g * 64 + hh * 8);
;         const unsigned vwo = (unsigned)(((b * 2 + g) * 64 + l31) * SEQ + s_lo + hh * 8);
.LBB0_933:
	s_or_b64 exec, exec, s[4:5]
	s_mov_b64 s[4:5], s[64:65]
	s_barrier
	s_load_dwordx2 s[6:7], s[4:5], 0xc8
	s_mov_b32 s2, s89
	s_waitcnt lgkmcnt(0)
	v_readlane_b32 s4, v254, 0
	v_mbcnt_lo_u32_b32 v0, -1, s2
	v_mbcnt_hi_u32_b32 v4, -1, v0
	v_add_u32_e32 v3, s4, v4
	v_ashrrev_i32_e32 v2, 6, v3
	v_readlane_b32 s2, v254, 33
	v_readlane_b32 s5, v254, 1
	s_nop 0
	v_add_u32_e32 v165, s2, v2
	s_movk_i32 s2, 0x800
	v_cmp_gt_i32_e32 vcc, s2, v165
	s_and_saveexec_b64 s[18:19], vcc
	s_cbranch_execz .LBB0_1158
	v_lshlrev_b32_e32 v6, 1, v4
	v_lshrrev_b32_e32 v8, 1, v4
	v_lshl_add_u32 v164, v2, 9, 0
	v_and_b32_e32 v0, 19, v4
	v_and_b32_e32 v6, 8, v6
	v_and_b32_e32 v7, 4, v8
	s_movk_i32 s2, 0x3e00
	v_and_b32_e32 v5, 63, v4
	s_add_u32 s20, s6, 0x8000000
	v_or3_b32 v224, v7, v0, v6
	v_mad_u64_u32 v[6:7], s[4:5], v2, s2, v[164:165]
	v_and_b32_e32 v222, 31, v4
	v_bfe_u32 v223, v4, 5, 1
	s_addc_u32 s21, s7, 0
	v_lshlrev_b32_e32 v7, 2, v5
	v_cmp_gt_u32_e64 s[4:5], 32, v5
	v_and_b32_e32 v11, 15, v4
	v_bfe_u32 v229, v4, 2, 2
	v_and_b32_e32 v230, 3, v4
	v_and_b32_e32 v170, 24, v8
	v_mov_b32_e32 v171, v1
	v_and_b32_e32 v4, 48, v4
	v_mov_b32_e32 v5, v1
	v_lshlrev_b32_e32 v0, 4, v223
	v_lshl_add_u64 v[172:173], s[20:21], 0, v[4:5]
	v_lshl_add_u64 v[174:175], s[6:7], 0, v[4:5]
	v_lshl_add_u64 v[4:5], s[6:7], 0, v[170:171]
	s_mov_b64 s[8:9], 0x4000000
	v_lshl_add_u64 v[176:177], v[4:5], 0, s[8:9]
	v_lshl_or_b32 v4, v224, 7, v0
	v_mov_b32_e32 v5, v1
	s_add_u32 s22, s6, 0x11e00000
	v_lshl_add_u64 v[166:167], s[20:21], 0, v[0:1]
	v_lshlrev_b32_e32 v10, 2, v222
	v_lshl_add_u64 v[168:169], s[6:7], 0, v[0:1]
	v_lshl_add_u64 v[4:5], s[6:7], 0, v[4:5]
	s_mov_b64 s[8:9], 0x1a600000
	v_lshl_or_b32 v0, v222, 10, v0
	s_addc_u32 s23, s7, 0
	v_add_u32_e32 v225, v6, v7
	v_add_u32_e32 v226, v6, v10
	v_lshlrev_b32_e32 v6, 8, v223
	v_bfe_u32 v171, v3, 6, 3
	v_lshl_add_u64 v[178:179], v[4:5], 0, s[8:9]
	v_lshlrev_b32_e32 v3, 7, v223
	v_lshl_add_u64 v[4:5], s[6:7], 0, v[0:1]
	v_lshlrev_b32_e32 v0, 14, v2
	v_lshlrev_b32_e32 v9, 3, v223
	v_xor_b32_e32 v227, 0x80, v7
	v_lshlrev_b32_e32 v7, 4, v222
	v_sub_u32_e32 v234, v222, v3
	v_lshlrev_b32_e32 v3, 10, v171
	s_mov_b64 s[8:9], 0x1a708020
	v_or3_b32 v0, v0, v6, v10
	v_readlane_b32 s2, v255, 9
	s_add_u32 s24, s6, 0x12600c00
	v_lshlrev_b32_e32 v228, 1, v223
	v_or_b32_e32 v232, 0x400, v9
	v_or_b32_e32 v233, 0x300, v170
	v_add_u32_e32 v235, 0xfffffdf1, v3
	v_lshl_add_u64 v[180:181], v[4:5], 0, s[8:9]
	v_add_u32_e32 v236, s2, v0
	v_or_b32_e32 v237, 31, v3
	v_sub_u32_e32 v238, v222, v9
	s_addc_u32 s25, s7, 0
	v_lshl_or_b32 v239, v222, 13, v9
	s_mov_b64 s[26:27], 0
	v_add_u32_e32 v240, v164, v7
	v_lshlrev_b32_e32 v241, 5, v11
	s_branch .LBB0_936

; DI void nsa_phase(unsigned char* lds, KParamPtr P, int wv) {
;     ...
;       const int s_lo = t0 >= 512 ? t0 - 512 : 0;
;       const int nwt = (t0 + 32 - s_lo) >> 5;
; #pragma unroll 1
;       for (int hp = 0; hp < 4; ++hp) {
;         const int head = g * 4 + hp;
;         const float* tabh = tab + head * 128;
;         bf16x8 qf[4];
; #pragma unroll
;         for (int ks = 0; ks < 4; ++ks) qf[ks] = ldg8(proj + tok * EIN + C_NQ + head * 64 + ks * 16 + hh * 8);
;         f32x16 O[2]; O[0] = zero16(); O[1] = zero16();
;         float m = NEGB, l = 0.f;
;         bf16x8 kf[4];
;         const unsigned kwo = (unsigned)((b * SEQ + s_lo + pr) * EIN + C_KW + g * 64 + hh * 8);
;         const unsigned vwo = (unsigned)(((b * 2 + g) * 64 + l31) * SEQ + s_lo + hh * 8);
; #pragma unroll
;         for (int ks = 0; ks < 4; ++ks) kf[ks] = ldg8(proj + kwo + ks * 16);
.LBB0_1030:
	s_and_saveexec_b64 s[6:7], s[4:5]
	ds_write_b128 v240, v[2:5] offset:8192
	s_or_b64 exec, exec, s[6:7]
	v_add_u32_e32 v0, 0xfffffe00, v242
	v_cmp_lt_i32_e32 vcc, 15, v244
	v_lshlrev_b32_e32 v244, 6, v245
	v_lshlrev_b32_e32 v245, 19, v163
	v_cndmask_b32_e32 v4, 0, v0, vcc
	v_sub_u32_e32 v0, v242, v4
	v_add_u32_e32 v0, 32, v0
	v_ashrrev_i32_e32 v248, 5, v0
	v_add_u32_e32 v0, v4, v182
	v_or_b32_e32 v2, v0, v224
	v_or_b32_e32 v0, v244, v232
	v_mad_u64_u32 v[2:3], s[6:7], v2, s74, v[0:1]
	v_add_u32_e32 v0, v237, v246
	v_mov_b32_e32 v3, v1
	v_sub_u32_e32 v246, v0, v4
	v_lshrrev_b32_e32 v0, 4, v4
	v_lshlrev_b32_e32 v0, 10, v0
	v_lshl_add_u32 v0, v222, 4, v0
	v_and_b32_e32 v198, 8, v232
	v_add3_u32 v0, v0, v198, v245
	s_mov_b32 s16, 0
	v_lshl_add_u64 v[190:191], v[2:3], 1, s[20:21]
	v_cmp_lt_i32_e64 s[6:7], 0, v248
	v_add_u32_e32 v249, 31, v4
	v_lshl_add_u64 v[192:193], v[0:1], 1, s[24:25]
	s_branch .LBB0_1035

; #define MFMA32(a, b, c) __builtin_amdgcn_mfma_f32_32x32x16_bf16((a), (b), (c), 0, 0, 0)
; DI float ex2(float x) { return __builtin_amdgcn_exp2f(x); }
; DI float red_max32(float x) { auto r = __builtin_amdgcn_permlane32_swap(__float_as_uint(x), __float_as_uint(x), false, false); return fmaxf(__uint_as_float(r[0]), __uint_as_float(r[1])); }
; DI void nsa_phase(unsigned char* lds, KParamPtr P, int wv) {
;     ...
;         for (int wt = 0; wt < nwt; ++wt) {
;           const int s0 = s_lo + wt * 32;
;           bf16x8 vf[4];
; #pragma unroll
;           for (int st = 0; st < 2; ++st)
; #pragma unroll
;             for (int et = 0; et < 2; ++et) vf[st * 2 + et] = ldg8(vwT + vwo + (unsigned)(et * 32 * SEQ + wt * 32 + st * 16));
;           f32x16 s = zero16();
; #pragma unroll
;           for (int ks = 0; ks < 4; ++ks) s = MFMA32(kf[ks], qf[ks], s);
;           {
;             const int wn_ = wt + 1 < nwt ? wt + 1 : wt;
; #pragma unroll
;             for (int ks = 0; ks < 4; ++ks) kf[ks] = ldg8(proj + kwo + (unsigned)(wn_ * 32 * EIN + ks * 16));
;     ...
;           mloc = red_max32(mloc);
;           const float mn = fmaxf(m, mloc);
;           const float alpha = ex2(m - mn);
;           float ls = 0.f;
; #pragma unroll
;           for (int i = 0; i < 16; ++i) { float p = (s[i] > -1e29f) ? ex2(s[i] - mn) : 0.f; s[i] = p; ls += p; }
;           l = l * alpha + ls; m = mn;
; #pragma unroll
;           for (int et = 0; et < 2; ++et)
; #pragma unroll
;             for (int i = 0; i < 16; ++i) O[et][i] *= alpha;
; #pragma unroll
;           for (int st = 0; st < 2; ++st) {
;             bf16x8 pf = pack8(s, st);
; #pragma unroll
;             for (int et = 0; et < 2; ++et) O[et] = MFMA32(vf[st * 2 + et], pf, O[et]);
;           }
.LBB0_1037:
	s_or_b64 exec, exec, s[8:9]
	v_mov_b32_e32 v34, v0
	s_nop 1
	v_permlane32_swap_b32_e32 v0, v34
	v_max3_f32 v34, v219, v0, v34
	v_sub_f32_e32 v35, v198, v34
	v_exp_f32_e32 v35, v35
	v_cmp_lt_f32_e32 vcc, s62, v198
	v_sub_f32_e32 v0, v219, v34
	v_exp_f32_e32 v0, v0
	v_cndmask_b32_e32 v36, 0, v35, vcc
	v_sub_f32_e32 v35, v199, v34
	v_exp_f32_e32 v35, v35
	v_cmp_lt_f32_e32 vcc, s62, v199
	v_pk_mul_f32 v[32:33], v[32:33], v[0:1] op_sel_hi:[1,0]
	v_pk_mul_f32 v[30:31], v[30:31], v[0:1] op_sel_hi:[1,0]
	v_cndmask_b32_e32 v37, 0, v35, vcc
	v_sub_f32_e32 v35, v200, v34
	v_exp_f32_e32 v35, v35
	v_cmp_lt_f32_e32 vcc, s62, v200
	v_pk_mul_f32 v[28:29], v[28:29], v[0:1] op_sel_hi:[1,0]
	v_pk_mul_f32 v[26:27], v[26:27], v[0:1] op_sel_hi:[1,0]
	v_cndmask_b32_e32 v38, 0, v35, vcc
	v_sub_f32_e32 v35, v201, v34
	v_exp_f32_e32 v35, v35
	v_cmp_lt_f32_e32 vcc, s62, v201
	v_pk_mul_f32 v[24:25], v[24:25], v[0:1] op_sel_hi:[1,0]
	v_pk_mul_f32 v[22:23], v[22:23], v[0:1] op_sel_hi:[1,0]
	v_cndmask_b32_e32 v39, 0, v35, vcc
	v_sub_f32_e32 v35, v202, v34
	v_exp_f32_e32 v35, v35
	v_cmp_lt_f32_e32 vcc, s62, v202
	v_pk_mul_f32 v[20:21], v[20:21], v[0:1] op_sel_hi:[1,0]
	v_pk_mul_f32 v[18:19], v[18:19], v[0:1] op_sel_hi:[1,0]
	v_cndmask_b32_e32 v40, 0, v35, vcc
	v_sub_f32_e32 v35, v203, v34
	v_exp_f32_e32 v35, v35
	v_cmp_lt_f32_e32 vcc, s62, v203
	v_pk_mul_f32 v[16:17], v[16:17], v[0:1] op_sel_hi:[1,0]
	v_pk_mul_f32 v[14:15], v[14:15], v[0:1] op_sel_hi:[1,0]
	v_cndmask_b32_e32 v41, 0, v35, vcc
	v_sub_f32_e32 v35, v204, v34
	v_exp_f32_e32 v35, v35
	v_cmp_lt_f32_e32 vcc, s62, v204
	v_pk_mul_f32 v[12:13], v[12:13], v[0:1] op_sel_hi:[1,0]
	v_pk_mul_f32 v[10:11], v[10:11], v[0:1] op_sel_hi:[1,0]
	v_cndmask_b32_e32 v42, 0, v35, vcc
	v_sub_f32_e32 v35, v205, v34
	v_exp_f32_e32 v35, v35
	v_cmp_lt_f32_e32 vcc, s62, v205
	v_pk_mul_f32 v[8:9], v[8:9], v[0:1] op_sel_hi:[1,0]
	v_pk_mul_f32 v[6:7], v[6:7], v[0:1] op_sel_hi:[1,0]
	v_cndmask_b32_e32 v43, 0, v35, vcc
	v_sub_f32_e32 v35, v206, v34
	v_exp_f32_e32 v35, v35
	v_cmp_lt_f32_e32 vcc, s62, v206
	v_pk_mul_f32 v[4:5], v[4:5], v[0:1] op_sel_hi:[1,0]
	v_pk_mul_f32 v[2:3], v[2:3], v[0:1] op_sel_hi:[1,0]
	v_cndmask_b32_e32 v44, 0, v35, vcc
	v_sub_f32_e32 v35, v207, v34
	v_exp_f32_e32 v35, v35
	v_cmp_lt_f32_e32 vcc, s62, v207
	v_subrev_u32_e32 v252, 32, v252
	v_add_u32_e32 v251, 32, v251
	v_cndmask_b32_e32 v45, 0, v35, vcc
	v_add_co_u32_e32 v196, vcc, 0x1000, v196
	v_addc_co_u32_e32 v197, vcc, 0, v197, vcc
	v_sub_f32_e32 v35, v208, v34
	v_exp_f32_e32 v35, v35
	v_cmp_lt_f32_e32 vcc, s62, v208
	v_mov_b32_e32 v219, v34
	v_cndmask_b32_e32 v46, 0, v35, vcc
	v_sub_f32_e32 v35, v209, v34
	v_exp_f32_e32 v35, v35
	v_cmp_lt_f32_e32 vcc, s62, v209
	s_nop 1
	v_cndmask_b32_e32 v47, 0, v35, vcc
	v_sub_f32_e32 v35, v210, v34
	v_exp_f32_e32 v35, v35
	v_cmp_lt_f32_e32 vcc, s62, v210
	s_nop 1
	v_cndmask_b32_e32 v48, 0, v35, vcc
	v_sub_f32_e32 v35, v211, v34
	v_exp_f32_e32 v35, v35
	v_cmp_lt_f32_e32 vcc, s62, v211
	s_nop 1
	v_cndmask_b32_e32 v49, 0, v35, vcc
	v_sub_f32_e32 v35, v212, v34
	v_exp_f32_e32 v35, v35
	v_cmp_lt_f32_e32 vcc, s62, v212
	s_nop 1
	v_cndmask_b32_e32 v198, 0, v35, vcc
	v_sub_f32_e32 v35, v213, v34
	v_exp_f32_e32 v35, v35
	v_cmp_lt_f32_e32 vcc, s62, v213
	s_nop 1
	v_cndmask_b32_e32 v199, 0, v35, vcc
	v_add_f32_e32 v35, 0, v36
	v_add_f32_e32 v35, v37, v35
	v_add_f32_e32 v35, v38, v35
	v_add_f32_e32 v35, v39, v35
	v_cvt_pk_bf16_f32 v36, v36, v37
	v_cvt_pk_bf16_f32 v37, v38, v39
	v_cvt_pk_bf16_f32 v38, v40, v41
	v_cvt_pk_bf16_f32 v39, v42, v43
	v_add_f32_e32 v35, v40, v35
	v_add_f32_e32 v35, v41, v35
	s_waitcnt vmcnt(0) lgkmcnt(0)
	v_mfma_f32_32x32x16_bf16 v[18:33], v[158:161], v[36:39], v[18:33]
	v_add_f32_e32 v35, v42, v35
	v_add_f32_e32 v35, v43, v35
	v_add_f32_e32 v35, v44, v35
	v_add_f32_e32 v35, v45, v35
	v_add_f32_e32 v35, v46, v35
	v_add_f32_e32 v35, v47, v35
	v_add_f32_e32 v35, v48, v35
	v_mfma_f32_32x32x16_bf16 v[2:17], v[154:157], v[36:39], v[2:17]
	v_cvt_pk_bf16_f32 v36, v44, v45
	v_cvt_pk_bf16_f32 v37, v46, v47
	v_cvt_pk_bf16_f32 v38, v48, v49
	v_cvt_pk_bf16_f32 v39, v198, v199
	v_add_f32_e32 v35, v49, v35
	v_add_f32_e32 v35, v198, v35
	v_add_f32_e32 v35, v199, v35
	v_mfma_f32_32x32x16_bf16 v[18:33], v[150:153], v[36:39], v[18:33]
	v_fmac_f32_e32 v35, v253, v0
	v_cmp_eq_u32_e32 vcc, s17, v248
	s_or_b64 s[12:13], vcc, s[12:13]
	v_mov_b32_e32 v253, v35
	v_mfma_f32_32x32x16_bf16 v[2:17], v[146:149], v[36:39], v[2:17]
	s_andn2_b64 exec, exec, s[12:13]
	s_cbranch_execz .LBB0_1033
.LBB0_1038:
	s_waitcnt vmcnt(0) lgkmcnt(0)
	v_mfma_f32_32x32x16_bf16 v[34:49], v[142:145], v[114:117], 0
	s_mov_b32 s8, 0xfffff400
	v_add_co_u32_e32 v142, vcc, s8, v196
	s_mov_b32 s8, 0xfffffc00
	s_nop 0
	v_addc_co_u32_e32 v143, vcc, -1, v197, vcc
	v_add_co_u32_e32 v144, vcc, 0xfffff800, v196
	v_mfma_f32_32x32x16_bf16 v[34:49], v[138:141], v[118:121], v[34:49]
	s_nop 0
	v_addc_co_u32_e32 v145, vcc, -1, v197, vcc
	v_add_co_u32_e32 v138, vcc, s8, v196
	s_mov_b32 s2, s17
	s_nop 0
	v_addc_co_u32_e32 v139, vcc, -1, v197, vcc
	v_mfma_f32_32x32x16_bf16 v[34:49], v[134:137], v[122:125], v[34:49]
	s_add_i32 s17, s17, 1
	v_mov_b32_e32 v0, s2
	v_mov_b32_e32 v134, s17
	v_cmp_lt_i32_e32 vcc, s17, v248
	s_mov_b32 s2, 0x13c00
	flat_load_dwordx4 v[158:161], v[142:143]
	flat_load_dwordx4 v[154:157], v[144:145]
	v_cndmask_b32_e32 v0, v0, v134, vcc
	v_mul_lo_u32 v0, v0, s2
	v_lshl_add_u64 v[198:199], v[0:1], 1, v[190:191]
	flat_load_dwordx4 v[150:153], v[138:139]
	flat_load_dwordx4 v[146:149], v[196:197]
	flat_load_dwordx4 v[142:145], v[198:199]
	s_nop 0
	flat_load_dwordx4 v[138:141], v[198:199] offset:32
	v_mfma_f32_32x32x16_bf16 v[34:49], v[130:133], v[126:129], v[34:49]
	flat_load_dwordx4 v[134:137], v[198:199] offset:64
	flat_load_dwordx4 v[130:133], v[198:199] offset:96
	v_cmp_gt_i32_e32 vcc, v251, v242
	v_cmp_lt_i32_e64 s[8:9], s1, v252
	v_subrev_u32_e32 v0, 62, v252
	s_or_b64 s[8:9], vcc, s[8:9]
	v_cmp_gt_i32_e32 vcc, s91, v0
	s_or_b64 s[8:9], s[8:9], vcc
	s_and_saveexec_b64 s[14:15], s[8:9]
	s_xor_b64 s[8:9], exec, s[14:15]
	s_cbranch_execz .LBB0_1072
	v_add_u32_e32 v0, v238, v252
	v_subrev_u32_e32 v200, 31, v0
	v_cmp_gt_u32_e32 vcc, s34, v200
	v_mov_b32_e32 v199, 0xf149f2ca
	v_mov_b32_e32 v198, 0xf149f2ca
	s_and_saveexec_b64 s[14:15], vcc
	s_cbranch_execz .LBB0_1041
	v_min_u32_e32 v198, 0x7f, v200
	v_lshl_add_u32 v198, v198, 2, v163
	ds_read_b32 v198, v198
	s_waitcnt lgkmcnt(0)
	v_fmac_f32_e32 v198, 0x3e38aa3b, v34

; DI void nsa_phase(unsigned char* lds, KParamPtr P, int wv) {
;     ...
;       const int col = lane & 15, q4 = lane >> 4;
;       const int qq = col >> 2, hcol = g * 4 + (col & 3);
;       const float* tabc = tab + hcol * 128;
;       const int rk = 8 * (col >> 2) + (col & 3);
;       const unsigned kbase = (unsigned)((b * SEQ + rk) * EIN + C_KS + g * 64 + q4 * 8);
;       const unsigned vbase = (unsigned)(((b * 2 + g) * 64 + col) * SEQ + q4 * 8);
; #pragma unroll 1
;       for (int grp_ = 0; grp_ < 8 * REP_C; ++grp_) {
;         const int grp = grp_ & 7;
;         const int tq = t0 + grp * 4 + qq;
;         const int tmin = t0 + grp * 4, tmax = tmin + 3;
;         const size_t tokq = (size_t)b * SEQ + tq;
;         const u32x4 mym = *(const u32x4*)(selL + (grp * 4 + qq) * 16);
.LBB0_1074:
	v_lshl_or_b32 v0, v229, 3, v230
	v_or_b32_e32 v4, v243, v230
	v_or_b32_e32 v0, v182, v0
	v_or_b32_e32 v2, v244, v233
	v_lshl_add_u32 v123, v229, 7, v245
	v_lshl_add_u32 v123, v230, 5, v123
	v_add_u32_e32 v123, v123, v170
	v_add_u32_e32 v123, 0x9c00000, v123
	v_lshlrev_b32_e32 v0, 7, v4
	v_lshl_add_u64 v[46:47], v[172:173], 0, v[0:1]
	v_lshl_add_u64 v[116:117], v[176:177], 0, v[0:1]
	v_add_u32_e32 v0, 0xffffffa0, v247
	v_mul_u32_u24_e32 v2, 3, v4
	v_lshl_add_u32 v0, 2, v0, -1
	v_cmp_gt_u32_e32 vcc, s91, v247
	v_lshlrev_b32_e32 v2, 1, v2
	v_mov_b32_e32 v3, v1
	v_cndmask_b32_e32 v125, -1, v0, vcc
	v_subrev_u32_e32 v0, 64, v247
	v_lshl_add_u64 v[48:49], s[20:21], 0, v[2:3]
	v_lshlrev_b32_e32 v2, 8, v4
	s_movk_i32 s2, 0x5e
	v_lshl_add_u32 v126, 2, v0, -1
	v_subrev_u32_e32 v0, 32, v247
	v_lshl_add_u32 v122, v4, 9, 0
	v_or3_b32 v124, v245, v241, v170
	v_cmp_lt_i32_e64 s[6:7], 30, v247
	v_lshl_add_u64 v[114:115], v[174:175], 0, v[2:3]
	v_cmp_lt_u32_e64 s[8:9], 62, v247
	v_cmp_lt_u32_e64 s[10:11], s2, v247
	v_lshl_add_u32 v127, 2, v0, -1
	v_lshl_add_u32 v128, 2, v247, -1
	s_mov_b32 s38, 0
	s_waitcnt lgkmcnt(0)
	s_branch .LBB0_1077

; DI void nsa_phase(unsigned char* lds, KParamPtr P, int wv) {
;     ...
;         auto load_k = [&](int jb) {
;           const unsigned ko = kbase + (unsigned)(jb * 64 * EIN);
; #pragma unroll
;           for (int hf = 0; hf < 2; ++hf)
; #pragma unroll
;             for (int tl = 0; tl < 2; ++tl) {
;               kf[(hf * 2 + tl) * 2 + 0] = ldg8(proj + ko + (unsigned)((hf * 32 + 4 * tl) * EIN));
;               kf[(hf * 2 + tl) * 2 + 1] = ldg8(proj + ko + (unsigned)((hf * 32 + 4 * tl) * EIN + 32));
;             }
;         };
;         auto load_v = [&](int jb) {
;           const unsigned vo = vbase + (unsigned)(jb * 64);
; #pragma unroll
;           for (int hf = 0; hf < 2; ++hf)
; #pragma unroll
;             for (int e = 0; e < 4; ++e) vf[hf * 4 + e] = ldg8(vsT + vo + (unsigned)(e * 16 * SEQ + hf * 32));
;         };
;         int jb = next_blk();
;         if (jb >= 0) { load_k(jb); load_v(jb); }
.LBB0_1092:
	v_lshl_add_u32 v0, v136, 12, v123
	v_lshl_add_u64 v[14:15], v[0:1], 1, s[20:21]
	v_add_co_u32_e32 v16, vcc, 0, v14
	flat_load_dwordx4 v[50:53], v[14:15]
	flat_load_dwordx4 v[54:57], v[14:15] offset:1024
	v_addc_co_u32_e32 v17, vcc, 0, v15, vcc
	flat_load_dwordx4 v[58:61], v[16:17] offset:2048
	flat_load_dwordx4 v[62:65], v[16:17] offset:3072
	v_add_co_u32_e32 v16, vcc, 0x1000, v14
	v_lshlrev_b32_e32 v0, 12, v136
	s_nop 0
	v_addc_co_u32_e32 v17, vcc, 0, v15, vcc
	v_add_co_u32_e32 v14, vcc, 0x1000, v14
	v_add_lshl_u32 v0, v0, v124, 1
	s_nop 0
	v_addc_co_u32_e32 v15, vcc, 0, v15, vcc
	flat_load_dwordx4 v[66:69], v[16:17]
	flat_load_dwordx4 v[70:73], v[16:17] offset:1024
	flat_load_dwordx4 v[74:77], v[14:15] offset:2048
	flat_load_dwordx4 v[78:81], v[14:15] offset:3072
	v_lshl_add_u64 v[14:15], s[22:23], 0, v[0:1]
	v_add_co_u32_e32 v16, vcc, 0x800, v14
	s_nop 1
	v_addc_co_u32_e32 v17, vcc, 0, v15, vcc
	v_add_co_u32_e32 v18, vcc, 0x1000, v14
	s_nop 1
	v_addc_co_u32_e32 v19, vcc, 0, v15, vcc
	v_add_co_u32_e32 v20, vcc, 0x1800, v14
	s_nop 1
	v_addc_co_u32_e32 v21, vcc, 0, v15, vcc
	flat_load_dwordx4 v[82:85], v[14:15]
	flat_load_dwordx4 v[86:89], v[14:15] offset:1024
	flat_load_dwordx4 v[94:97], v[16:17]
	flat_load_dwordx4 v[90:93], v[16:17] offset:1024
	flat_load_dwordx4 v[102:105], v[18:19]
	flat_load_dwordx4 v[98:101], v[18:19] offset:1024
	flat_load_dwordx4 v[110:113], v[20:21]
	flat_load_dwordx4 v[106:109], v[20:21] offset:1024

; DI void nsa_phase(unsigned char* lds, KParamPtr P, int wv) {
;     ...
;         auto load_k = [&](int jb) {
;           const unsigned ko = kbase + (unsigned)(jb * 64 * EIN);
; #pragma unroll
;           for (int hf = 0; hf < 2; ++hf)
; #pragma unroll
;             for (int tl = 0; tl < 2; ++tl) {
;               kf[(hf * 2 + tl) * 2 + 0] = ldg8(proj + ko + (unsigned)((hf * 32 + 4 * tl) * EIN));
;               kf[(hf * 2 + tl) * 2 + 1] = ldg8(proj + ko + (unsigned)((hf * 32 + 4 * tl) * EIN + 32));
;             }
;         };
;     ...
;           const int jn = next_blk();
;           if (jn >= 0) load_k(jn);
.LBB0_1108:
	s_or_b64 exec, exec, s[12:13]
	v_cmp_lt_i32_e64 s[14:15], -1, v134
	v_cmp_gt_i32_e64 s[12:13], 0, v134
	s_and_saveexec_b64 s[16:17], s[14:15]
	s_cbranch_execz .LBB0_1110
	v_lshl_add_u32 v0, v134, 12, v123
	v_lshl_add_u64 v[74:75], v[0:1], 1, s[20:21]
	v_add_co_u32_e32 v62, vcc, 0, v74
	flat_load_dwordx4 v[50:53], v[74:75]
	flat_load_dwordx4 v[54:57], v[74:75] offset:1024
	v_addc_co_u32_e32 v63, vcc, 0, v75, vcc
	v_add_co_u32_e32 v70, vcc, 0x1000, v74
	flat_load_dwordx4 v[58:61], v[62:63] offset:2048
	s_nop 0
	flat_load_dwordx4 v[62:65], v[62:63] offset:3072
	v_addc_co_u32_e32 v71, vcc, 0, v75, vcc
	v_add_co_u32_e32 v78, vcc, 0x1000, v74
	flat_load_dwordx4 v[66:69], v[70:71]
	s_nop 0
	flat_load_dwordx4 v[70:73], v[70:71] offset:1024
	v_addc_co_u32_e32 v79, vcc, 0, v75, vcc
	flat_load_dwordx4 v[74:77], v[78:79] offset:2048
	s_nop 0
	flat_load_dwordx4 v[78:81], v[78:79] offset:3072
